# v29 + 64-byte alignment of the 24 hot loop heads (20 GEMM K-loops, 4 attention tile loops)
# speedup vs baseline: 1.0103x; 1.0023x over previous
.LBB0_200:
	s_ashr_i32 s15, s14, 31
	s_lshl_b64 s[16:17], s[14:15], 20
	v_readlane_b32 s18, v242, 15
	v_readlane_b32 s19, v242, 16
	s_add_u32 s16, s18, s16
	s_addc_u32 s17, s19, s17
	s_and_b64 s[18:19], s[2:3], exec
	s_cselect_b32 s15, s17, s23
	s_cselect_b32 s69, s16, s22
	s_ashr_i32 s13, s12, 31
	s_lshl_b64 s[18:19], s[12:13], 20
	v_readlane_b32 s13, v243, 60
	s_add_u32 s18, s13, s18
	v_readlane_b32 s13, v243, 61
	s_addc_u32 s19, s13, s19
	s_and_b64 s[28:29], s[2:3], exec
	s_cselect_b32 s13, s19, s1
	s_cselect_b32 s70, s18, s0
	s_add_u32 s34, s22, 0x80080
	s_addc_u32 s35, s23, 0
	s_add_u32 s71, s0, 0x100
	v_mov_b32_e32 v2, 0
	s_addc_u32 s72, s1, 0
	s_mov_b32 s73, -2
	v_mov_b32_e32 v3, v2
	v_mov_b32_e32 v4, v2
	v_mov_b32_e32 v5, v2
	v_mov_b32_e32 v10, v2
	v_mov_b32_e32 v11, v2
	v_mov_b32_e32 v12, v2
	v_mov_b32_e32 v13, v2
	v_mov_b32_e32 v18, v2
	v_mov_b32_e32 v19, v2
	v_mov_b32_e32 v20, v2
	v_mov_b32_e32 v21, v2
	v_mov_b32_e32 v26, v2
	v_mov_b32_e32 v27, v2
	v_mov_b32_e32 v28, v2
	v_mov_b32_e32 v29, v2
	v_mov_b32_e32 v34, v2
	v_mov_b32_e32 v35, v2
	v_mov_b32_e32 v36, v2
	v_mov_b32_e32 v37, v2
	v_mov_b32_e32 v42, v2
	v_mov_b32_e32 v43, v2
	v_mov_b32_e32 v44, v2
	v_mov_b32_e32 v45, v2
	v_mov_b32_e32 v50, v2
	v_mov_b32_e32 v51, v2
	v_mov_b32_e32 v52, v2
	v_mov_b32_e32 v53, v2
	v_mov_b32_e32 v58, v2
	v_mov_b32_e32 v59, v2
	v_mov_b32_e32 v60, v2
	v_mov_b32_e32 v61, v2
	v_mov_b32_e32 v6, v2
	v_mov_b32_e32 v7, v2
	v_mov_b32_e32 v8, v2
	v_mov_b32_e32 v9, v2
	v_mov_b32_e32 v14, v2
	v_mov_b32_e32 v15, v2
	v_mov_b32_e32 v16, v2
	v_mov_b32_e32 v17, v2
	v_mov_b32_e32 v22, v2
	v_mov_b32_e32 v23, v2
	v_mov_b32_e32 v24, v2
	v_mov_b32_e32 v25, v2
	v_mov_b32_e32 v30, v2
	v_mov_b32_e32 v31, v2
	v_mov_b32_e32 v32, v2
	v_mov_b32_e32 v33, v2
	v_mov_b32_e32 v38, v2
	v_mov_b32_e32 v39, v2
	v_mov_b32_e32 v40, v2
	v_mov_b32_e32 v41, v2
	v_mov_b32_e32 v46, v2
	v_mov_b32_e32 v47, v2
	v_mov_b32_e32 v48, v2
	v_mov_b32_e32 v49, v2
	v_mov_b32_e32 v54, v2
	v_mov_b32_e32 v55, v2
	v_mov_b32_e32 v56, v2
	v_mov_b32_e32 v57, v2
	v_mov_b32_e32 v62, v2
	v_mov_b32_e32 v63, v2
	v_mov_b32_e32 v64, v2
	v_mov_b32_e32 v65, v2
	v_mov_b32_e32 v66, v2
	v_mov_b32_e32 v67, v2
	v_mov_b32_e32 v68, v2
	v_mov_b32_e32 v69, v2
	v_mov_b32_e32 v74, v2
	v_mov_b32_e32 v75, v2
	v_mov_b32_e32 v76, v2
	v_mov_b32_e32 v77, v2
	v_mov_b32_e32 v82, v2
	v_mov_b32_e32 v83, v2
	v_mov_b32_e32 v84, v2
	v_mov_b32_e32 v85, v2
	v_mov_b32_e32 v90, v2
	v_mov_b32_e32 v91, v2
	v_mov_b32_e32 v92, v2
	v_mov_b32_e32 v93, v2
	v_mov_b32_e32 v98, v2
	v_mov_b32_e32 v99, v2
	v_mov_b32_e32 v100, v2
	v_mov_b32_e32 v101, v2
	v_mov_b32_e32 v106, v2
	v_mov_b32_e32 v107, v2
	v_mov_b32_e32 v108, v2
	v_mov_b32_e32 v109, v2
	v_mov_b32_e32 v114, v2
	v_mov_b32_e32 v115, v2
	v_mov_b32_e32 v116, v2
	v_mov_b32_e32 v117, v2
	v_mov_b32_e32 v122, v2
	v_mov_b32_e32 v123, v2
	v_mov_b32_e32 v124, v2
	v_mov_b32_e32 v125, v2
	v_mov_b32_e32 v70, v2
	v_mov_b32_e32 v71, v2
	v_mov_b32_e32 v72, v2
	v_mov_b32_e32 v73, v2
	v_mov_b32_e32 v78, v2
	v_mov_b32_e32 v79, v2
	v_mov_b32_e32 v80, v2
	v_mov_b32_e32 v81, v2
	v_mov_b32_e32 v86, v2
	v_mov_b32_e32 v87, v2
	v_mov_b32_e32 v88, v2
	v_mov_b32_e32 v89, v2
	v_mov_b32_e32 v94, v2
	v_mov_b32_e32 v95, v2
	v_mov_b32_e32 v96, v2
	v_mov_b32_e32 v97, v2
	v_mov_b32_e32 v102, v2
	v_mov_b32_e32 v103, v2
	v_mov_b32_e32 v104, v2
	v_mov_b32_e32 v105, v2
	v_mov_b32_e32 v110, v2
	v_mov_b32_e32 v111, v2
	v_mov_b32_e32 v112, v2
	v_mov_b32_e32 v113, v2
	v_mov_b32_e32 v118, v2
	v_mov_b32_e32 v119, v2
	v_mov_b32_e32 v120, v2
	v_mov_b32_e32 v121, v2
	v_mov_b32_e32 v126, v2
	v_mov_b32_e32 v127, v2
	v_mov_b32_e32 v128, v2
	v_mov_b32_e32 v129, v2
	.p2alignl 6, 3212836864

.LBB0_296:
	s_cmp_lg_u32 s18, 0
	s_cselect_b64 s[86:87], -1, 0
	s_cmp_eq_u32 s18, 0
	s_cselect_b32 s19, 0x58, 8
	s_add_i32 s68, s19, -2
	s_add_u32 s88, s24, 0x160080
	s_addc_u32 s89, s25, 0
	s_add_u32 s24, s0, 0x100
	v_mov_b32_e32 v2, 0
	s_mov_b32 s22, 0
	s_addc_u32 s25, s1, 0
	v_mov_b32_e32 v3, v2
	v_mov_b32_e32 v4, v2
	v_mov_b32_e32 v5, v2
	v_mov_b32_e32 v26, v2
	v_mov_b32_e32 v27, v2
	v_mov_b32_e32 v28, v2
	v_mov_b32_e32 v29, v2
	v_mov_b32_e32 v6, v2
	v_mov_b32_e32 v7, v2
	v_mov_b32_e32 v8, v2
	v_mov_b32_e32 v9, v2
	v_mov_b32_e32 v34, v2
	v_mov_b32_e32 v35, v2
	v_mov_b32_e32 v36, v2
	v_mov_b32_e32 v37, v2
	v_mov_b32_e32 v10, v2
	v_mov_b32_e32 v11, v2
	v_mov_b32_e32 v12, v2
	v_mov_b32_e32 v13, v2
	v_mov_b32_e32 v42, v2
	v_mov_b32_e32 v43, v2
	v_mov_b32_e32 v44, v2
	v_mov_b32_e32 v45, v2
	v_mov_b32_e32 v14, v2
	v_mov_b32_e32 v15, v2
	v_mov_b32_e32 v16, v2
	v_mov_b32_e32 v17, v2
	v_mov_b32_e32 v46, v2
	v_mov_b32_e32 v47, v2
	v_mov_b32_e32 v48, v2
	v_mov_b32_e32 v49, v2
	v_mov_b32_e32 v62, v2
	v_mov_b32_e32 v63, v2
	v_mov_b32_e32 v64, v2
	v_mov_b32_e32 v65, v2
	v_mov_b32_e32 v98, v2
	v_mov_b32_e32 v99, v2
	v_mov_b32_e32 v100, v2
	v_mov_b32_e32 v101, v2
	v_mov_b32_e32 v70, v2
	v_mov_b32_e32 v71, v2
	v_mov_b32_e32 v72, v2
	v_mov_b32_e32 v73, v2
	v_mov_b32_e32 v102, v2
	v_mov_b32_e32 v103, v2
	v_mov_b32_e32 v104, v2
	v_mov_b32_e32 v105, v2
	v_mov_b32_e32 v74, v2
	v_mov_b32_e32 v75, v2
	v_mov_b32_e32 v76, v2
	v_mov_b32_e32 v77, v2
	v_mov_b32_e32 v106, v2
	v_mov_b32_e32 v107, v2
	v_mov_b32_e32 v108, v2
	v_mov_b32_e32 v109, v2
	v_mov_b32_e32 v78, v2
	v_mov_b32_e32 v79, v2
	v_mov_b32_e32 v80, v2
	v_mov_b32_e32 v81, v2
	v_mov_b32_e32 v110, v2
	v_mov_b32_e32 v111, v2
	v_mov_b32_e32 v112, v2
	v_mov_b32_e32 v113, v2
	v_mov_b32_e32 v18, v2
	v_mov_b32_e32 v19, v2
	v_mov_b32_e32 v20, v2
	v_mov_b32_e32 v21, v2
	v_mov_b32_e32 v50, v2
	v_mov_b32_e32 v51, v2
	v_mov_b32_e32 v52, v2
	v_mov_b32_e32 v53, v2
	v_mov_b32_e32 v22, v2
	v_mov_b32_e32 v23, v2
	v_mov_b32_e32 v24, v2
	v_mov_b32_e32 v25, v2
	v_mov_b32_e32 v54, v2
	v_mov_b32_e32 v55, v2
	v_mov_b32_e32 v56, v2
	v_mov_b32_e32 v57, v2
	v_mov_b32_e32 v30, v2
	v_mov_b32_e32 v31, v2
	v_mov_b32_e32 v32, v2
	v_mov_b32_e32 v33, v2
	v_mov_b32_e32 v58, v2
	v_mov_b32_e32 v59, v2
	v_mov_b32_e32 v60, v2
	v_mov_b32_e32 v61, v2
	v_mov_b32_e32 v38, v2
	v_mov_b32_e32 v39, v2
	v_mov_b32_e32 v40, v2
	v_mov_b32_e32 v41, v2
	v_mov_b32_e32 v66, v2
	v_mov_b32_e32 v67, v2
	v_mov_b32_e32 v68, v2
	v_mov_b32_e32 v69, v2
	v_mov_b32_e32 v82, v2
	v_mov_b32_e32 v83, v2
	v_mov_b32_e32 v84, v2
	v_mov_b32_e32 v85, v2
	v_mov_b32_e32 v114, v2
	v_mov_b32_e32 v115, v2
	v_mov_b32_e32 v116, v2
	v_mov_b32_e32 v117, v2
	v_mov_b32_e32 v86, v2
	v_mov_b32_e32 v87, v2
	v_mov_b32_e32 v88, v2
	v_mov_b32_e32 v89, v2
	v_mov_b32_e32 v118, v2
	v_mov_b32_e32 v119, v2
	v_mov_b32_e32 v120, v2
	v_mov_b32_e32 v121, v2
	v_mov_b32_e32 v90, v2
	v_mov_b32_e32 v91, v2
	v_mov_b32_e32 v92, v2
	v_mov_b32_e32 v93, v2
	v_mov_b32_e32 v122, v2
	v_mov_b32_e32 v123, v2
	v_mov_b32_e32 v124, v2
	v_mov_b32_e32 v125, v2
	v_mov_b32_e32 v94, v2
	v_mov_b32_e32 v95, v2
	v_mov_b32_e32 v96, v2
	v_mov_b32_e32 v97, v2
	v_mov_b32_e32 v126, v2
	v_mov_b32_e32 v127, v2
	v_mov_b32_e32 v128, v2
	v_mov_b32_e32 v129, v2
	.p2alignl 6, 3212836864

.LBB0_437:
	s_ashr_i32 s17, s16, 31
	s_lshl_b64 s[18:19], s[16:17], 20
	v_readlane_b32 s22, v242, 15
	v_readlane_b32 s23, v242, 16
	s_add_u32 s18, s22, s18
	s_addc_u32 s19, s23, s19
	s_and_b64 s[22:23], s[2:3], exec
	s_cselect_b32 s5, s19, s25
	s_cselect_b32 s17, s18, s24
	s_ashr_i32 s15, s14, 31
	s_lshl_b64 s[22:23], s[14:15], 20
	s_add_u32 s86, s20, s22
	s_addc_u32 s87, s26, s23
	s_and_b64 s[22:23], s[2:3], exec
	s_cselect_b32 s15, s87, s1
	s_cselect_b32 s68, s86, s0
	s_add_u32 s90, s24, 0x80080
	s_addc_u32 s91, s25, 0
	s_add_u32 s24, s0, 0x100
	v_mov_b32_e32 v2, 0
	s_addc_u32 s25, s1, 0
	s_mov_b32 s69, -2
	v_mov_b32_e32 v3, v2
	v_mov_b32_e32 v4, v2
	v_mov_b32_e32 v5, v2
	v_mov_b32_e32 v6, v2
	v_mov_b32_e32 v7, v2
	v_mov_b32_e32 v8, v2
	v_mov_b32_e32 v9, v2
	v_mov_b32_e32 v18, v2
	v_mov_b32_e32 v19, v2
	v_mov_b32_e32 v20, v2
	v_mov_b32_e32 v21, v2
	v_mov_b32_e32 v22, v2
	v_mov_b32_e32 v23, v2
	v_mov_b32_e32 v24, v2
	v_mov_b32_e32 v25, v2
	v_mov_b32_e32 v34, v2
	v_mov_b32_e32 v35, v2
	v_mov_b32_e32 v36, v2
	v_mov_b32_e32 v37, v2
	v_mov_b32_e32 v38, v2
	v_mov_b32_e32 v39, v2
	v_mov_b32_e32 v40, v2
	v_mov_b32_e32 v41, v2
	v_mov_b32_e32 v50, v2
	v_mov_b32_e32 v51, v2
	v_mov_b32_e32 v52, v2
	v_mov_b32_e32 v53, v2
	v_mov_b32_e32 v54, v2
	v_mov_b32_e32 v55, v2
	v_mov_b32_e32 v56, v2
	v_mov_b32_e32 v57, v2
	v_mov_b32_e32 v10, v2
	v_mov_b32_e32 v11, v2
	v_mov_b32_e32 v12, v2
	v_mov_b32_e32 v13, v2
	v_mov_b32_e32 v14, v2
	v_mov_b32_e32 v15, v2
	v_mov_b32_e32 v16, v2
	v_mov_b32_e32 v17, v2
	v_mov_b32_e32 v26, v2
	v_mov_b32_e32 v27, v2
	v_mov_b32_e32 v28, v2
	v_mov_b32_e32 v29, v2
	v_mov_b32_e32 v30, v2
	v_mov_b32_e32 v31, v2
	v_mov_b32_e32 v32, v2
	v_mov_b32_e32 v33, v2
	v_mov_b32_e32 v42, v2
	v_mov_b32_e32 v43, v2
	v_mov_b32_e32 v44, v2
	v_mov_b32_e32 v45, v2
	v_mov_b32_e32 v46, v2
	v_mov_b32_e32 v47, v2
	v_mov_b32_e32 v48, v2
	v_mov_b32_e32 v49, v2
	v_mov_b32_e32 v58, v2
	v_mov_b32_e32 v59, v2
	v_mov_b32_e32 v60, v2
	v_mov_b32_e32 v61, v2
	v_mov_b32_e32 v62, v2
	v_mov_b32_e32 v63, v2
	v_mov_b32_e32 v64, v2
	v_mov_b32_e32 v65, v2
	v_mov_b32_e32 v66, v2
	v_mov_b32_e32 v67, v2
	v_mov_b32_e32 v68, v2
	v_mov_b32_e32 v69, v2
	v_mov_b32_e32 v70, v2
	v_mov_b32_e32 v71, v2
	v_mov_b32_e32 v72, v2
	v_mov_b32_e32 v73, v2
	v_mov_b32_e32 v82, v2
	v_mov_b32_e32 v83, v2
	v_mov_b32_e32 v84, v2
	v_mov_b32_e32 v85, v2
	v_mov_b32_e32 v86, v2
	v_mov_b32_e32 v87, v2
	v_mov_b32_e32 v88, v2
	v_mov_b32_e32 v89, v2
	v_mov_b32_e32 v98, v2
	v_mov_b32_e32 v99, v2
	v_mov_b32_e32 v100, v2
	v_mov_b32_e32 v101, v2
	v_mov_b32_e32 v102, v2
	v_mov_b32_e32 v103, v2
	v_mov_b32_e32 v104, v2
	v_mov_b32_e32 v105, v2
	v_mov_b32_e32 v114, v2
	v_mov_b32_e32 v115, v2
	v_mov_b32_e32 v116, v2
	v_mov_b32_e32 v117, v2
	v_mov_b32_e32 v118, v2
	v_mov_b32_e32 v119, v2
	v_mov_b32_e32 v120, v2
	v_mov_b32_e32 v121, v2
	v_mov_b32_e32 v74, v2
	v_mov_b32_e32 v75, v2
	v_mov_b32_e32 v76, v2
	v_mov_b32_e32 v77, v2
	v_mov_b32_e32 v78, v2
	v_mov_b32_e32 v79, v2
	v_mov_b32_e32 v80, v2
	v_mov_b32_e32 v81, v2
	v_mov_b32_e32 v90, v2
	v_mov_b32_e32 v91, v2
	v_mov_b32_e32 v92, v2
	v_mov_b32_e32 v93, v2
	v_mov_b32_e32 v94, v2
	v_mov_b32_e32 v95, v2
	v_mov_b32_e32 v96, v2
	v_mov_b32_e32 v97, v2
	v_mov_b32_e32 v106, v2
	v_mov_b32_e32 v107, v2
	v_mov_b32_e32 v108, v2
	v_mov_b32_e32 v109, v2
	v_mov_b32_e32 v110, v2
	v_mov_b32_e32 v111, v2
	v_mov_b32_e32 v112, v2
	v_mov_b32_e32 v113, v2
	v_mov_b32_e32 v122, v2
	v_mov_b32_e32 v123, v2
	v_mov_b32_e32 v124, v2
	v_mov_b32_e32 v125, v2
	v_mov_b32_e32 v126, v2
	v_mov_b32_e32 v127, v2
	v_mov_b32_e32 v128, v2
	v_mov_b32_e32 v129, v2
	.p2alignl 6, 3212836864

.LBB0_646:
	s_ashr_i32 s13, s12, 31
	s_lshl_b64 s[18:19], s[12:13], 18
	s_add_u32 s18, s26, s18
	s_addc_u32 s19, s27, s19
	s_and_b64 s[4:5], s[4:5], exec
	s_cselect_b32 s13, s19, s1
	s_cselect_b32 s75, s18, s0
	s_add_u32 s4, s22, 0x180080
	s_addc_u32 s5, s23, 0
	s_add_u32 s76, s0, 0x100
	v_mov_b32_e32 v2, 0
	s_addc_u32 s77, s1, 0
	s_mov_b32 s78, -2
	v_mov_b32_e32 v3, v2
	v_mov_b32_e32 v4, v2
	v_mov_b32_e32 v5, v2
	v_mov_b32_e32 v6, v2
	v_mov_b32_e32 v7, v2
	v_mov_b32_e32 v8, v2
	v_mov_b32_e32 v9, v2
	v_mov_b32_e32 v10, v2
	v_mov_b32_e32 v11, v2
	v_mov_b32_e32 v12, v2
	v_mov_b32_e32 v13, v2
	v_mov_b32_e32 v14, v2
	v_mov_b32_e32 v15, v2
	v_mov_b32_e32 v16, v2
	v_mov_b32_e32 v17, v2
	v_mov_b32_e32 v26, v2
	v_mov_b32_e32 v27, v2
	v_mov_b32_e32 v28, v2
	v_mov_b32_e32 v29, v2
	v_mov_b32_e32 v30, v2
	v_mov_b32_e32 v31, v2
	v_mov_b32_e32 v32, v2
	v_mov_b32_e32 v33, v2
	v_mov_b32_e32 v42, v2
	v_mov_b32_e32 v43, v2
	v_mov_b32_e32 v44, v2
	v_mov_b32_e32 v45, v2
	v_mov_b32_e32 v46, v2
	v_mov_b32_e32 v47, v2
	v_mov_b32_e32 v48, v2
	v_mov_b32_e32 v49, v2
	v_mov_b32_e32 v18, v2
	v_mov_b32_e32 v19, v2
	v_mov_b32_e32 v20, v2
	v_mov_b32_e32 v21, v2
	v_mov_b32_e32 v22, v2
	v_mov_b32_e32 v23, v2
	v_mov_b32_e32 v24, v2
	v_mov_b32_e32 v25, v2
	v_mov_b32_e32 v34, v2
	v_mov_b32_e32 v35, v2
	v_mov_b32_e32 v36, v2
	v_mov_b32_e32 v37, v2
	v_mov_b32_e32 v38, v2
	v_mov_b32_e32 v39, v2
	v_mov_b32_e32 v40, v2
	v_mov_b32_e32 v41, v2
	v_mov_b32_e32 v50, v2
	v_mov_b32_e32 v51, v2
	v_mov_b32_e32 v52, v2
	v_mov_b32_e32 v53, v2
	v_mov_b32_e32 v54, v2
	v_mov_b32_e32 v55, v2
	v_mov_b32_e32 v56, v2
	v_mov_b32_e32 v57, v2
	v_mov_b32_e32 v58, v2
	v_mov_b32_e32 v59, v2
	v_mov_b32_e32 v60, v2
	v_mov_b32_e32 v61, v2
	v_mov_b32_e32 v62, v2
	v_mov_b32_e32 v63, v2
	v_mov_b32_e32 v64, v2
	v_mov_b32_e32 v65, v2
	v_mov_b32_e32 v66, v2
	v_mov_b32_e32 v67, v2
	v_mov_b32_e32 v68, v2
	v_mov_b32_e32 v69, v2
	v_mov_b32_e32 v70, v2
	v_mov_b32_e32 v71, v2
	v_mov_b32_e32 v72, v2
	v_mov_b32_e32 v73, v2
	v_mov_b32_e32 v74, v2
	v_mov_b32_e32 v75, v2
	v_mov_b32_e32 v76, v2
	v_mov_b32_e32 v77, v2
	v_mov_b32_e32 v78, v2
	v_mov_b32_e32 v79, v2
	v_mov_b32_e32 v80, v2
	v_mov_b32_e32 v81, v2
	v_mov_b32_e32 v90, v2
	v_mov_b32_e32 v91, v2
	v_mov_b32_e32 v92, v2
	v_mov_b32_e32 v93, v2
	v_mov_b32_e32 v94, v2
	v_mov_b32_e32 v95, v2
	v_mov_b32_e32 v96, v2
	v_mov_b32_e32 v97, v2
	v_mov_b32_e32 v106, v2
	v_mov_b32_e32 v107, v2
	v_mov_b32_e32 v108, v2
	v_mov_b32_e32 v109, v2
	v_mov_b32_e32 v110, v2
	v_mov_b32_e32 v111, v2
	v_mov_b32_e32 v112, v2
	v_mov_b32_e32 v113, v2
	v_mov_b32_e32 v82, v2
	v_mov_b32_e32 v83, v2
	v_mov_b32_e32 v84, v2
	v_mov_b32_e32 v85, v2
	v_mov_b32_e32 v86, v2
	v_mov_b32_e32 v87, v2
	v_mov_b32_e32 v88, v2
	v_mov_b32_e32 v89, v2
	v_mov_b32_e32 v98, v2
	v_mov_b32_e32 v99, v2
	v_mov_b32_e32 v100, v2
	v_mov_b32_e32 v101, v2
	v_mov_b32_e32 v102, v2
	v_mov_b32_e32 v103, v2
	v_mov_b32_e32 v104, v2
	v_mov_b32_e32 v105, v2
	v_mov_b32_e32 v114, v2
	v_mov_b32_e32 v115, v2
	v_mov_b32_e32 v116, v2
	v_mov_b32_e32 v117, v2
	v_mov_b32_e32 v118, v2
	v_mov_b32_e32 v119, v2
	v_mov_b32_e32 v120, v2
	v_mov_b32_e32 v121, v2
	v_mov_b32_e32 v122, v2
	v_mov_b32_e32 v123, v2
	v_mov_b32_e32 v124, v2
	v_mov_b32_e32 v125, v2
	v_mov_b32_e32 v126, v2
	v_mov_b32_e32 v127, v2
	v_mov_b32_e32 v128, v2
	v_mov_b32_e32 v129, v2
	.p2alignl 6, 3212836864

.LBB0_664:
	s_ashr_i32 s87, s86, 31
	s_lshl_b64 s[0:1], s[86:87], 17
	s_add_u32 s92, s27, s0
	s_addc_u32 s93, s30, s1
	s_and_b64 s[0:1], s[4:5], exec
	v_mov_b32_e32 v2, 0
	s_cselect_b32 s73, s93, s19
	s_cselect_b32 s74, s92, s18
	s_mov_b32 s24, 0
	s_mov_b64 s[4:5], -1
	s_mov_b64 s[0:1], 0
	v_mov_b32_e32 v3, v2
	v_mov_b32_e32 v4, v2
	v_mov_b32_e32 v5, v2
	v_mov_b32_e32 v6, v2
	v_mov_b32_e32 v7, v2
	v_mov_b32_e32 v8, v2
	v_mov_b32_e32 v9, v2
	v_mov_b32_e32 v10, v2
	v_mov_b32_e32 v11, v2
	v_mov_b32_e32 v12, v2
	v_mov_b32_e32 v13, v2
	v_mov_b32_e32 v14, v2
	v_mov_b32_e32 v15, v2
	v_mov_b32_e32 v16, v2
	v_mov_b32_e32 v17, v2
	v_mov_b32_e32 v26, v2
	v_mov_b32_e32 v27, v2
	v_mov_b32_e32 v28, v2
	v_mov_b32_e32 v29, v2
	v_mov_b32_e32 v30, v2
	v_mov_b32_e32 v31, v2
	v_mov_b32_e32 v32, v2
	v_mov_b32_e32 v33, v2
	v_mov_b32_e32 v42, v2
	v_mov_b32_e32 v43, v2
	v_mov_b32_e32 v44, v2
	v_mov_b32_e32 v45, v2
	v_mov_b32_e32 v46, v2
	v_mov_b32_e32 v47, v2
	v_mov_b32_e32 v48, v2
	v_mov_b32_e32 v49, v2
	v_mov_b32_e32 v18, v2
	v_mov_b32_e32 v19, v2
	v_mov_b32_e32 v20, v2
	v_mov_b32_e32 v21, v2
	v_mov_b32_e32 v22, v2
	v_mov_b32_e32 v23, v2
	v_mov_b32_e32 v24, v2
	v_mov_b32_e32 v25, v2
	v_mov_b32_e32 v34, v2
	v_mov_b32_e32 v35, v2
	v_mov_b32_e32 v36, v2
	v_mov_b32_e32 v37, v2
	v_mov_b32_e32 v38, v2
	v_mov_b32_e32 v39, v2
	v_mov_b32_e32 v40, v2
	v_mov_b32_e32 v41, v2
	v_mov_b32_e32 v50, v2
	v_mov_b32_e32 v51, v2
	v_mov_b32_e32 v52, v2
	v_mov_b32_e32 v53, v2
	v_mov_b32_e32 v54, v2
	v_mov_b32_e32 v55, v2
	v_mov_b32_e32 v56, v2
	v_mov_b32_e32 v57, v2
	v_mov_b32_e32 v58, v2
	v_mov_b32_e32 v59, v2
	v_mov_b32_e32 v60, v2
	v_mov_b32_e32 v61, v2
	v_mov_b32_e32 v62, v2
	v_mov_b32_e32 v63, v2
	v_mov_b32_e32 v64, v2
	v_mov_b32_e32 v65, v2
	v_mov_b32_e32 v66, v2
	v_mov_b32_e32 v67, v2
	v_mov_b32_e32 v68, v2
	v_mov_b32_e32 v69, v2
	v_mov_b32_e32 v70, v2
	v_mov_b32_e32 v71, v2
	v_mov_b32_e32 v72, v2
	v_mov_b32_e32 v73, v2
	v_mov_b32_e32 v74, v2
	v_mov_b32_e32 v75, v2
	v_mov_b32_e32 v76, v2
	v_mov_b32_e32 v77, v2
	v_mov_b32_e32 v78, v2
	v_mov_b32_e32 v79, v2
	v_mov_b32_e32 v80, v2
	v_mov_b32_e32 v81, v2
	v_mov_b32_e32 v90, v2
	v_mov_b32_e32 v91, v2
	v_mov_b32_e32 v92, v2
	v_mov_b32_e32 v93, v2
	v_mov_b32_e32 v94, v2
	v_mov_b32_e32 v95, v2
	v_mov_b32_e32 v96, v2
	v_mov_b32_e32 v97, v2
	v_mov_b32_e32 v106, v2
	v_mov_b32_e32 v107, v2
	v_mov_b32_e32 v108, v2
	v_mov_b32_e32 v109, v2
	v_mov_b32_e32 v110, v2
	v_mov_b32_e32 v111, v2
	v_mov_b32_e32 v112, v2
	v_mov_b32_e32 v113, v2
	v_mov_b32_e32 v82, v2
	v_mov_b32_e32 v83, v2
	v_mov_b32_e32 v84, v2
	v_mov_b32_e32 v85, v2
	v_mov_b32_e32 v86, v2
	v_mov_b32_e32 v87, v2
	v_mov_b32_e32 v88, v2
	v_mov_b32_e32 v89, v2
	v_mov_b32_e32 v98, v2
	v_mov_b32_e32 v99, v2
	v_mov_b32_e32 v100, v2
	v_mov_b32_e32 v101, v2
	v_mov_b32_e32 v102, v2
	v_mov_b32_e32 v103, v2
	v_mov_b32_e32 v104, v2
	v_mov_b32_e32 v105, v2
	v_mov_b32_e32 v114, v2
	v_mov_b32_e32 v115, v2
	v_mov_b32_e32 v116, v2
	v_mov_b32_e32 v117, v2
	v_mov_b32_e32 v118, v2
	v_mov_b32_e32 v119, v2
	v_mov_b32_e32 v120, v2
	v_mov_b32_e32 v121, v2
	v_mov_b32_e32 v122, v2
	v_mov_b32_e32 v123, v2
	v_mov_b32_e32 v124, v2
	v_mov_b32_e32 v125, v2
	v_mov_b32_e32 v126, v2
	v_mov_b32_e32 v127, v2
	v_mov_b32_e32 v128, v2
	v_mov_b32_e32 v129, v2
	.p2alignl 6, 3212836864

.LBB0_891:
	s_lshr_b32 s16, s19, 6
	s_and_b64 s[12:13], s[12:13], exec
	s_cselect_b32 s12, s19, s16
	s_and_b32 s17, s12, 7
	s_mul_i32 s12, s9, 0xc00
	s_mul_hi_u32 s13, s8, 0xc00
	s_add_i32 s13, s13, s12
	s_mul_i32 s12, s8, 0xc00
	v_readlane_b32 s20, v242, 21
	v_readlane_b32 s21, v242, 22
	s_add_u32 s12, s20, s12
	s_addc_u32 s13, s21, s13
	s_mul_i32 s16, s17, 0x180
	s_add_u32 s28, s12, s16
	s_addc_u32 s29, s13, 0
	s_mul_i32 s12, s1, 0xc00
	s_mul_hi_u32 s13, s0, 0xc00
	s_add_i32 s13, s13, s12
	s_mul_i32 s12, s0, 0xc00
	s_add_u32 s12, s27, s12
	s_addc_u32 s13, s30, s13
	s_add_u32 s12, s12, s16
	s_mul_i32 s20, s15, 0x3000000
	s_mul_hi_u32 s21, s14, 0x3000000
	s_addc_u32 s13, s13, 0
	s_add_i32 s21, s21, s20
	s_mul_i32 s20, s14, 0x3000000
	s_add_u32 s20, s27, s20
	s_addc_u32 s21, s30, s21
	s_add_u32 s22, s20, s16
	s_addc_u32 s23, s21, 0
	s_lshl_b64 s[0:1], s[0:1], 12
	s_add_u32 s0, s31, s0
	s_addc_u32 s1, s34, s1
	s_lshl_b32 s16, s17, 9
	s_add_u32 s0, s0, s16
	s_addc_u32 s1, s1, 0
	s_add_u32 s24, s0, 0x100
	s_addc_u32 s25, s1, 0
	s_lshl_b64 s[14:15], s[14:15], 26
	s_add_u32 s14, s31, s14
	s_addc_u32 s15, s34, s15
	s_add_u32 s14, s14, s16
	s_addc_u32 s15, s15, 0
	s_add_u32 s33, s14, 0x100
	v_readfirstlane_b32 s68, v0
	s_addc_u32 s35, s15, 0
	s_lshr_b32 s20, s68, 6
	s_lshl_b32 s16, s20, 5
	v_or_b32_e32 v4, s16, v1
	v_mov_b64_e32 v[2:3], s[28:29]
	s_movk_i32 s14, 0xc00
	v_mad_u64_u32 v[2:3], s[14:15], v4, s14, v[2:3]
	s_andn2_b32 s68, s68, 63
	v_lshl_add_u64 v[2:3], v[2:3], 0, v[148:149]
	global_load_dwordx4 v[142:145], v[2:3], off
	global_load_dwordx4 v[138:141], v[2:3], off offset:32
	global_load_dwordx4 v[134:137], v[2:3], off offset:64
	global_load_dwordx4 v[130:133], v[2:3], off offset:96
	global_load_dwordx4 v[126:129], v[2:3], off offset:128
	global_load_dwordx4 v[122:125], v[2:3], off offset:160
	global_load_dwordx4 v[118:121], v[2:3], off offset:192
	global_load_dwordx4 v[114:117], v[2:3], off offset:224
	global_load_dwordx4 v[110:113], v[2:3], off offset:256
	global_load_dwordx4 v[106:109], v[2:3], off offset:288
	global_load_dwordx4 v[102:105], v[2:3], off offset:320
	global_load_dwordx4 v[98:101], v[2:3], off offset:352
	v_or_b32_e32 v2, s68, v166
	v_mul_hi_i32 v3, v2, s11
	v_lshrrev_b32_e32 v4, 31, v3
	v_ashrrev_i32_e32 v3, 2, v3
	v_add_u32_e32 v3, v3, v4
	v_mul_lo_u32 v4, v3, 24
	v_sub_u32_e32 v4, v2, v4
	v_mul_lo_u32 v5, v3, s18
	v_lshrrev_b32_e32 v3, 1, v3
	v_bitop3_b32 v3, v3, v4, 7 bitop3:0x6c
	v_lshl_add_u32 v160, v3, 3, v5
	v_add_u32_e32 v3, 0x200, v2
	v_mul_hi_i32 v4, v3, s11
	v_lshrrev_b32_e32 v5, 31, v4
	v_ashrrev_i32_e32 v4, 2, v4
	v_add_u32_e32 v4, v4, v5
	v_mul_lo_u32 v5, v4, 24
	v_sub_u32_e32 v3, v3, v5
	v_mul_lo_u32 v5, v4, s18
	v_lshrrev_b32_e32 v4, 1, v4
	v_bitop3_b32 v3, v4, v3, 7 bitop3:0x6c
	v_lshl_add_u32 v162, v3, 3, v5
	v_add_u32_e32 v3, 0x400, v2
	v_mul_hi_i32 v4, v3, s11
	v_lshrrev_b32_e32 v5, 31, v4
	v_ashrrev_i32_e32 v4, 2, v4
	v_add_u32_e32 v4, v4, v5
	s_ashr_i32 s14, s68, 4
	v_mul_lo_u32 v5, v4, 24
	s_and_b32 s15, s14, 0x1ffff0
	s_lshr_b32 s14, s14, 1
	v_sub_u32_e32 v3, v3, v5
	v_mul_lo_u32 v5, v4, s18
	v_lshrrev_b32_e32 v4, 1, v4
	s_and_b32 s14, s14, 4
	v_bitop3_b32 v3, v4, v3, 7 bitop3:0x6c
	s_or_b32 s14, s15, s14
	v_lshl_add_u32 v170, v3, 3, v5
	v_or_b32_e32 v3, s14, v169
	s_add_i32 s14, s68, 0x200
	s_ashr_i32 s14, s14, 4
	s_and_b32 s15, s14, 0x1ffff0
	s_lshr_b32 s14, s14, 1
	s_and_b32 s14, s14, 4
	v_and_or_b32 v2, v2, s10, v165
	s_or_b32 s14, s15, s14
	v_lshl_or_b32 v172, v3, 11, v2
	v_or_b32_e32 v3, s14, v169
	s_lshl_b32 s14, s20, 10
	s_add_i32 s69, s14, 0
	v_ashrrev_i32_e32 v161, 31, v160
	v_lshl_or_b32 v174, v3, 11, v2
	s_add_i32 m0, s69, 0x8000
	v_lshl_add_u64 v[2:3], v[160:161], 1, s[12:13]
	v_ashrrev_i32_e32 v163, 31, v162
	global_load_lds_dwordx4 v[2:3], off
	v_lshl_add_u64 v[2:3], v[162:163], 1, s[12:13]
	s_add_i32 m0, s69, 0xa000
	v_ashrrev_i32_e32 v171, 31, v170
	global_load_lds_dwordx4 v[2:3], off
	v_lshl_add_u64 v[2:3], v[170:171], 1, s[12:13]
	s_add_i32 m0, s69, 0xc000
	v_ashrrev_i32_e32 v173, 31, v172
	global_load_lds_dwordx4 v[2:3], off
	v_lshl_add_u64 v[2:3], v[172:173], 1, s[0:1]
	v_lshl_add_u64 v[2:3], v[2:3], 0, s[6:7]
	s_mov_b32 m0, s69
	v_ashrrev_i32_e32 v175, 31, v174
	global_load_lds_dwordx4 v[2:3], off
	v_lshl_add_u64 v[2:3], v[174:175], 1, s[0:1]
	v_lshl_add_u64 v[2:3], v[2:3], 0, s[6:7]
	s_add_i32 m0, s69, 0x2000
	v_mov_b32_e32 v151, 0
	global_load_lds_dwordx4 v[2:3], off
	s_waitcnt vmcnt(0)
	s_add_i32 s0, s4, 1
	s_mov_b32 s4, 0
	s_mov_b64 s[14:15], 64
	v_mov_b32_e32 v2, 0
	v_mov_b32_e32 v3, v151
	v_mov_b32_e32 v4, v151
	v_mov_b32_e32 v5, v151
	v_mov_b32_e32 v6, v151
	v_mov_b32_e32 v7, v151
	v_mov_b32_e32 v8, v151
	v_mov_b32_e32 v9, v151
	v_mov_b32_e32 v10, v151
	v_mov_b32_e32 v11, v151
	v_mov_b32_e32 v12, v151
	v_mov_b32_e32 v13, v151
	v_mov_b32_e32 v14, v151
	v_mov_b32_e32 v15, v151
	v_mov_b32_e32 v16, v151
	v_mov_b32_e32 v17, v151
	v_mov_b32_e32 v18, 0
	v_mov_b32_e32 v19, v151
	v_mov_b32_e32 v20, v151
	v_mov_b32_e32 v21, v151
	v_mov_b32_e32 v22, v151
	v_mov_b32_e32 v23, v151
	v_mov_b32_e32 v24, v151
	v_mov_b32_e32 v25, v151
	v_mov_b32_e32 v26, v151
	v_mov_b32_e32 v27, v151
	v_mov_b32_e32 v28, v151
	v_mov_b32_e32 v29, v151
	v_mov_b32_e32 v30, v151
	v_mov_b32_e32 v31, v151
	v_mov_b32_e32 v32, v151
	v_mov_b32_e32 v33, v151
	v_mov_b32_e32 v34, 0
	v_mov_b32_e32 v35, v151
	v_mov_b32_e32 v36, v151
	v_mov_b32_e32 v37, v151
	v_mov_b32_e32 v38, v151
	v_mov_b32_e32 v39, v151
	v_mov_b32_e32 v40, v151
	v_mov_b32_e32 v41, v151
	v_mov_b32_e32 v42, v151
	v_mov_b32_e32 v43, v151
	v_mov_b32_e32 v44, v151
	v_mov_b32_e32 v45, v151
	v_mov_b32_e32 v46, v151
	v_mov_b32_e32 v47, v151
	v_mov_b32_e32 v48, v151
	v_mov_b32_e32 v49, v151
	v_mov_b32_e32 v50, 0
	v_mov_b32_e32 v51, v151
	v_mov_b32_e32 v52, v151
	v_mov_b32_e32 v53, v151
	v_mov_b32_e32 v54, v151
	v_mov_b32_e32 v55, v151
	v_mov_b32_e32 v56, v151
	v_mov_b32_e32 v57, v151
	v_mov_b32_e32 v58, v151
	v_mov_b32_e32 v59, v151
	v_mov_b32_e32 v60, v151
	v_mov_b32_e32 v61, v151
	v_mov_b32_e32 v62, v151
	v_mov_b32_e32 v63, v151
	v_mov_b32_e32 v64, v151
	v_mov_b32_e32 v65, v151
	s_waitcnt vmcnt(0) lgkmcnt(0)
	s_barrier
	.p2alignl 6, 3212836864

.LBB0_904:
	v_add_f32_e32 v1, v1, v116
	s_add_u32 s0, s18, 0x240000
	v_add_f32_e32 v1, 0, v1
	v_add_f32_e32 v66, v66, v67
	s_addc_u32 s1, s19, 0
	v_add_f32_e32 v1, v1, v66
	v_lshl_add_u64 v[66:67], v[72:73], 1, s[0:1]
	s_mov_b32 m0, s35
	v_exp_f32_e32 v175, v106
	global_load_lds_dwordx4 v[66:67], off
	v_lshl_add_u64 v[66:67], v[70:71], 1, s[0:1]
	s_mov_b32 m0, s86
	v_exp_f32_e32 v176, v107
	global_load_lds_dwordx4 v[66:67], off
	v_exp_f32_e32 v177, v108
	v_exp_f32_e32 v178, v109
	v_exp_f32_e32 v179, v110
	v_exp_f32_e32 v180, v111
	v_exp_f32_e32 v181, v112
	v_exp_f32_e32 v192, v113
	ds_read_b128 v[66:69], v188 offset:40960
	ds_read_b128 v[70:73], v188 offset:45056
	ds_read_b128 v[106:109], v189 offset:40960
	ds_read_b128 v[110:113], v189 offset:45056
	ds_read_b128 v[116:119], v190 offset:40960
	ds_read_b128 v[120:123], v190 offset:45056
	ds_read_b128 v[124:127], v191 offset:40960
	ds_read_b128 v[170:173], v191 offset:45056
	v_exp_f32_e32 v151, v98
	v_exp_f32_e32 v153, v99
	v_exp_f32_e32 v155, v100
	v_exp_f32_e32 v157, v101
	v_exp_f32_e32 v159, v102
	v_exp_f32_e32 v161, v103
	v_exp_f32_e32 v163, v104
	v_exp_f32_e32 v174, v105
	s_waitcnt lgkmcnt(0)
	v_mfma_f32_32x32x16_bf16 v[90:105], v[66:69], v[128:131], 0
	v_exp_f32_e32 v193, v74
	v_exp_f32_e32 v194, v75
	v_exp_f32_e32 v195, v76
	v_exp_f32_e32 v196, v77
	v_exp_f32_e32 v197, v78
	v_exp_f32_e32 v198, v79
	v_exp_f32_e32 v199, v80
	v_exp_f32_e32 v200, v81
	v_mfma_f32_32x32x16_bf16 v[66:81], v[70:73], v[128:131], 0
	v_mfma_f32_32x32x16_bf16 v[90:105], v[106:109], v[132:135], v[90:105]
	v_exp_f32_e32 v82, v82
	v_exp_f32_e32 v83, v83
	v_exp_f32_e32 v84, v84
	v_exp_f32_e32 v85, v85
	v_exp_f32_e32 v86, v86
	v_exp_f32_e32 v87, v87
	v_exp_f32_e32 v88, v88
	v_mfma_f32_32x32x16_bf16 v[66:81], v[110:113], v[132:135], v[66:81]
	v_exp_f32_e32 v89, v89
	v_add_f32_e32 v106, v151, v153
	v_add_f32_e32 v107, v193, v194
	v_mfma_f32_32x32x16_bf16 v[90:105], v[116:119], v[136:139], v[90:105]
	v_add_f32_e32 v106, v106, v155
	v_add_f32_e32 v107, v107, v195
	v_cvt_pk_bf16_f32 v108, v159, v161
	v_add_f32_e32 v106, v106, v157
	v_add_f32_e32 v107, v107, v196
	v_cvt_pk_bf16_f32 v109, v163, v174
	v_add_f32_e32 v106, v106, v159
	v_add_f32_e32 v107, v107, v197
	v_mfma_f32_32x32x16_bf16 v[66:81], v[120:123], v[136:139], v[66:81]
	v_add_f32_e32 v106, v106, v161
	v_add_f32_e32 v107, v107, v198
	s_nop 0
	v_add_f32_e32 v106, v106, v163
	v_add_f32_e32 v107, v107, v199
	s_nop 0
	v_add_f32_e32 v106, v106, v174
	v_add_f32_e32 v107, v107, v200
	s_nop 0
	v_add_f32_e32 v106, v106, v175
	v_add_f32_e32 v107, v107, v82
	s_nop 0
	v_add_f32_e32 v106, v106, v176
	v_add_f32_e32 v107, v107, v83
	s_nop 0
	v_add_f32_e32 v106, v106, v177
	v_add_f32_e32 v107, v107, v84
	s_nop 0
	v_add_f32_e32 v106, v106, v178
	v_add_f32_e32 v107, v107, v85
	s_nop 0
	v_add_f32_e32 v106, v106, v179
	v_add_f32_e32 v107, v107, v86
	s_nop 0
	v_add_f32_e32 v106, v106, v180
	v_add_f32_e32 v107, v107, v87
	s_nop 0
	v_add_f32_e32 v106, v106, v181
	v_add_f32_e32 v107, v107, v88
	s_nop 0
	v_add_f32_e32 v106, v106, v192
	v_add_f32_e32 v107, v107, v89
	s_nop 0
	v_add_f32_e32 v106, v106, v107
	v_mov_b32_e32 v107, v106
	s_nop 1
	v_permlane32_swap_b32_e32 v106, v107
	v_add_f32_e32 v106, v106, v107
	v_add_f32_e32 v149, v1, v106
	v_cvt_pk_bf16_f32 v106, v151, v153
	v_cvt_pk_bf16_f32 v107, v155, v157
	s_nop 0
	v_permlane32_swap_b32_e32 v106, v108
	v_permlane32_swap_b32_e32 v107, v109
	v_mfma_f32_32x32x16_bf16 v[90:105], v[124:127], v[140:143], v[90:105]
	v_cvt_pk_bf16_f32 v110, v175, v176
	v_cvt_pk_bf16_f32 v111, v177, v178
	v_cvt_pk_bf16_f32 v112, v179, v180
	v_cvt_pk_bf16_f32 v113, v181, v192
	v_cvt_pk_bf16_f32 v116, v193, v194
	v_cvt_pk_bf16_f32 v117, v195, v196
	v_cvt_pk_bf16_f32 v118, v197, v198
	v_mfma_f32_32x32x16_bf16 v[66:81], v[170:173], v[140:143], v[66:81]
	v_cvt_pk_bf16_f32 v119, v199, v200
	v_cvt_pk_bf16_f32 v120, v82, v83
	v_cvt_pk_bf16_f32 v121, v84, v85
	v_cvt_pk_bf16_f32 v122, v86, v87
	v_cvt_pk_bf16_f32 v123, v88, v89
	v_permlane32_swap_b32_e32 v110, v112
	v_permlane32_swap_b32_e32 v111, v113
	v_permlane32_swap_b32_e32 v116, v118
	v_permlane32_swap_b32_e32 v117, v119
	v_permlane32_swap_b32_e32 v120, v122
	v_permlane32_swap_b32_e32 v121, v123
	ds_read_b64_tr_b16 v[82:83], v184 offset:0
	ds_read_b64_tr_b16 v[84:85], v184 offset:0x800
	ds_read_b64_tr_b16 v[86:87], v184 offset:0x1000
	ds_read_b64_tr_b16 v[88:89], v184 offset:0x1800
	ds_read_b64_tr_b16 v[124:125], v184 offset:0x2000
	ds_read_b64_tr_b16 v[126:127], v184 offset:0x2800
	ds_read_b64_tr_b16 v[170:171], v184 offset:0x3000
	ds_read_b64_tr_b16 v[172:173], v184 offset:0x3800
	ds_read_b64_tr_b16 v[174:175], v184 offset:0x200
	ds_read_b64_tr_b16 v[176:177], v184 offset:0xa00
	ds_read_b64_tr_b16 v[178:179], v184 offset:0x1200
	ds_read_b64_tr_b16 v[180:181], v184 offset:0x1a00
	ds_read_b64_tr_b16 v[192:193], v184 offset:0x2200
	ds_read_b64_tr_b16 v[194:195], v184 offset:0x2a00
	ds_read_b64_tr_b16 v[196:197], v184 offset:0x3200
	ds_read_b64_tr_b16 v[198:199], v184 offset:0x3a00
	s_waitcnt lgkmcnt(8)
	s_nop 0
	v_mfma_f32_32x32x16_bf16 v[2:17], v[106:109], v[82:85], v[2:17]
	v_exp_f32_e32 v1, v91
	v_exp_f32_e32 v82, v92
	v_exp_f32_e32 v83, v93
	v_mfma_f32_32x32x16_bf16 v[2:17], v[110:113], v[86:89], v[2:17]
	v_exp_f32_e32 v88, v90
	v_mfma_f32_32x32x16_bf16 v[2:17], v[116:119], v[124:127], v[2:17]
	v_mfma_f32_32x32x16_bf16 v[2:17], v[120:123], v[170:173], v[2:17]
	ds_read_b64_tr_b16 v[90:91], v184 offset:0x400
	ds_read_b64_tr_b16 v[92:93], v184 offset:0xc00
	ds_read_b64_tr_b16 v[124:125], v184 offset:0x1400
	ds_read_b64_tr_b16 v[126:127], v184 offset:0x1c00
	ds_read_b64_tr_b16 v[170:171], v184 offset:0x2400
	ds_read_b64_tr_b16 v[172:173], v184 offset:0x2c00
	ds_read_b64_tr_b16 v[200:201], v184 offset:0x3400
	ds_read_b64_tr_b16 v[202:203], v184 offset:0x3c00
	s_waitcnt lgkmcnt(8)
	v_mfma_f32_32x32x16_bf16 v[18:33], v[106:109], v[174:177], v[18:33]
	v_exp_f32_e32 v84, v94
	v_exp_f32_e32 v85, v95
	v_exp_f32_e32 v86, v96
	v_exp_f32_e32 v87, v97
	v_mfma_f32_32x32x16_bf16 v[18:33], v[110:113], v[178:181], v[18:33]
	v_mfma_f32_32x32x16_bf16 v[18:33], v[116:119], v[192:195], v[18:33]
	v_mfma_f32_32x32x16_bf16 v[18:33], v[120:123], v[196:199], v[18:33]
	ds_read_b64_tr_b16 v[94:95], v184 offset:0x600
	ds_read_b64_tr_b16 v[96:97], v184 offset:0xe00
	ds_read_b64_tr_b16 v[174:175], v184 offset:0x1600
	ds_read_b64_tr_b16 v[176:177], v184 offset:0x1e00
	ds_read_b64_tr_b16 v[178:179], v184 offset:0x2600
	ds_read_b64_tr_b16 v[180:181], v184 offset:0x2e00
	ds_read_b64_tr_b16 v[192:193], v184 offset:0x3600
	ds_read_b64_tr_b16 v[194:195], v184 offset:0x3e00
	s_waitcnt lgkmcnt(8)
	v_mfma_f32_32x32x16_bf16 v[34:49], v[106:109], v[90:93], v[34:49]
	v_exp_f32_e32 v90, v98
	v_exp_f32_e32 v89, v99
	v_exp_f32_e32 v92, v100
	v_exp_f32_e32 v91, v101
	v_mfma_f32_32x32x16_bf16 v[34:49], v[110:113], v[124:127], v[34:49]
	v_mfma_f32_32x32x16_bf16 v[34:49], v[116:119], v[170:173], v[34:49]
	v_mfma_f32_32x32x16_bf16 v[34:49], v[120:123], v[200:203], v[34:49]
	s_waitcnt lgkmcnt(0)
	v_mfma_f32_32x32x16_bf16 v[50:65], v[106:109], v[94:97], v[50:65]
	v_exp_f32_e32 v94, v102
	v_exp_f32_e32 v93, v103
	v_exp_f32_e32 v95, v104
	v_exp_f32_e32 v151, v105
	v_mfma_f32_32x32x16_bf16 v[50:65], v[110:113], v[174:177], v[50:65]
	v_mfma_f32_32x32x16_bf16 v[50:65], v[116:119], v[178:181], v[50:65]
	v_mfma_f32_32x32x16_bf16 v[50:65], v[120:123], v[192:195], v[50:65]
	s_waitcnt vmcnt(0)
	s_and_b64 vcc, exec, s[4:5]
	s_waitcnt vmcnt(0)
	s_barrier
	s_cbranch_vccnz .LBB0_911
	v_readlane_b32 s36, v243, 63
	v_readlane_b32 s50, v242, 13
	v_readlane_b32 s51, v242, 14
	s_add_u32 s4, s50, s88
	v_mov_b32_e32 v96, s25
	v_mov_b32_e32 v97, v145
	s_addc_u32 s5, s51, s87
	s_add_i32 s92, s92, s91
	v_lshl_add_u64 v[170:171], v[114:115], 1, v[96:97]
	v_add_u32_e32 v96, s92, v182
	v_add_u32_e32 v97, s10, v166
	v_mul_lo_u32 v96, v96, s22
	v_and_b32_e32 v98, 0x60, v97
	v_or3_b32 v96, v169, v96, v98
	v_ashrrev_i32_e32 v97, 31, v96
	s_add_i32 s90, s90, s89
	v_lshlrev_b64 v[172:173], 1, v[96:97]
	v_add_u32_e32 v96, s90, v182
	v_mul_lo_u32 v96, v96, s22
	v_or3_b32 v96, v169, v96, v98
	v_ashrrev_i32_e32 v97, 31, v96
	v_lshlrev_b64 v[174:175], 1, v[96:97]
	v_or_b32_e32 v172, s24, v172
	v_or_b32_e32 v174, s24, v174
	s_mov_b32 s16, 6
	v_readlane_b32 s37, v242, 0
	v_readlane_b32 s38, v242, 1
	v_readlane_b32 s39, v242, 2
	v_readlane_b32 s40, v242, 3
	v_readlane_b32 s41, v242, 4
	v_readlane_b32 s42, v242, 5
	v_readlane_b32 s43, v242, 6
	v_readlane_b32 s44, v242, 7
	v_readlane_b32 s45, v242, 8
	v_readlane_b32 s46, v242, 9
	v_readlane_b32 s47, v242, 10
	v_readlane_b32 s48, v242, 11
	v_readlane_b32 s49, v242, 12
	v_exp_f32_e32 v222, v66
	v_exp_f32_e32 v223, v67
	v_exp_f32_e32 v224, v68
	v_exp_f32_e32 v225, v69
	v_exp_f32_e32 v226, v70
	v_exp_f32_e32 v227, v71
	v_exp_f32_e32 v228, v72
	v_exp_f32_e32 v229, v73
	v_exp_f32_e32 v230, v74
	v_exp_f32_e32 v231, v75
	v_exp_f32_e32 v232, v76
	v_exp_f32_e32 v233, v77
	v_exp_f32_e32 v234, v78
	v_exp_f32_e32 v235, v79
	v_exp_f32_e32 v236, v80
	v_exp_f32_e32 v237, v81
	s_branch .LBB0_907
	.p2alignl 6, 3212836864

.LBB0_986:
	s_ashr_i32 s15, s14, 31
	s_lshl_b64 s[16:17], s[14:15], 20
	v_readlane_b32 s18, v242, 15
	v_readlane_b32 s19, v242, 16
	s_add_u32 s16, s18, s16
	s_addc_u32 s17, s19, s17
	s_and_b64 s[18:19], s[2:3], exec
	s_cselect_b32 s15, s17, s23
	s_cselect_b32 s69, s16, s22
	s_ashr_i32 s13, s12, 31
	s_lshl_b64 s[18:19], s[12:13], 20
	s_add_u32 s18, s20, s18
	s_addc_u32 s19, s24, s19
	s_and_b64 s[28:29], s[2:3], exec
	s_cselect_b32 s13, s19, s1
	s_cselect_b32 s70, s18, s0
	s_add_u32 s88, s22, 0x80080
	s_addc_u32 s89, s23, 0
	s_add_u32 s71, s0, 0x100
	v_mov_b32_e32 v2, 0
	s_addc_u32 s72, s1, 0
	s_mov_b32 s73, -2
	v_mov_b32_e32 v3, v2
	v_mov_b32_e32 v4, v2
	v_mov_b32_e32 v5, v2
	v_mov_b32_e32 v6, v2
	v_mov_b32_e32 v7, v2
	v_mov_b32_e32 v8, v2
	v_mov_b32_e32 v9, v2
	v_mov_b32_e32 v18, v2
	v_mov_b32_e32 v19, v2
	v_mov_b32_e32 v20, v2
	v_mov_b32_e32 v21, v2
	v_mov_b32_e32 v22, v2
	v_mov_b32_e32 v23, v2
	v_mov_b32_e32 v24, v2
	v_mov_b32_e32 v25, v2
	v_mov_b32_e32 v34, v2
	v_mov_b32_e32 v35, v2
	v_mov_b32_e32 v36, v2
	v_mov_b32_e32 v37, v2
	s_waitcnt lgkmcnt(0)
	v_mov_b32_e32 v38, v2
	v_mov_b32_e32 v39, v2
	v_mov_b32_e32 v40, v2
	v_mov_b32_e32 v41, v2
	v_mov_b32_e32 v50, v2
	v_mov_b32_e32 v51, v2
	v_mov_b32_e32 v52, v2
	v_mov_b32_e32 v53, v2
	v_mov_b32_e32 v54, v2
	v_mov_b32_e32 v55, v2
	v_mov_b32_e32 v56, v2
	v_mov_b32_e32 v57, v2
	v_mov_b32_e32 v10, v2
	v_mov_b32_e32 v11, v2
	v_mov_b32_e32 v12, v2
	v_mov_b32_e32 v13, v2
	v_mov_b32_e32 v14, v2
	v_mov_b32_e32 v15, v2
	v_mov_b32_e32 v16, v2
	v_mov_b32_e32 v17, v2
	v_mov_b32_e32 v26, v2
	v_mov_b32_e32 v27, v2
	v_mov_b32_e32 v28, v2
	v_mov_b32_e32 v29, v2
	v_mov_b32_e32 v30, v2
	v_mov_b32_e32 v31, v2
	v_mov_b32_e32 v32, v2
	v_mov_b32_e32 v33, v2
	v_mov_b32_e32 v42, v2
	v_mov_b32_e32 v43, v2
	v_mov_b32_e32 v44, v2
	v_mov_b32_e32 v45, v2
	v_mov_b32_e32 v46, v2
	v_mov_b32_e32 v47, v2
	v_mov_b32_e32 v48, v2
	v_mov_b32_e32 v49, v2
	v_mov_b32_e32 v58, v2
	v_mov_b32_e32 v59, v2
	v_mov_b32_e32 v60, v2
	v_mov_b32_e32 v61, v2
	v_mov_b32_e32 v62, v2
	v_mov_b32_e32 v63, v2
	v_mov_b32_e32 v64, v2
	v_mov_b32_e32 v65, v2
	v_mov_b32_e32 v66, v2
	v_mov_b32_e32 v67, v2
	v_mov_b32_e32 v68, v2
	v_mov_b32_e32 v69, v2
	v_mov_b32_e32 v70, v2
	v_mov_b32_e32 v71, v2
	v_mov_b32_e32 v72, v2
	v_mov_b32_e32 v73, v2
	v_mov_b32_e32 v82, v2
	v_mov_b32_e32 v83, v2
	v_mov_b32_e32 v84, v2
	v_mov_b32_e32 v85, v2
	v_mov_b32_e32 v86, v2
	v_mov_b32_e32 v87, v2
	v_mov_b32_e32 v88, v2
	v_mov_b32_e32 v89, v2
	v_mov_b32_e32 v98, v2
	v_mov_b32_e32 v99, v2
	v_mov_b32_e32 v100, v2
	v_mov_b32_e32 v101, v2
	v_mov_b32_e32 v102, v2
	v_mov_b32_e32 v103, v2
	v_mov_b32_e32 v104, v2
	v_mov_b32_e32 v105, v2
	v_mov_b32_e32 v114, v2
	v_mov_b32_e32 v115, v2
	v_mov_b32_e32 v116, v2
	v_mov_b32_e32 v117, v2
	v_mov_b32_e32 v118, v2
	v_mov_b32_e32 v119, v2
	v_mov_b32_e32 v120, v2
	v_mov_b32_e32 v121, v2
	v_mov_b32_e32 v74, v2
	v_mov_b32_e32 v75, v2
	v_mov_b32_e32 v76, v2
	v_mov_b32_e32 v77, v2
	v_mov_b32_e32 v78, v2
	v_mov_b32_e32 v79, v2
	v_mov_b32_e32 v80, v2
	v_mov_b32_e32 v81, v2
	v_mov_b32_e32 v90, v2
	v_mov_b32_e32 v91, v2
	v_mov_b32_e32 v92, v2
	v_mov_b32_e32 v93, v2
	v_mov_b32_e32 v94, v2
	v_mov_b32_e32 v95, v2
	v_mov_b32_e32 v96, v2
	v_mov_b32_e32 v97, v2
	v_mov_b32_e32 v106, v2
	v_mov_b32_e32 v107, v2
	v_mov_b32_e32 v108, v2
	v_mov_b32_e32 v109, v2
	v_mov_b32_e32 v110, v2
	v_mov_b32_e32 v111, v2
	v_mov_b32_e32 v112, v2
	v_mov_b32_e32 v113, v2
	v_mov_b32_e32 v122, v2
	v_mov_b32_e32 v123, v2
	v_mov_b32_e32 v124, v2
	v_mov_b32_e32 v125, v2
	v_mov_b32_e32 v126, v2
	v_mov_b32_e32 v127, v2
	v_mov_b32_e32 v128, v2
	v_mov_b32_e32 v129, v2
	.p2alignl 6, 3212836864

.LBB0_1061:
	s_ashr_i32 s15, s14, 31
	s_lshl_b64 s[28:29], s[14:15], 19
	s_add_u32 s15, s20, s28
	s_addc_u32 s21, s24, s29
	s_ashr_i32 s17, s16, 31
	s_lshl_b64 s[28:29], s[16:17], 22
	s_add_u32 s86, s15, s28
	s_addc_u32 s87, s21, s29
	s_and_b64 s[4:5], s[4:5], exec
	s_cselect_b32 s15, s87, s1
	s_cselect_b32 s17, s86, s0
	s_add_u32 s4, s22, 0x180080
	s_addc_u32 s5, s23, 0
	s_add_u32 s69, s0, 0x100
	v_mov_b32_e32 v2, 0
	s_addc_u32 s70, s1, 0
	s_mov_b32 s71, -2
	v_mov_b32_e32 v3, v2
	v_mov_b32_e32 v4, v2
	v_mov_b32_e32 v5, v2
	v_mov_b32_e32 v6, v2
	v_mov_b32_e32 v7, v2
	v_mov_b32_e32 v8, v2
	v_mov_b32_e32 v9, v2
	v_mov_b32_e32 v14, v2
	v_mov_b32_e32 v15, v2
	v_mov_b32_e32 v16, v2
	v_mov_b32_e32 v17, v2
	v_mov_b32_e32 v22, v2
	v_mov_b32_e32 v23, v2
	v_mov_b32_e32 v24, v2
	v_mov_b32_e32 v25, v2
	v_mov_b32_e32 v34, v2
	v_mov_b32_e32 v35, v2
	v_mov_b32_e32 v36, v2
	v_mov_b32_e32 v37, v2
	s_waitcnt lgkmcnt(0)
	v_mov_b32_e32 v38, v2
	v_mov_b32_e32 v39, v2
	v_mov_b32_e32 v40, v2
	v_mov_b32_e32 v41, v2
	v_mov_b32_e32 v42, v2
	v_mov_b32_e32 v43, v2
	v_mov_b32_e32 v44, v2
	v_mov_b32_e32 v45, v2
	v_mov_b32_e32 v46, v2
	v_mov_b32_e32 v47, v2
	v_mov_b32_e32 v48, v2
	v_mov_b32_e32 v49, v2
	v_mov_b32_e32 v10, v2
	v_mov_b32_e32 v11, v2
	v_mov_b32_e32 v12, v2
	v_mov_b32_e32 v13, v2
	v_mov_b32_e32 v18, v2
	v_mov_b32_e32 v19, v2
	v_mov_b32_e32 v20, v2
	v_mov_b32_e32 v21, v2
	v_mov_b32_e32 v26, v2
	v_mov_b32_e32 v27, v2
	v_mov_b32_e32 v28, v2
	v_mov_b32_e32 v29, v2
	v_mov_b32_e32 v30, v2
	v_mov_b32_e32 v31, v2
	v_mov_b32_e32 v32, v2
	v_mov_b32_e32 v33, v2
	v_mov_b32_e32 v50, v2
	v_mov_b32_e32 v51, v2
	v_mov_b32_e32 v52, v2
	v_mov_b32_e32 v53, v2
	v_mov_b32_e32 v54, v2
	v_mov_b32_e32 v55, v2
	v_mov_b32_e32 v56, v2
	v_mov_b32_e32 v57, v2
	v_mov_b32_e32 v58, v2
	v_mov_b32_e32 v59, v2
	v_mov_b32_e32 v60, v2
	v_mov_b32_e32 v61, v2
	v_mov_b32_e32 v62, v2
	v_mov_b32_e32 v63, v2
	v_mov_b32_e32 v64, v2
	v_mov_b32_e32 v65, v2
	v_mov_b32_e32 v66, v2
	v_mov_b32_e32 v67, v2
	v_mov_b32_e32 v68, v2
	v_mov_b32_e32 v69, v2
	v_mov_b32_e32 v70, v2
	v_mov_b32_e32 v71, v2
	v_mov_b32_e32 v72, v2
	v_mov_b32_e32 v73, v2
	v_mov_b32_e32 v74, v2
	v_mov_b32_e32 v75, v2
	v_mov_b32_e32 v76, v2
	v_mov_b32_e32 v77, v2
	v_mov_b32_e32 v78, v2
	v_mov_b32_e32 v79, v2
	v_mov_b32_e32 v80, v2
	v_mov_b32_e32 v81, v2
	v_mov_b32_e32 v98, v2
	v_mov_b32_e32 v99, v2
	v_mov_b32_e32 v100, v2
	v_mov_b32_e32 v101, v2
	v_mov_b32_e32 v102, v2
	v_mov_b32_e32 v103, v2
	v_mov_b32_e32 v104, v2
	v_mov_b32_e32 v105, v2
	v_mov_b32_e32 v106, v2
	v_mov_b32_e32 v107, v2
	v_mov_b32_e32 v108, v2
	v_mov_b32_e32 v109, v2
	v_mov_b32_e32 v110, v2
	v_mov_b32_e32 v111, v2
	v_mov_b32_e32 v112, v2
	v_mov_b32_e32 v113, v2
	v_mov_b32_e32 v82, v2
	v_mov_b32_e32 v83, v2
	v_mov_b32_e32 v84, v2
	v_mov_b32_e32 v85, v2
	v_mov_b32_e32 v86, v2
	v_mov_b32_e32 v87, v2
	v_mov_b32_e32 v88, v2
	v_mov_b32_e32 v89, v2
	v_mov_b32_e32 v90, v2
	v_mov_b32_e32 v91, v2
	v_mov_b32_e32 v92, v2
	v_mov_b32_e32 v93, v2
	v_mov_b32_e32 v94, v2
	v_mov_b32_e32 v95, v2
	v_mov_b32_e32 v96, v2
	v_mov_b32_e32 v97, v2
	v_mov_b32_e32 v114, v2
	v_mov_b32_e32 v115, v2
	v_mov_b32_e32 v116, v2
	v_mov_b32_e32 v117, v2
	v_mov_b32_e32 v118, v2
	v_mov_b32_e32 v119, v2
	v_mov_b32_e32 v120, v2
	v_mov_b32_e32 v121, v2
	v_mov_b32_e32 v122, v2
	v_mov_b32_e32 v123, v2
	v_mov_b32_e32 v124, v2
	v_mov_b32_e32 v125, v2
	v_mov_b32_e32 v126, v2
	v_mov_b32_e32 v127, v2
	v_mov_b32_e32 v128, v2
	v_mov_b32_e32 v129, v2
	.p2alignl 6, 3212836864

.LBB0_1166:
	s_ashr_i32 s15, s14, 31
	s_lshl_b64 s[16:17], s[14:15], 20
	v_readlane_b32 s18, v242, 15
	v_readlane_b32 s19, v242, 16
	s_add_u32 s16, s18, s16
	s_addc_u32 s17, s19, s17
	s_and_b64 s[18:19], s[2:3], exec
	s_cselect_b32 s15, s17, s23
	s_cselect_b32 s69, s16, s22
	s_ashr_i32 s13, s12, 31
	s_lshl_b64 s[18:19], s[12:13], 20
	s_add_u32 s18, s20, s18
	s_addc_u32 s19, s24, s19
	s_and_b64 s[28:29], s[2:3], exec
	s_cselect_b32 s13, s19, s1
	s_cselect_b32 s70, s18, s0
	s_add_u32 s88, s22, 0x80080
	s_addc_u32 s89, s23, 0
	s_add_u32 s71, s0, 0x100
	v_mov_b32_e32 v2, 0
	s_addc_u32 s72, s1, 0
	s_mov_b32 s73, -2
	v_mov_b32_e32 v3, v2
	v_mov_b32_e32 v4, v2
	v_mov_b32_e32 v5, v2
	v_mov_b32_e32 v34, v2
	v_mov_b32_e32 v35, v2
	v_mov_b32_e32 v36, v2
	v_mov_b32_e32 v37, v2
	v_mov_b32_e32 v6, v2
	v_mov_b32_e32 v7, v2
	v_mov_b32_e32 v8, v2
	v_mov_b32_e32 v9, v2
	s_waitcnt lgkmcnt(0)
	v_mov_b32_e32 v38, v2
	v_mov_b32_e32 v39, v2
	v_mov_b32_e32 v40, v2
	v_mov_b32_e32 v41, v2
	v_mov_b32_e32 v10, v2
	v_mov_b32_e32 v11, v2
	v_mov_b32_e32 v12, v2
	v_mov_b32_e32 v13, v2
	v_mov_b32_e32 v42, v2
	v_mov_b32_e32 v43, v2
	v_mov_b32_e32 v44, v2
	v_mov_b32_e32 v45, v2
	v_mov_b32_e32 v14, v2
	v_mov_b32_e32 v15, v2
	v_mov_b32_e32 v16, v2
	v_mov_b32_e32 v17, v2
	v_mov_b32_e32 v46, v2
	v_mov_b32_e32 v47, v2
	v_mov_b32_e32 v48, v2
	v_mov_b32_e32 v49, v2
	v_mov_b32_e32 v66, v2
	v_mov_b32_e32 v67, v2
	v_mov_b32_e32 v68, v2
	v_mov_b32_e32 v69, v2
	v_mov_b32_e32 v102, v2
	v_mov_b32_e32 v103, v2
	v_mov_b32_e32 v104, v2
	v_mov_b32_e32 v105, v2
	v_mov_b32_e32 v70, v2
	v_mov_b32_e32 v71, v2
	v_mov_b32_e32 v72, v2
	v_mov_b32_e32 v73, v2
	v_mov_b32_e32 v106, v2
	v_mov_b32_e32 v107, v2
	v_mov_b32_e32 v108, v2
	v_mov_b32_e32 v109, v2
	v_mov_b32_e32 v74, v2
	v_mov_b32_e32 v75, v2
	v_mov_b32_e32 v76, v2
	v_mov_b32_e32 v77, v2
	v_mov_b32_e32 v110, v2
	v_mov_b32_e32 v111, v2
	v_mov_b32_e32 v112, v2
	v_mov_b32_e32 v113, v2
	v_mov_b32_e32 v78, v2
	v_mov_b32_e32 v79, v2
	v_mov_b32_e32 v80, v2
	v_mov_b32_e32 v81, v2
	v_mov_b32_e32 v114, v2
	v_mov_b32_e32 v115, v2
	v_mov_b32_e32 v116, v2
	v_mov_b32_e32 v117, v2
	s_waitcnt vmcnt(0)
	v_mov_b32_e32 v18, v2
	v_mov_b32_e32 v19, v2
	v_mov_b32_e32 v20, v2
	v_mov_b32_e32 v21, v2
	v_mov_b32_e32 v50, v2
	v_mov_b32_e32 v51, v2
	v_mov_b32_e32 v52, v2
	v_mov_b32_e32 v53, v2
	v_mov_b32_e32 v22, v2
	v_mov_b32_e32 v23, v2
	v_mov_b32_e32 v24, v2
	v_mov_b32_e32 v25, v2
	v_mov_b32_e32 v54, v2
	v_mov_b32_e32 v55, v2
	v_mov_b32_e32 v56, v2
	v_mov_b32_e32 v57, v2
	v_mov_b32_e32 v26, v2
	v_mov_b32_e32 v27, v2
	v_mov_b32_e32 v28, v2
	v_mov_b32_e32 v29, v2
	v_mov_b32_e32 v58, v2
	v_mov_b32_e32 v59, v2
	v_mov_b32_e32 v60, v2
	v_mov_b32_e32 v61, v2
	v_mov_b32_e32 v30, v2
	v_mov_b32_e32 v31, v2
	v_mov_b32_e32 v32, v2
	v_mov_b32_e32 v33, v2
	v_mov_b32_e32 v62, v2
	v_mov_b32_e32 v63, v2
	v_mov_b32_e32 v64, v2
	v_mov_b32_e32 v65, v2
	v_mov_b32_e32 v82, v2
	v_mov_b32_e32 v83, v2
	v_mov_b32_e32 v84, v2
	v_mov_b32_e32 v85, v2
	v_mov_b32_e32 v118, v2
	v_mov_b32_e32 v119, v2
	v_mov_b32_e32 v120, v2
	v_mov_b32_e32 v121, v2
	v_mov_b32_e32 v86, v2
	v_mov_b32_e32 v87, v2
	v_mov_b32_e32 v88, v2
	v_mov_b32_e32 v89, v2
	v_mov_b32_e32 v122, v2
	v_mov_b32_e32 v123, v2
	v_mov_b32_e32 v124, v2
	v_mov_b32_e32 v125, v2
	v_mov_b32_e32 v94, v2
	v_mov_b32_e32 v95, v2
	v_mov_b32_e32 v96, v2
	v_mov_b32_e32 v97, v2
	v_mov_b32_e32 v126, v2
	v_mov_b32_e32 v127, v2
	v_mov_b32_e32 v128, v2
	v_mov_b32_e32 v129, v2
	v_mov_b32_e32 v98, v2
	v_mov_b32_e32 v99, v2
	v_mov_b32_e32 v100, v2
	v_mov_b32_e32 v101, v2
	v_mov_b32_e32 v130, v2
	v_mov_b32_e32 v131, v2
	v_mov_b32_e32 v132, v2
	v_mov_b32_e32 v133, v2
	.p2alignl 6, 3212836864

.LBB0_1295:
	s_ashr_i32 s15, s14, 31
	s_lshl_b64 s[16:17], s[14:15], 20
	v_readlane_b32 s18, v242, 15
	v_readlane_b32 s19, v242, 16
	s_add_u32 s16, s18, s16
	s_addc_u32 s17, s19, s17
	s_and_b64 s[18:19], s[2:3], exec
	s_cselect_b32 s15, s17, s23
	s_cselect_b32 s69, s16, s22
	s_ashr_i32 s13, s12, 31
	s_lshl_b64 s[18:19], s[12:13], 20
	s_add_u32 s18, s20, s18
	s_addc_u32 s19, s24, s19
	s_and_b64 s[28:29], s[2:3], exec
	s_cselect_b32 s13, s19, s1
	s_cselect_b32 s70, s18, s0
	s_add_u32 s88, s22, 0x80080
	s_addc_u32 s89, s23, 0
	s_add_u32 s71, s0, 0x100
	v_mov_b32_e32 v2, 0
	s_addc_u32 s72, s1, 0
	s_mov_b32 s73, -2
	v_mov_b32_e32 v3, v2
	v_mov_b32_e32 v4, v2
	v_mov_b32_e32 v5, v2
	v_mov_b32_e32 v10, v2
	v_mov_b32_e32 v11, v2
	v_mov_b32_e32 v12, v2
	v_mov_b32_e32 v13, v2
	v_mov_b32_e32 v18, v2
	v_mov_b32_e32 v19, v2
	v_mov_b32_e32 v20, v2
	v_mov_b32_e32 v21, v2
	v_mov_b32_e32 v26, v2
	v_mov_b32_e32 v27, v2
	v_mov_b32_e32 v28, v2
	v_mov_b32_e32 v29, v2
	v_mov_b32_e32 v34, v2
	v_mov_b32_e32 v35, v2
	v_mov_b32_e32 v36, v2
	v_mov_b32_e32 v37, v2
	v_mov_b32_e32 v42, v2
	v_mov_b32_e32 v43, v2
	v_mov_b32_e32 v44, v2
	v_mov_b32_e32 v45, v2
	v_mov_b32_e32 v50, v2
	v_mov_b32_e32 v51, v2
	v_mov_b32_e32 v52, v2
	v_mov_b32_e32 v53, v2
	v_mov_b32_e32 v58, v2
	v_mov_b32_e32 v59, v2
	v_mov_b32_e32 v60, v2
	v_mov_b32_e32 v61, v2
	v_mov_b32_e32 v6, v2
	v_mov_b32_e32 v7, v2
	v_mov_b32_e32 v8, v2
	v_mov_b32_e32 v9, v2
	v_mov_b32_e32 v14, v2
	v_mov_b32_e32 v15, v2
	v_mov_b32_e32 v16, v2
	v_mov_b32_e32 v17, v2
	v_mov_b32_e32 v22, v2
	v_mov_b32_e32 v23, v2
	v_mov_b32_e32 v24, v2
	v_mov_b32_e32 v25, v2
	v_mov_b32_e32 v30, v2
	v_mov_b32_e32 v31, v2
	v_mov_b32_e32 v32, v2
	v_mov_b32_e32 v33, v2
	s_waitcnt lgkmcnt(0)
	v_mov_b32_e32 v38, v2
	v_mov_b32_e32 v39, v2
	v_mov_b32_e32 v40, v2
	v_mov_b32_e32 v41, v2
	v_mov_b32_e32 v46, v2
	v_mov_b32_e32 v47, v2
	v_mov_b32_e32 v48, v2
	v_mov_b32_e32 v49, v2
	v_mov_b32_e32 v54, v2
	v_mov_b32_e32 v55, v2
	v_mov_b32_e32 v56, v2
	v_mov_b32_e32 v57, v2
	v_mov_b32_e32 v62, v2
	v_mov_b32_e32 v63, v2
	v_mov_b32_e32 v64, v2
	v_mov_b32_e32 v65, v2
	v_mov_b32_e32 v66, v2
	v_mov_b32_e32 v67, v2
	v_mov_b32_e32 v68, v2
	v_mov_b32_e32 v69, v2
	v_mov_b32_e32 v74, v2
	v_mov_b32_e32 v75, v2
	v_mov_b32_e32 v76, v2
	v_mov_b32_e32 v77, v2
	v_mov_b32_e32 v82, v2
	v_mov_b32_e32 v83, v2
	v_mov_b32_e32 v84, v2
	v_mov_b32_e32 v85, v2
	v_mov_b32_e32 v90, v2
	v_mov_b32_e32 v91, v2
	v_mov_b32_e32 v92, v2
	v_mov_b32_e32 v93, v2
	v_mov_b32_e32 v98, v2
	v_mov_b32_e32 v99, v2
	v_mov_b32_e32 v100, v2
	v_mov_b32_e32 v101, v2
	v_mov_b32_e32 v106, v2
	v_mov_b32_e32 v107, v2
	v_mov_b32_e32 v108, v2
	v_mov_b32_e32 v109, v2
	v_mov_b32_e32 v114, v2
	v_mov_b32_e32 v115, v2
	v_mov_b32_e32 v116, v2
	v_mov_b32_e32 v117, v2
	v_mov_b32_e32 v122, v2
	v_mov_b32_e32 v123, v2
	v_mov_b32_e32 v124, v2
	v_mov_b32_e32 v125, v2
	v_mov_b32_e32 v70, v2
	v_mov_b32_e32 v71, v2
	v_mov_b32_e32 v72, v2
	v_mov_b32_e32 v73, v2
	v_mov_b32_e32 v78, v2
	v_mov_b32_e32 v79, v2
	v_mov_b32_e32 v80, v2
	v_mov_b32_e32 v81, v2
	v_mov_b32_e32 v86, v2
	v_mov_b32_e32 v87, v2
	v_mov_b32_e32 v88, v2
	v_mov_b32_e32 v89, v2
	v_mov_b32_e32 v94, v2
	v_mov_b32_e32 v95, v2
	v_mov_b32_e32 v96, v2
	v_mov_b32_e32 v97, v2
	v_mov_b32_e32 v102, v2
	v_mov_b32_e32 v103, v2
	v_mov_b32_e32 v104, v2
	v_mov_b32_e32 v105, v2
	v_mov_b32_e32 v110, v2
	v_mov_b32_e32 v111, v2
	v_mov_b32_e32 v112, v2
	v_mov_b32_e32 v113, v2
	v_mov_b32_e32 v118, v2
	v_mov_b32_e32 v119, v2
	v_mov_b32_e32 v120, v2
	v_mov_b32_e32 v121, v2
	v_mov_b32_e32 v126, v2
	v_mov_b32_e32 v127, v2
	v_mov_b32_e32 v128, v2
	v_mov_b32_e32 v129, v2
	.p2alignl 6, 3212836864

.LBB0_1391:
	s_cmp_lg_u32 s18, 0
	s_cselect_b64 s[86:87], -1, 0
	s_cmp_eq_u32 s18, 0
	s_cselect_b32 s19, 0x58, 8
	s_add_i32 s68, s19, -2
	s_add_u32 s88, s24, 0x160080
	s_addc_u32 s89, s25, 0
	s_add_u32 s24, s0, 0x100
	v_mov_b32_e32 v2, 0
	s_mov_b32 s22, 0
	s_addc_u32 s25, s1, 0
	v_mov_b32_e32 v3, v2
	v_mov_b32_e32 v4, v2
	v_mov_b32_e32 v5, v2
	v_mov_b32_e32 v34, v2
	v_mov_b32_e32 v35, v2
	v_mov_b32_e32 v36, v2
	v_mov_b32_e32 v37, v2
	v_mov_b32_e32 v6, v2
	v_mov_b32_e32 v7, v2
	v_mov_b32_e32 v8, v2
	v_mov_b32_e32 v9, v2
	s_waitcnt lgkmcnt(0)
	v_mov_b32_e32 v38, v2
	v_mov_b32_e32 v39, v2
	v_mov_b32_e32 v40, v2
	v_mov_b32_e32 v41, v2
	v_mov_b32_e32 v10, v2
	v_mov_b32_e32 v11, v2
	v_mov_b32_e32 v12, v2
	v_mov_b32_e32 v13, v2
	v_mov_b32_e32 v42, v2
	v_mov_b32_e32 v43, v2
	v_mov_b32_e32 v44, v2
	v_mov_b32_e32 v45, v2
	v_mov_b32_e32 v14, v2
	v_mov_b32_e32 v15, v2
	v_mov_b32_e32 v16, v2
	v_mov_b32_e32 v17, v2
	v_mov_b32_e32 v46, v2
	v_mov_b32_e32 v47, v2
	v_mov_b32_e32 v48, v2
	v_mov_b32_e32 v49, v2
	v_mov_b32_e32 v66, v2
	v_mov_b32_e32 v67, v2
	v_mov_b32_e32 v68, v2
	v_mov_b32_e32 v69, v2
	v_mov_b32_e32 v98, v2
	v_mov_b32_e32 v99, v2
	v_mov_b32_e32 v100, v2
	v_mov_b32_e32 v101, v2
	v_mov_b32_e32 v70, v2
	v_mov_b32_e32 v71, v2
	v_mov_b32_e32 v72, v2
	v_mov_b32_e32 v73, v2
	v_mov_b32_e32 v102, v2
	v_mov_b32_e32 v103, v2
	v_mov_b32_e32 v104, v2
	v_mov_b32_e32 v105, v2
	v_mov_b32_e32 v74, v2
	v_mov_b32_e32 v75, v2
	v_mov_b32_e32 v76, v2
	v_mov_b32_e32 v77, v2
	v_mov_b32_e32 v106, v2
	v_mov_b32_e32 v107, v2
	v_mov_b32_e32 v108, v2
	v_mov_b32_e32 v109, v2
	v_mov_b32_e32 v78, v2
	v_mov_b32_e32 v79, v2
	v_mov_b32_e32 v80, v2
	v_mov_b32_e32 v81, v2
	v_mov_b32_e32 v110, v2
	v_mov_b32_e32 v111, v2
	v_mov_b32_e32 v112, v2
	v_mov_b32_e32 v113, v2
	s_waitcnt vmcnt(0)
	v_mov_b32_e32 v18, v2
	v_mov_b32_e32 v19, v2
	v_mov_b32_e32 v20, v2
	v_mov_b32_e32 v21, v2
	v_mov_b32_e32 v50, v2
	v_mov_b32_e32 v51, v2
	v_mov_b32_e32 v52, v2
	v_mov_b32_e32 v53, v2
	v_mov_b32_e32 v22, v2
	v_mov_b32_e32 v23, v2
	v_mov_b32_e32 v24, v2
	v_mov_b32_e32 v25, v2
	v_mov_b32_e32 v54, v2
	v_mov_b32_e32 v55, v2
	v_mov_b32_e32 v56, v2
	v_mov_b32_e32 v57, v2
	v_mov_b32_e32 v26, v2
	v_mov_b32_e32 v27, v2
	v_mov_b32_e32 v28, v2
	v_mov_b32_e32 v29, v2
	v_mov_b32_e32 v58, v2
	v_mov_b32_e32 v59, v2
	v_mov_b32_e32 v60, v2
	v_mov_b32_e32 v61, v2
	v_mov_b32_e32 v30, v2
	v_mov_b32_e32 v31, v2
	v_mov_b32_e32 v32, v2
	v_mov_b32_e32 v33, v2
	v_mov_b32_e32 v62, v2
	v_mov_b32_e32 v63, v2
	v_mov_b32_e32 v64, v2
	v_mov_b32_e32 v65, v2
	v_mov_b32_e32 v82, v2
	v_mov_b32_e32 v83, v2
	v_mov_b32_e32 v84, v2
	v_mov_b32_e32 v85, v2
	v_mov_b32_e32 v114, v2
	v_mov_b32_e32 v115, v2
	v_mov_b32_e32 v116, v2
	v_mov_b32_e32 v117, v2
	v_mov_b32_e32 v86, v2
	v_mov_b32_e32 v87, v2
	v_mov_b32_e32 v88, v2
	v_mov_b32_e32 v89, v2
	v_mov_b32_e32 v118, v2
	v_mov_b32_e32 v119, v2
	v_mov_b32_e32 v120, v2
	v_mov_b32_e32 v121, v2
	v_mov_b32_e32 v90, v2
	v_mov_b32_e32 v91, v2
	v_mov_b32_e32 v92, v2
	v_mov_b32_e32 v93, v2
	v_mov_b32_e32 v122, v2
	v_mov_b32_e32 v123, v2
	v_mov_b32_e32 v124, v2
	v_mov_b32_e32 v125, v2
	v_mov_b32_e32 v94, v2
	v_mov_b32_e32 v95, v2
	v_mov_b32_e32 v96, v2
	v_mov_b32_e32 v97, v2
	v_mov_b32_e32 v126, v2
	v_mov_b32_e32 v127, v2
	v_mov_b32_e32 v128, v2
	v_mov_b32_e32 v129, v2
	.p2alignl 6, 3212836864

.LBB0_1637:
	s_ashr_i32 s15, s14, 31
	s_lshl_b64 s[16:17], s[14:15], 20
	v_readlane_b32 s18, v242, 15
	v_readlane_b32 s19, v242, 16
	s_add_u32 s16, s18, s16
	s_addc_u32 s17, s19, s17
	s_and_b64 s[18:19], s[2:3], exec
	s_cselect_b32 s15, s17, s23
	s_cselect_b32 s56, s16, s22
	s_ashr_i32 s13, s12, 31
	s_lshl_b64 s[18:19], s[12:13], 20
	v_readlane_b32 s13, v243, 60
	s_add_u32 s18, s13, s18
	v_readlane_b32 s13, v243, 61
	s_addc_u32 s19, s13, s19
	s_and_b64 s[28:29], s[2:3], exec
	s_cselect_b32 s13, s19, s1
	s_cselect_b32 s57, s18, s0
	s_add_u32 s46, s22, 0x80080
	s_addc_u32 s47, s23, 0
	s_add_u32 s62, s0, 0x100
	v_mov_b32_e32 v2, 0
	s_addc_u32 s63, s1, 0
	s_mov_b32 s66, -2
	v_mov_b32_e32 v3, v2
	v_mov_b32_e32 v4, v2
	v_mov_b32_e32 v5, v2
	v_mov_b32_e32 v10, v2
	v_mov_b32_e32 v11, v2
	v_mov_b32_e32 v12, v2
	v_mov_b32_e32 v13, v2
	v_mov_b32_e32 v18, v2
	v_mov_b32_e32 v19, v2
	v_mov_b32_e32 v20, v2
	v_mov_b32_e32 v21, v2
	v_mov_b32_e32 v26, v2
	v_mov_b32_e32 v27, v2
	v_mov_b32_e32 v28, v2
	v_mov_b32_e32 v29, v2
	v_mov_b32_e32 v34, v2
	v_mov_b32_e32 v35, v2
	v_mov_b32_e32 v36, v2
	v_mov_b32_e32 v37, v2
	v_mov_b32_e32 v42, v2
	v_mov_b32_e32 v43, v2
	v_mov_b32_e32 v44, v2
	v_mov_b32_e32 v45, v2
	v_mov_b32_e32 v50, v2
	v_mov_b32_e32 v51, v2
	v_mov_b32_e32 v52, v2
	v_mov_b32_e32 v53, v2
	v_mov_b32_e32 v58, v2
	v_mov_b32_e32 v59, v2
	v_mov_b32_e32 v60, v2
	v_mov_b32_e32 v61, v2
	v_mov_b32_e32 v6, v2
	v_mov_b32_e32 v7, v2
	v_mov_b32_e32 v8, v2
	v_mov_b32_e32 v9, v2
	v_mov_b32_e32 v14, v2
	v_mov_b32_e32 v15, v2
	v_mov_b32_e32 v16, v2
	v_mov_b32_e32 v17, v2
	v_mov_b32_e32 v22, v2
	v_mov_b32_e32 v23, v2
	v_mov_b32_e32 v24, v2
	v_mov_b32_e32 v25, v2
	v_mov_b32_e32 v30, v2
	v_mov_b32_e32 v31, v2
	v_mov_b32_e32 v32, v2
	v_mov_b32_e32 v33, v2
	s_waitcnt lgkmcnt(0)
	v_mov_b32_e32 v38, v2
	v_mov_b32_e32 v39, v2
	v_mov_b32_e32 v40, v2
	v_mov_b32_e32 v41, v2
	v_mov_b32_e32 v46, v2
	v_mov_b32_e32 v47, v2
	v_mov_b32_e32 v48, v2
	v_mov_b32_e32 v49, v2
	v_mov_b32_e32 v54, v2
	v_mov_b32_e32 v55, v2
	v_mov_b32_e32 v56, v2
	v_mov_b32_e32 v57, v2
	v_mov_b32_e32 v62, v2
	v_mov_b32_e32 v63, v2
	v_mov_b32_e32 v64, v2
	v_mov_b32_e32 v65, v2
	v_mov_b32_e32 v66, v2
	v_mov_b32_e32 v67, v2
	v_mov_b32_e32 v68, v2
	v_mov_b32_e32 v69, v2
	v_mov_b32_e32 v74, v2
	v_mov_b32_e32 v75, v2
	v_mov_b32_e32 v76, v2
	v_mov_b32_e32 v77, v2
	v_mov_b32_e32 v82, v2
	v_mov_b32_e32 v83, v2
	v_mov_b32_e32 v84, v2
	v_mov_b32_e32 v85, v2
	v_mov_b32_e32 v90, v2
	v_mov_b32_e32 v91, v2
	v_mov_b32_e32 v92, v2
	v_mov_b32_e32 v93, v2
	v_mov_b32_e32 v98, v2
	v_mov_b32_e32 v99, v2
	v_mov_b32_e32 v100, v2
	v_mov_b32_e32 v101, v2
	v_mov_b32_e32 v106, v2
	v_mov_b32_e32 v107, v2
	v_mov_b32_e32 v108, v2
	v_mov_b32_e32 v109, v2
	v_mov_b32_e32 v114, v2
	v_mov_b32_e32 v115, v2
	v_mov_b32_e32 v116, v2
	v_mov_b32_e32 v117, v2
	v_mov_b32_e32 v122, v2
	v_mov_b32_e32 v123, v2
	v_mov_b32_e32 v124, v2
	v_mov_b32_e32 v125, v2
	v_mov_b32_e32 v70, v2
	v_mov_b32_e32 v71, v2
	v_mov_b32_e32 v72, v2
	v_mov_b32_e32 v73, v2
	v_mov_b32_e32 v78, v2
	v_mov_b32_e32 v79, v2
	v_mov_b32_e32 v80, v2
	v_mov_b32_e32 v81, v2
	v_mov_b32_e32 v86, v2
	v_mov_b32_e32 v87, v2
	v_mov_b32_e32 v88, v2
	v_mov_b32_e32 v89, v2
	v_mov_b32_e32 v94, v2
	v_mov_b32_e32 v95, v2
	v_mov_b32_e32 v96, v2
	v_mov_b32_e32 v97, v2
	v_mov_b32_e32 v102, v2
	v_mov_b32_e32 v103, v2
	v_mov_b32_e32 v104, v2
	v_mov_b32_e32 v105, v2
	v_mov_b32_e32 v110, v2
	v_mov_b32_e32 v111, v2
	v_mov_b32_e32 v112, v2
	v_mov_b32_e32 v113, v2
	v_mov_b32_e32 v118, v2
	v_mov_b32_e32 v119, v2
	v_mov_b32_e32 v120, v2
	v_mov_b32_e32 v121, v2
	v_mov_b32_e32 v126, v2
	v_mov_b32_e32 v127, v2
	v_mov_b32_e32 v128, v2
	v_mov_b32_e32 v129, v2
	.p2alignl 6, 3212836864

.LBB0_1733:
	s_cmp_lg_u32 s18, 0
	s_cselect_b64 s[46:47], -1, 0
	s_cmp_eq_u32 s18, 0
	s_cselect_b32 s19, 0x58, 8
	s_add_i32 s68, s19, -2
	s_add_u32 s44, s24, 0x160080
	s_addc_u32 s45, s25, 0
	s_add_u32 s24, s0, 0x100
	v_mov_b32_e32 v2, 0
	s_mov_b32 s22, 0
	s_addc_u32 s25, s1, 0
	v_mov_b32_e32 v3, v2
	v_mov_b32_e32 v4, v2
	v_mov_b32_e32 v5, v2
	v_mov_b32_e32 v34, v2
	v_mov_b32_e32 v35, v2
	v_mov_b32_e32 v36, v2
	v_mov_b32_e32 v37, v2
	v_mov_b32_e32 v6, v2
	v_mov_b32_e32 v7, v2
	v_mov_b32_e32 v8, v2
	v_mov_b32_e32 v9, v2
	s_waitcnt lgkmcnt(0)
	v_mov_b32_e32 v38, v2
	v_mov_b32_e32 v39, v2
	v_mov_b32_e32 v40, v2
	v_mov_b32_e32 v41, v2
	v_mov_b32_e32 v10, v2
	v_mov_b32_e32 v11, v2
	v_mov_b32_e32 v12, v2
	v_mov_b32_e32 v13, v2
	v_mov_b32_e32 v42, v2
	v_mov_b32_e32 v43, v2
	v_mov_b32_e32 v44, v2
	v_mov_b32_e32 v45, v2
	v_mov_b32_e32 v14, v2
	v_mov_b32_e32 v15, v2
	v_mov_b32_e32 v16, v2
	v_mov_b32_e32 v17, v2
	v_mov_b32_e32 v46, v2
	v_mov_b32_e32 v47, v2
	v_mov_b32_e32 v48, v2
	v_mov_b32_e32 v49, v2
	v_mov_b32_e32 v66, v2
	v_mov_b32_e32 v67, v2
	v_mov_b32_e32 v68, v2
	v_mov_b32_e32 v69, v2
	v_mov_b32_e32 v98, v2
	v_mov_b32_e32 v99, v2
	v_mov_b32_e32 v100, v2
	v_mov_b32_e32 v101, v2
	v_mov_b32_e32 v70, v2
	v_mov_b32_e32 v71, v2
	v_mov_b32_e32 v72, v2
	v_mov_b32_e32 v73, v2
	v_mov_b32_e32 v102, v2
	v_mov_b32_e32 v103, v2
	v_mov_b32_e32 v104, v2
	v_mov_b32_e32 v105, v2
	v_mov_b32_e32 v74, v2
	v_mov_b32_e32 v75, v2
	v_mov_b32_e32 v76, v2
	v_mov_b32_e32 v77, v2
	v_mov_b32_e32 v106, v2
	v_mov_b32_e32 v107, v2
	v_mov_b32_e32 v108, v2
	v_mov_b32_e32 v109, v2
	v_mov_b32_e32 v78, v2
	v_mov_b32_e32 v79, v2
	v_mov_b32_e32 v80, v2
	v_mov_b32_e32 v81, v2
	v_mov_b32_e32 v110, v2
	v_mov_b32_e32 v111, v2
	v_mov_b32_e32 v112, v2
	v_mov_b32_e32 v113, v2
	s_waitcnt vmcnt(0)
	v_mov_b32_e32 v18, v2
	v_mov_b32_e32 v19, v2
	v_mov_b32_e32 v20, v2
	v_mov_b32_e32 v21, v2
	v_mov_b32_e32 v50, v2
	v_mov_b32_e32 v51, v2
	v_mov_b32_e32 v52, v2
	v_mov_b32_e32 v53, v2
	v_mov_b32_e32 v22, v2
	v_mov_b32_e32 v23, v2
	v_mov_b32_e32 v24, v2
	v_mov_b32_e32 v25, v2
	v_mov_b32_e32 v54, v2
	v_mov_b32_e32 v55, v2
	v_mov_b32_e32 v56, v2
	v_mov_b32_e32 v57, v2
	v_mov_b32_e32 v26, v2
	v_mov_b32_e32 v27, v2
	v_mov_b32_e32 v28, v2
	v_mov_b32_e32 v29, v2
	v_mov_b32_e32 v58, v2
	v_mov_b32_e32 v59, v2
	v_mov_b32_e32 v60, v2
	v_mov_b32_e32 v61, v2
	v_mov_b32_e32 v30, v2
	v_mov_b32_e32 v31, v2
	v_mov_b32_e32 v32, v2
	v_mov_b32_e32 v33, v2
	v_mov_b32_e32 v62, v2
	v_mov_b32_e32 v63, v2
	v_mov_b32_e32 v64, v2
	v_mov_b32_e32 v65, v2
	v_mov_b32_e32 v82, v2
	v_mov_b32_e32 v83, v2
	v_mov_b32_e32 v84, v2
	v_mov_b32_e32 v85, v2
	v_mov_b32_e32 v114, v2
	v_mov_b32_e32 v115, v2
	v_mov_b32_e32 v116, v2
	v_mov_b32_e32 v117, v2
	v_mov_b32_e32 v86, v2
	v_mov_b32_e32 v87, v2
	v_mov_b32_e32 v88, v2
	v_mov_b32_e32 v89, v2
	v_mov_b32_e32 v118, v2
	v_mov_b32_e32 v119, v2
	v_mov_b32_e32 v120, v2
	v_mov_b32_e32 v121, v2
	v_mov_b32_e32 v90, v2
	v_mov_b32_e32 v91, v2
	v_mov_b32_e32 v92, v2
	v_mov_b32_e32 v93, v2
	v_mov_b32_e32 v122, v2
	v_mov_b32_e32 v123, v2
	v_mov_b32_e32 v124, v2
	v_mov_b32_e32 v125, v2
	v_mov_b32_e32 v94, v2
	v_mov_b32_e32 v95, v2
	v_mov_b32_e32 v96, v2
	v_mov_b32_e32 v97, v2
	v_mov_b32_e32 v126, v2
	v_mov_b32_e32 v127, v2
	v_mov_b32_e32 v128, v2
	v_mov_b32_e32 v129, v2
	.p2alignl 6, 3212836864

.LBB0_1874:
	s_ashr_i32 s17, s16, 31
	s_lshl_b64 s[18:19], s[16:17], 20
	v_readlane_b32 s28, v242, 15
	v_readlane_b32 s29, v242, 16
	s_add_u32 s18, s28, s18
	s_addc_u32 s19, s29, s19
	s_and_b64 s[28:29], s[2:3], exec
	s_cselect_b32 s5, s19, s23
	s_cselect_b32 s17, s18, s22
	s_ashr_i32 s15, s14, 31
	s_lshl_b64 s[28:29], s[14:15], 20
	s_add_u32 s44, s20, s28
	s_addc_u32 s45, s24, s29
	s_and_b64 s[28:29], s[2:3], exec
	s_cselect_b32 s15, s45, s1
	s_cselect_b32 s63, s44, s0
	s_add_u32 s52, s22, 0x80080
	s_addc_u32 s53, s23, 0
	s_add_u32 s66, s0, 0x100
	v_mov_b32_e32 v2, 0
	s_addc_u32 s67, s1, 0
	s_mov_b32 s68, -2
	v_mov_b32_e32 v3, v2
	v_mov_b32_e32 v4, v2
	v_mov_b32_e32 v5, v2
	v_mov_b32_e32 v6, v2
	v_mov_b32_e32 v7, v2
	v_mov_b32_e32 v8, v2
	v_mov_b32_e32 v9, v2
	v_mov_b32_e32 v18, v2
	v_mov_b32_e32 v19, v2
	v_mov_b32_e32 v20, v2
	v_mov_b32_e32 v21, v2
	v_mov_b32_e32 v22, v2
	v_mov_b32_e32 v23, v2
	v_mov_b32_e32 v24, v2
	v_mov_b32_e32 v25, v2
	v_mov_b32_e32 v34, v2
	v_mov_b32_e32 v35, v2
	v_mov_b32_e32 v36, v2
	v_mov_b32_e32 v37, v2
	s_waitcnt lgkmcnt(0)
	v_mov_b32_e32 v38, v2
	v_mov_b32_e32 v39, v2
	v_mov_b32_e32 v40, v2
	v_mov_b32_e32 v41, v2
	v_mov_b32_e32 v50, v2
	v_mov_b32_e32 v51, v2
	v_mov_b32_e32 v52, v2
	v_mov_b32_e32 v53, v2
	v_mov_b32_e32 v54, v2
	v_mov_b32_e32 v55, v2
	v_mov_b32_e32 v56, v2
	v_mov_b32_e32 v57, v2
	v_mov_b32_e32 v10, v2
	v_mov_b32_e32 v11, v2
	v_mov_b32_e32 v12, v2
	v_mov_b32_e32 v13, v2
	v_mov_b32_e32 v14, v2
	v_mov_b32_e32 v15, v2
	v_mov_b32_e32 v16, v2
	v_mov_b32_e32 v17, v2
	v_mov_b32_e32 v26, v2
	v_mov_b32_e32 v27, v2
	v_mov_b32_e32 v28, v2
	v_mov_b32_e32 v29, v2
	v_mov_b32_e32 v30, v2
	v_mov_b32_e32 v31, v2
	v_mov_b32_e32 v32, v2
	v_mov_b32_e32 v33, v2
	v_mov_b32_e32 v42, v2
	v_mov_b32_e32 v43, v2
	v_mov_b32_e32 v44, v2
	v_mov_b32_e32 v45, v2
	v_mov_b32_e32 v46, v2
	v_mov_b32_e32 v47, v2
	v_mov_b32_e32 v48, v2
	v_mov_b32_e32 v49, v2
	v_mov_b32_e32 v58, v2
	v_mov_b32_e32 v59, v2
	v_mov_b32_e32 v60, v2
	v_mov_b32_e32 v61, v2
	v_mov_b32_e32 v62, v2
	v_mov_b32_e32 v63, v2
	v_mov_b32_e32 v64, v2
	v_mov_b32_e32 v65, v2
	v_mov_b32_e32 v66, v2
	v_mov_b32_e32 v67, v2
	v_mov_b32_e32 v68, v2
	v_mov_b32_e32 v69, v2
	v_mov_b32_e32 v70, v2
	v_mov_b32_e32 v71, v2
	v_mov_b32_e32 v72, v2
	v_mov_b32_e32 v73, v2
	v_mov_b32_e32 v82, v2
	v_mov_b32_e32 v83, v2
	v_mov_b32_e32 v84, v2
	v_mov_b32_e32 v85, v2
	v_mov_b32_e32 v86, v2
	v_mov_b32_e32 v87, v2
	v_mov_b32_e32 v88, v2
	v_mov_b32_e32 v89, v2
	v_mov_b32_e32 v98, v2
	v_mov_b32_e32 v99, v2
	v_mov_b32_e32 v100, v2
	v_mov_b32_e32 v101, v2
	v_mov_b32_e32 v102, v2
	v_mov_b32_e32 v103, v2
	v_mov_b32_e32 v104, v2
	v_mov_b32_e32 v105, v2
	v_mov_b32_e32 v114, v2
	v_mov_b32_e32 v115, v2
	v_mov_b32_e32 v116, v2
	v_mov_b32_e32 v117, v2
	v_mov_b32_e32 v118, v2
	v_mov_b32_e32 v119, v2
	v_mov_b32_e32 v120, v2
	v_mov_b32_e32 v121, v2
	v_mov_b32_e32 v74, v2
	v_mov_b32_e32 v75, v2
	v_mov_b32_e32 v76, v2
	v_mov_b32_e32 v77, v2
	v_mov_b32_e32 v78, v2
	v_mov_b32_e32 v79, v2
	v_mov_b32_e32 v80, v2
	v_mov_b32_e32 v81, v2
	v_mov_b32_e32 v90, v2
	v_mov_b32_e32 v91, v2
	v_mov_b32_e32 v92, v2
	v_mov_b32_e32 v93, v2
	v_mov_b32_e32 v94, v2
	v_mov_b32_e32 v95, v2
	v_mov_b32_e32 v96, v2
	v_mov_b32_e32 v97, v2
	v_mov_b32_e32 v106, v2
	v_mov_b32_e32 v107, v2
	v_mov_b32_e32 v108, v2
	v_mov_b32_e32 v109, v2
	v_mov_b32_e32 v110, v2
	v_mov_b32_e32 v111, v2
	v_mov_b32_e32 v112, v2
	v_mov_b32_e32 v113, v2
	v_mov_b32_e32 v122, v2
	v_mov_b32_e32 v123, v2
	v_mov_b32_e32 v124, v2
	v_mov_b32_e32 v125, v2
	v_mov_b32_e32 v126, v2
	v_mov_b32_e32 v127, v2
	v_mov_b32_e32 v128, v2
	v_mov_b32_e32 v129, v2
	.p2alignl 6, 3212836864

.LBB0_2083:
	s_ashr_i32 s13, s12, 31
	s_lshl_b64 s[16:17], s[12:13], 18
	s_add_u32 s16, s24, s16
	s_addc_u32 s17, s25, s17
	s_and_b64 s[4:5], s[4:5], exec
	s_cselect_b32 s13, s17, s1
	s_cselect_b32 s62, s16, s0
	s_add_u32 s4, s18, 0x180080
	s_addc_u32 s5, s19, 0
	s_add_u32 s63, s0, 0x100
	v_mov_b32_e32 v2, 0
	s_addc_u32 s66, s1, 0
	s_mov_b32 s67, -2
	v_mov_b32_e32 v3, v2
	v_mov_b32_e32 v4, v2
	v_mov_b32_e32 v5, v2
	v_mov_b32_e32 v6, v2
	v_mov_b32_e32 v7, v2
	v_mov_b32_e32 v8, v2
	v_mov_b32_e32 v9, v2
	v_mov_b32_e32 v10, v2
	v_mov_b32_e32 v11, v2
	v_mov_b32_e32 v12, v2
	v_mov_b32_e32 v13, v2
	v_mov_b32_e32 v14, v2
	v_mov_b32_e32 v15, v2
	v_mov_b32_e32 v16, v2
	v_mov_b32_e32 v17, v2
	v_mov_b32_e32 v26, v2
	v_mov_b32_e32 v27, v2
	v_mov_b32_e32 v28, v2
	v_mov_b32_e32 v29, v2
	v_mov_b32_e32 v30, v2
	v_mov_b32_e32 v31, v2
	v_mov_b32_e32 v32, v2
	v_mov_b32_e32 v33, v2
	v_mov_b32_e32 v42, v2
	v_mov_b32_e32 v43, v2
	v_mov_b32_e32 v44, v2
	v_mov_b32_e32 v45, v2
	v_mov_b32_e32 v46, v2
	v_mov_b32_e32 v47, v2
	v_mov_b32_e32 v48, v2
	v_mov_b32_e32 v49, v2
	v_mov_b32_e32 v18, v2
	v_mov_b32_e32 v19, v2
	v_mov_b32_e32 v20, v2
	v_mov_b32_e32 v21, v2
	v_mov_b32_e32 v22, v2
	v_mov_b32_e32 v23, v2
	v_mov_b32_e32 v24, v2
	v_mov_b32_e32 v25, v2
	v_mov_b32_e32 v34, v2
	v_mov_b32_e32 v35, v2
	v_mov_b32_e32 v36, v2
	v_mov_b32_e32 v37, v2
	s_waitcnt lgkmcnt(0)
	v_mov_b32_e32 v38, v2
	v_mov_b32_e32 v39, v2
	v_mov_b32_e32 v40, v2
	v_mov_b32_e32 v41, v2
	v_mov_b32_e32 v50, v2
	v_mov_b32_e32 v51, v2
	v_mov_b32_e32 v52, v2
	v_mov_b32_e32 v53, v2
	v_mov_b32_e32 v54, v2
	v_mov_b32_e32 v55, v2
	v_mov_b32_e32 v56, v2
	v_mov_b32_e32 v57, v2
	v_mov_b32_e32 v58, v2
	v_mov_b32_e32 v59, v2
	v_mov_b32_e32 v60, v2
	v_mov_b32_e32 v61, v2
	v_mov_b32_e32 v62, v2
	v_mov_b32_e32 v63, v2
	v_mov_b32_e32 v64, v2
	v_mov_b32_e32 v65, v2
	v_mov_b32_e32 v66, v2
	v_mov_b32_e32 v67, v2
	v_mov_b32_e32 v68, v2
	v_mov_b32_e32 v69, v2
	v_mov_b32_e32 v70, v2
	v_mov_b32_e32 v71, v2
	v_mov_b32_e32 v72, v2
	v_mov_b32_e32 v73, v2
	v_mov_b32_e32 v74, v2
	v_mov_b32_e32 v75, v2
	v_mov_b32_e32 v76, v2
	v_mov_b32_e32 v77, v2
	v_mov_b32_e32 v78, v2
	v_mov_b32_e32 v79, v2
	v_mov_b32_e32 v80, v2
	v_mov_b32_e32 v81, v2
	v_mov_b32_e32 v90, v2
	v_mov_b32_e32 v91, v2
	v_mov_b32_e32 v92, v2
	v_mov_b32_e32 v93, v2
	v_mov_b32_e32 v94, v2
	v_mov_b32_e32 v95, v2
	v_mov_b32_e32 v96, v2
	v_mov_b32_e32 v97, v2
	v_mov_b32_e32 v106, v2
	v_mov_b32_e32 v107, v2
	v_mov_b32_e32 v108, v2
	v_mov_b32_e32 v109, v2
	v_mov_b32_e32 v110, v2
	v_mov_b32_e32 v111, v2
	v_mov_b32_e32 v112, v2
	v_mov_b32_e32 v113, v2
	v_mov_b32_e32 v82, v2
	v_mov_b32_e32 v83, v2
	v_mov_b32_e32 v84, v2
	v_mov_b32_e32 v85, v2
	v_mov_b32_e32 v86, v2
	v_mov_b32_e32 v87, v2
	v_mov_b32_e32 v88, v2
	v_mov_b32_e32 v89, v2
	v_mov_b32_e32 v98, v2
	v_mov_b32_e32 v99, v2
	v_mov_b32_e32 v100, v2
	v_mov_b32_e32 v101, v2
	v_mov_b32_e32 v102, v2
	v_mov_b32_e32 v103, v2
	v_mov_b32_e32 v104, v2
	v_mov_b32_e32 v105, v2
	v_mov_b32_e32 v114, v2
	v_mov_b32_e32 v115, v2
	v_mov_b32_e32 v116, v2
	v_mov_b32_e32 v117, v2
	v_mov_b32_e32 v118, v2
	v_mov_b32_e32 v119, v2
	v_mov_b32_e32 v120, v2
	v_mov_b32_e32 v121, v2
	v_mov_b32_e32 v122, v2
	v_mov_b32_e32 v123, v2
	v_mov_b32_e32 v124, v2
	v_mov_b32_e32 v125, v2
	v_mov_b32_e32 v126, v2
	v_mov_b32_e32 v127, v2
	v_mov_b32_e32 v128, v2
	v_mov_b32_e32 v129, v2
	.p2alignl 6, 3212836864

.LBB0_2101:
	s_ashr_i32 s15, s14, 31
	s_lshl_b64 s[0:1], s[14:15], 17
	s_add_u32 s46, s27, s0
	s_addc_u32 s47, s30, s1
	s_and_b64 s[0:1], s[4:5], exec
	v_mov_b32_e32 v2, 0
	s_cselect_b32 s15, s47, s17
	s_cselect_b32 s78, s46, s16
	s_mov_b32 s24, 0
	s_mov_b64 s[4:5], -1
	s_mov_b64 s[0:1], 0
	v_mov_b32_e32 v3, v2
	v_mov_b32_e32 v4, v2
	v_mov_b32_e32 v5, v2
	v_mov_b32_e32 v6, v2
	v_mov_b32_e32 v7, v2
	v_mov_b32_e32 v8, v2
	v_mov_b32_e32 v9, v2
	v_mov_b32_e32 v10, v2
	v_mov_b32_e32 v11, v2
	v_mov_b32_e32 v12, v2
	v_mov_b32_e32 v13, v2
	v_mov_b32_e32 v14, v2
	v_mov_b32_e32 v15, v2
	v_mov_b32_e32 v16, v2
	v_mov_b32_e32 v17, v2
	v_mov_b32_e32 v26, v2
	v_mov_b32_e32 v27, v2
	v_mov_b32_e32 v28, v2
	v_mov_b32_e32 v29, v2
	v_mov_b32_e32 v30, v2
	v_mov_b32_e32 v31, v2
	v_mov_b32_e32 v32, v2
	v_mov_b32_e32 v33, v2
	v_mov_b32_e32 v42, v2
	v_mov_b32_e32 v43, v2
	v_mov_b32_e32 v44, v2
	v_mov_b32_e32 v45, v2
	v_mov_b32_e32 v46, v2
	v_mov_b32_e32 v47, v2
	v_mov_b32_e32 v48, v2
	v_mov_b32_e32 v49, v2
	v_mov_b32_e32 v18, v2
	v_mov_b32_e32 v19, v2
	v_mov_b32_e32 v20, v2
	v_mov_b32_e32 v21, v2
	v_mov_b32_e32 v22, v2
	v_mov_b32_e32 v23, v2
	v_mov_b32_e32 v24, v2
	v_mov_b32_e32 v25, v2
	v_mov_b32_e32 v34, v2
	v_mov_b32_e32 v35, v2
	v_mov_b32_e32 v36, v2
	v_mov_b32_e32 v37, v2
	s_waitcnt lgkmcnt(0)
	v_mov_b32_e32 v38, v2
	v_mov_b32_e32 v39, v2
	v_mov_b32_e32 v40, v2
	v_mov_b32_e32 v41, v2
	v_mov_b32_e32 v50, v2
	v_mov_b32_e32 v51, v2
	v_mov_b32_e32 v52, v2
	v_mov_b32_e32 v53, v2
	v_mov_b32_e32 v54, v2
	v_mov_b32_e32 v55, v2
	v_mov_b32_e32 v56, v2
	v_mov_b32_e32 v57, v2
	v_mov_b32_e32 v58, v2
	v_mov_b32_e32 v59, v2
	v_mov_b32_e32 v60, v2
	v_mov_b32_e32 v61, v2
	v_mov_b32_e32 v62, v2
	v_mov_b32_e32 v63, v2
	v_mov_b32_e32 v64, v2
	v_mov_b32_e32 v65, v2
	v_mov_b32_e32 v66, v2
	v_mov_b32_e32 v67, v2
	v_mov_b32_e32 v68, v2
	v_mov_b32_e32 v69, v2
	v_mov_b32_e32 v70, v2
	v_mov_b32_e32 v71, v2
	v_mov_b32_e32 v72, v2
	v_mov_b32_e32 v73, v2
	v_mov_b32_e32 v74, v2
	v_mov_b32_e32 v75, v2
	v_mov_b32_e32 v76, v2
	v_mov_b32_e32 v77, v2
	v_mov_b32_e32 v78, v2
	v_mov_b32_e32 v79, v2
	v_mov_b32_e32 v80, v2
	v_mov_b32_e32 v81, v2
	v_mov_b32_e32 v90, v2
	v_mov_b32_e32 v91, v2
	v_mov_b32_e32 v92, v2
	v_mov_b32_e32 v93, v2
	v_mov_b32_e32 v94, v2
	v_mov_b32_e32 v95, v2
	v_mov_b32_e32 v96, v2
	v_mov_b32_e32 v97, v2
	v_mov_b32_e32 v106, v2
	v_mov_b32_e32 v107, v2
	v_mov_b32_e32 v108, v2
	v_mov_b32_e32 v109, v2
	v_mov_b32_e32 v110, v2
	v_mov_b32_e32 v111, v2
	v_mov_b32_e32 v112, v2
	v_mov_b32_e32 v113, v2
	v_mov_b32_e32 v82, v2
	v_mov_b32_e32 v83, v2
	v_mov_b32_e32 v84, v2
	v_mov_b32_e32 v85, v2
	v_mov_b32_e32 v86, v2
	v_mov_b32_e32 v87, v2
	v_mov_b32_e32 v88, v2
	v_mov_b32_e32 v89, v2
	v_mov_b32_e32 v98, v2
	v_mov_b32_e32 v99, v2
	v_mov_b32_e32 v100, v2
	v_mov_b32_e32 v101, v2
	v_mov_b32_e32 v102, v2
	v_mov_b32_e32 v103, v2
	v_mov_b32_e32 v104, v2
	v_mov_b32_e32 v105, v2
	v_mov_b32_e32 v114, v2
	v_mov_b32_e32 v115, v2
	v_mov_b32_e32 v116, v2
	v_mov_b32_e32 v117, v2
	v_mov_b32_e32 v118, v2
	v_mov_b32_e32 v119, v2
	v_mov_b32_e32 v120, v2
	v_mov_b32_e32 v121, v2
	v_mov_b32_e32 v122, v2
	v_mov_b32_e32 v123, v2
	v_mov_b32_e32 v124, v2
	v_mov_b32_e32 v125, v2
	v_mov_b32_e32 v126, v2
	v_mov_b32_e32 v127, v2
	v_mov_b32_e32 v128, v2
	v_mov_b32_e32 v129, v2
	.p2alignl 6, 3212836864

.LBB0_2311:
	s_ashr_i32 s14, s33, 9
	s_ashr_i32 s15, s14, 31
	s_lshl_b32 s0, s33, 8
	s_lshl_b64 s[8:9], s[14:15], 14
	s_and_b32 s0, s0, 0x3f00
	s_or_b32 s8, s8, s0
	s_lshl_b32 s0, s14, 8
	s_add_i32 s0, s0, 0x8000
	s_mul_i32 s4, s9, 0xc00
	s_mul_hi_u32 s12, s8, 0xc00
	s_bfe_u32 s36, s33, 0x30006
	s_ashr_i32 s1, s0, 31
	s_add_i32 s12, s12, s4
	s_mul_i32 s4, s8, 0xc00
	v_readlane_b32 s28, v242, 21
	v_readlane_b32 s29, v242, 22
	s_add_u32 s4, s28, s4
	s_addc_u32 s12, s29, s12
	s_mul_i32 s21, s36, 0x180
	s_add_u32 s28, s4, s21
	s_addc_u32 s29, s12, 0
	s_mul_i32 s12, s0, 0xc00
	s_mul_hi_i32 s4, s0, 0xc00
	s_add_u32 s12, s24, s12
	s_addc_u32 s4, s25, s4
	s_add_u32 s12, s12, s21
	s_addc_u32 s13, s4, 0
	s_mul_i32 s35, s14, 0x3000000
	s_mul_hi_i32 s4, s14, 0x3000000
	s_add_u32 s35, s24, s35
	s_addc_u32 s4, s25, s4
	s_add_u32 s38, s35, s21
	s_addc_u32 s39, s4, 0
	s_lshl_b64 s[0:1], s[0:1], 12
	s_add_u32 s0, s31, s0
	s_addc_u32 s1, s34, s1
	s_lshl_b32 s4, s36, 9
	s_add_u32 s0, s0, s4
	s_addc_u32 s1, s1, 0
	s_add_u32 s44, s0, 0x100
	s_addc_u32 s45, s1, 0
	s_lshl_b64 s[14:15], s[14:15], 26
	s_add_u32 s14, s31, s14
	s_addc_u32 s15, s34, s15
	s_add_u32 s4, s14, s4
	s_addc_u32 s14, s15, 0
	s_add_u32 s46, s4, 0x100
	v_readfirstlane_b32 s52, v0
	s_addc_u32 s47, s14, 0
	s_lshr_b32 s37, s52, 6
	s_lshl_b32 s35, s37, 5
	v_or_b32_e32 v4, s35, v165
	v_mov_b64_e32 v[2:3], s[28:29]
	v_mad_u64_u32 v[2:3], s[14:15], v4, s19, v[2:3]
	s_andn2_b32 s52, s52, 63
	v_lshl_add_u64 v[2:3], v[2:3], 0, v[148:149]
	global_load_dwordx4 v[142:145], v[2:3], off
	global_load_dwordx4 v[138:141], v[2:3], off offset:32
	global_load_dwordx4 v[134:137], v[2:3], off offset:64
	global_load_dwordx4 v[130:133], v[2:3], off offset:96
	global_load_dwordx4 v[126:129], v[2:3], off offset:128
	global_load_dwordx4 v[122:125], v[2:3], off offset:160
	global_load_dwordx4 v[118:121], v[2:3], off offset:192
	global_load_dwordx4 v[114:117], v[2:3], off offset:224
	global_load_dwordx4 v[110:113], v[2:3], off offset:256
	global_load_dwordx4 v[106:109], v[2:3], off offset:288
	global_load_dwordx4 v[102:105], v[2:3], off offset:320
	global_load_dwordx4 v[98:101], v[2:3], off offset:352
	v_or_b32_e32 v2, s52, v166
	v_mul_hi_i32 v3, v2, s20
	v_lshrrev_b32_e32 v4, 31, v3
	v_ashrrev_i32_e32 v3, 2, v3
	v_add_u32_e32 v3, v3, v4
	v_mul_lo_u32 v4, v3, 24
	v_sub_u32_e32 v4, v2, v4
	v_mul_lo_u32 v5, v3, s22
	v_lshrrev_b32_e32 v3, 1, v3
	v_bitop3_b32 v3, v3, v4, 7 bitop3:0x6c
	v_lshl_add_u32 v160, v3, 3, v5
	v_add_u32_e32 v3, 0x200, v2
	v_mul_hi_i32 v4, v3, s20
	v_lshrrev_b32_e32 v5, 31, v4
	v_ashrrev_i32_e32 v4, 2, v4
	v_add_u32_e32 v4, v4, v5
	v_mul_lo_u32 v5, v4, 24
	v_sub_u32_e32 v3, v3, v5
	v_mul_lo_u32 v5, v4, s22
	v_lshrrev_b32_e32 v4, 1, v4
	v_bitop3_b32 v3, v4, v3, 7 bitop3:0x6c
	v_lshl_add_u32 v162, v3, 3, v5
	v_add_u32_e32 v3, 0x400, v2
	v_mul_hi_i32 v4, v3, s20
	v_lshrrev_b32_e32 v5, 31, v4
	v_ashrrev_i32_e32 v4, 2, v4
	v_add_u32_e32 v4, v4, v5
	s_ashr_i32 s4, s52, 4
	v_mul_lo_u32 v5, v4, 24
	s_and_b32 s14, s4, 0x1ffff0
	s_lshr_b32 s4, s4, 1
	v_sub_u32_e32 v3, v3, v5
	v_mul_lo_u32 v5, v4, s22
	v_lshrrev_b32_e32 v4, 1, v4
	s_and_b32 s4, s4, 4
	v_bitop3_b32 v3, v4, v3, 7 bitop3:0x6c
	s_or_b32 s4, s14, s4
	v_lshl_add_u32 v168, v3, 3, v5
	v_or_b32_e32 v3, s4, v178
	s_add_i32 s4, s52, 0x200
	s_ashr_i32 s4, s4, 4
	s_and_b32 s14, s4, 0x1ffff0
	s_lshr_b32 s4, s4, 1
	s_and_b32 s4, s4, 4
	v_and_or_b32 v2, v2, s16, v177
	s_or_b32 s4, s14, s4
	v_lshl_or_b32 v170, v3, 11, v2
	v_or_b32_e32 v3, s4, v178
	s_lshl_b32 s4, s37, 10
	s_add_i32 s53, s4, 0
	v_ashrrev_i32_e32 v161, 31, v160
	v_lshl_or_b32 v172, v3, 11, v2
	s_add_i32 m0, s53, 0x8000
	v_lshl_add_u64 v[2:3], v[160:161], 1, s[12:13]
	v_ashrrev_i32_e32 v163, 31, v162
	global_load_lds_dwordx4 v[2:3], off
	v_lshl_add_u64 v[2:3], v[162:163], 1, s[12:13]
	s_add_i32 m0, s53, 0xa000
	v_ashrrev_i32_e32 v169, 31, v168
	global_load_lds_dwordx4 v[2:3], off
	v_lshl_add_u64 v[2:3], v[168:169], 1, s[12:13]
	s_add_i32 m0, s53, 0xc000
	v_ashrrev_i32_e32 v171, 31, v170
	global_load_lds_dwordx4 v[2:3], off
	v_lshl_add_u64 v[2:3], v[170:171], 1, s[0:1]
	v_lshl_add_u64 v[2:3], v[2:3], 0, s[6:7]
	s_mov_b32 m0, s53
	v_ashrrev_i32_e32 v173, 31, v172
	global_load_lds_dwordx4 v[2:3], off
	v_lshl_add_u64 v[2:3], v[172:173], 1, s[0:1]
	v_lshl_add_u64 v[2:3], v[2:3], 0, s[6:7]
	s_add_i32 m0, s53, 0x2000
	s_mov_b32 s4, -3
	global_load_lds_dwordx4 v[2:3], off
	s_waitcnt vmcnt(0)
	s_mov_b64 s[0:1], 64
	v_mov_b32_e32 v151, 0
	v_mov_b32_e32 v2, 0
	v_mov_b32_e32 v3, v147
	v_mov_b32_e32 v4, v147
	v_mov_b32_e32 v5, v147
	v_mov_b32_e32 v6, v147
	v_mov_b32_e32 v7, v147
	v_mov_b32_e32 v8, v147
	v_mov_b32_e32 v9, v147
	v_mov_b32_e32 v10, v147
	v_mov_b32_e32 v11, v147
	v_mov_b32_e32 v12, v147
	v_mov_b32_e32 v13, v147
	v_mov_b32_e32 v14, v147
	v_mov_b32_e32 v15, v147
	v_mov_b32_e32 v16, v147
	v_mov_b32_e32 v17, v147
	v_mov_b32_e32 v18, 0
	v_mov_b32_e32 v19, v147
	v_mov_b32_e32 v20, v147
	v_mov_b32_e32 v21, v147
	v_mov_b32_e32 v22, v147
	v_mov_b32_e32 v23, v147
	v_mov_b32_e32 v24, v147
	v_mov_b32_e32 v25, v147
	v_mov_b32_e32 v26, v147
	v_mov_b32_e32 v27, v147
	v_mov_b32_e32 v28, v147
	v_mov_b32_e32 v29, v147
	v_mov_b32_e32 v30, v147
	v_mov_b32_e32 v31, v147
	v_mov_b32_e32 v32, v147
	v_mov_b32_e32 v33, v147
	v_mov_b32_e32 v34, 0
	v_mov_b32_e32 v35, v147
	v_mov_b32_e32 v36, v147
	v_mov_b32_e32 v37, v147
	v_mov_b32_e32 v38, v147
	v_mov_b32_e32 v39, v147
	v_mov_b32_e32 v40, v147
	v_mov_b32_e32 v41, v147
	v_mov_b32_e32 v42, v147
	v_mov_b32_e32 v43, v147
	v_mov_b32_e32 v44, v147
	v_mov_b32_e32 v45, v147
	v_mov_b32_e32 v46, v147
	v_mov_b32_e32 v47, v147
	v_mov_b32_e32 v48, v147
	v_mov_b32_e32 v49, v147
	v_mov_b32_e32 v50, 0
	v_mov_b32_e32 v51, v147
	v_mov_b32_e32 v52, v147
	v_mov_b32_e32 v53, v147
	v_mov_b32_e32 v54, v147
	v_mov_b32_e32 v55, v147
	v_mov_b32_e32 v56, v147
	v_mov_b32_e32 v57, v147
	v_mov_b32_e32 v58, v147
	v_mov_b32_e32 v59, v147
	v_mov_b32_e32 v60, v147
	v_mov_b32_e32 v61, v147
	v_mov_b32_e32 v62, v147
	v_mov_b32_e32 v63, v147
	v_mov_b32_e32 v64, v147
	v_mov_b32_e32 v65, v147
	s_waitcnt vmcnt(0) lgkmcnt(0)
	s_barrier
	.p2alignl 6, 3212836864

.LBB0_2318:
	s_lshl_b32 s0, s30, 1
	s_and_b32 s24, s0, 0x700
	s_ashr_i32 s0, s30, 10
	s_ashr_i32 s1, s0, 31
	s_lshl_b64 s[46:47], s[0:1], 14
	s_lshl_b32 s1, s30, 8
	s_and_b32 s1, s1, 0x3f00
	s_or_b32 s46, s46, s1
	s_bfe_u32 s23, s30, 0x40006
	s_mul_i32 s4, s47, 0x3000
	s_mul_hi_u32 s21, s46, 0x3000
	s_lshl_b32 s52, s23, 7
	s_lshl_b32 s1, s0, 8
	s_add_i32 s21, s21, s4
	s_mul_i32 s4, s46, 0x3000
	v_readlane_b32 s40, v242, 17
	v_readlane_b32 s41, v242, 18
	s_add_u32 s4, s40, s4
	s_addc_u32 s21, s41, s21
	s_add_u32 s4, s4, s52
	s_addc_u32 s21, s21, 0
	s_add_u32 s28, s4, 0x1000
	s_addc_u32 s29, s21, 0
	s_mul_i32 s4, s0, 0x300000
	s_mul_hi_i32 s1, s1, 0x3000
	s_add_u32 s4, s40, s4
	s_addc_u32 s21, s41, s1
	s_add_u32 s34, s4, s52
	s_addc_u32 s35, s21, 0
	s_mul_i32 s58, s0, 0xc000000
	s_mul_hi_i32 s25, s0, 0xc000000
	s_add_u32 s0, s40, s58
	s_addc_u32 s1, s41, s25
	s_add_u32 s0, s0, s52
	s_addc_u32 s1, s1, 0
	s_and_b32 s31, s52, 0x700
	s_add_u32 s61, s4, s31
	s_addc_u32 s62, s21, 0
	s_add_u32 s40, s61, 0x18002000
	v_readfirstlane_b32 s33, v0
	s_addc_u32 s41, s62, 0
	s_lshr_b32 s31, s33, 6
	s_lshl_b32 s4, s31, 5
	v_or_b32_e32 v4, s4, v165
	v_mov_b64_e32 v[2:3], s[28:29]
	v_mad_u64_u32 v[2:3], s[28:29], v4, s20, v[2:3]
	v_lshl_add_u64 v[2:3], v[2:3], 0, v[132:133]
	global_load_dwordx4 v[114:117], v[2:3], off
	global_load_dwordx4 v[118:121], v[2:3], off offset:32
	global_load_dwordx4 v[122:125], v[2:3], off offset:64
	global_load_dwordx4 v[126:129], v[2:3], off offset:96
	s_andn2_b32 s33, s33, 63
	s_ashr_i32 s21, s33, 4
	s_and_b32 s28, s21, -16
	s_lshr_b32 s21, s21, 1
	s_and_b32 s21, s21, 4
	v_or_b32_e32 v2, s33, v166
	s_or_b32 s60, s28, s21
	s_add_i32 s21, s33, 0x200
	v_ashrrev_i32_e32 v3, 31, v2
	s_ashr_i32 s21, s21, 4
	v_lshrrev_b32_e32 v3, 29, v3
	s_and_b32 s28, s21, -16
	s_lshr_b32 s21, s21, 1
	v_add_u32_e32 v3, v2, v3
	s_and_b32 s21, s21, 4
	v_ashrrev_i32_e32 v5, 3, v3
	v_and_b32_e32 v3, 0x1ffffff8, v3
	s_or_b32 s59, s28, s21
	v_sub_u32_e32 v3, v2, v3
	v_lshrrev_b32_e32 v4, 1, v5
	v_and_b32_e32 v137, 0x60, v2
	v_or_b32_e32 v2, s60, v163
	v_or_b32_e32 v6, s59, v163
	v_bitop3_b32 v3, v4, v3, 7 bitop3:0x6c
	v_or_b32_e32 v4, v137, v162
	v_mul_lo_u32 v2, v2, s22
	v_mul_lo_u32 v6, v6, s22
	v_mul_lo_u32 v5, v5, s22
	v_or_b32_e32 v2, v2, v4
	v_or_b32_e32 v4, v6, v4
	v_lshl_add_u32 v6, v3, 3, v5
	v_ashrrev_i32_e32 v7, 31, v6
	v_lshlrev_b64 v[150:151], 1, v[6:7]
	s_lshl_b32 s21, s31, 10
	v_lshl_add_u64 v[98:99], s[34:35], 0, v[150:151]
	s_add_i32 s34, s21, 0
	s_add_i32 s35, s34, 0x8000
	v_ashrrev_i32_e32 v3, 31, v2
	v_lshl_add_u64 v[6:7], v[98:99], 0, s[6:7]
	s_mov_b32 m0, s35
	v_lshlrev_b64 v[152:153], 1, v[2:3]
	v_ashrrev_i32_e32 v5, 31, v4
	global_load_lds_dwordx4 v[6:7], off
	v_lshl_add_u64 v[2:3], s[40:41], 0, v[152:153]
	s_mov_b32 m0, s34
	v_lshlrev_b64 v[154:155], 1, v[4:5]
	s_add_i32 s54, s34, 0x2000
	global_load_lds_dwordx4 v[2:3], off
	v_lshl_add_u64 v[2:3], s[40:41], 0, v[154:155]
	s_mov_b32 m0, s54
	s_add_i32 s55, s34, 0xa000
	global_load_lds_dwordx4 v[2:3], off
	v_lshl_add_u64 v[2:3], v[98:99], 0, s[8:9]
	s_mov_b32 m0, s55
	s_waitcnt vmcnt(0)
	s_waitcnt vmcnt(0) lgkmcnt(0)
	s_barrier
	global_load_lds_dwordx4 v[2:3], off
	ds_read_b128 v[2:5], v172 offset:32768
	ds_read_b128 v[18:21], v172 offset:36864
	s_waitcnt lgkmcnt(0)
	v_mfma_f32_32x32x16_bf16 v[2:17], v[2:5], v[114:117], 0
	ds_read_b128 v[22:25], v173 offset:32768
	ds_read_b128 v[34:37], v173 offset:36864
	s_add_u32 s28, s61, 0x180c2000
	v_lshl_add_u64 v[30:31], v[98:99], 0, s[12:13]
	s_mov_b32 m0, s35
	s_addc_u32 s29, s62, 0
	s_add_i32 s56, s34, 0x4000
	s_add_i32 s57, s34, 0x6000
	s_waitcnt lgkmcnt(0)
	v_mfma_f32_32x32x16_bf16 v[2:17], v[22:25], v[118:121], v[2:17]
	ds_read_b128 v[22:25], v174 offset:32768
	ds_read_b128 v[38:41], v174 offset:36864
	ds_read_b128 v[26:29], v175 offset:32768
	ds_read_b128 v[42:45], v175 offset:36864
	s_waitcnt vmcnt(0)
	s_waitcnt vmcnt(0) lgkmcnt(0)
	s_barrier
	global_load_lds_dwordx4 v[30:31], off
	v_mfma_f32_32x32x16_bf16 v[2:17], v[22:25], v[122:125], v[2:17]
	v_lshl_add_u64 v[22:23], s[28:29], 0, v[152:153]
	s_mov_b32 m0, s56
	s_mov_b32 s53, s5
	global_load_lds_dwordx4 v[22:23], off
	v_lshl_add_u64 v[22:23], s[28:29], 0, v[154:155]
	s_mov_b32 m0, s57
	v_mfma_f32_32x32x16_bf16 v[2:17], v[26:29], v[126:129], v[2:17]
	global_load_lds_dwordx4 v[22:23], off
	v_mfma_f32_32x32x16_bf16 v[18:33], v[18:21], v[114:117], 0
	s_nop 9
	v_exp_f32_e32 v54, v2
	v_exp_f32_e32 v55, v3
	v_exp_f32_e32 v56, v4
	v_exp_f32_e32 v57, v5
	v_exp_f32_e32 v58, v6
	v_exp_f32_e32 v59, v7
	v_exp_f32_e32 v60, v8
	v_mfma_f32_32x32x16_bf16 v[18:33], v[34:37], v[118:121], v[18:33]
	v_exp_f32_e32 v61, v9
	v_exp_f32_e32 v62, v10
	v_exp_f32_e32 v63, v11
	v_exp_f32_e32 v64, v12
	v_exp_f32_e32 v65, v13
	v_exp_f32_e32 v102, v14
	v_exp_f32_e32 v103, v15
	v_mfma_f32_32x32x16_bf16 v[18:33], v[38:41], v[122:125], v[18:33]
	v_exp_f32_e32 v104, v16
	v_exp_f32_e32 v105, v17
	ds_read_b128 v[2:5], v172 offset:40960
	ds_read_b128 v[6:9], v172 offset:45056
	ds_read_b128 v[10:13], v173 offset:40960
	ds_read_b128 v[14:17], v173 offset:45056
	ds_read_b128 v[34:37], v174 offset:40960
	ds_read_b128 v[38:41], v174 offset:45056
	ds_read_b128 v[46:49], v175 offset:40960
	ds_read_b128 v[50:53], v175 offset:45056
	v_mfma_f32_32x32x16_bf16 v[18:33], v[42:45], v[126:129], v[18:33]
	s_waitcnt lgkmcnt(0)
	v_mfma_f32_32x32x16_bf16 v[66:81], v[6:9], v[114:117], 0
	v_mfma_f32_32x32x16_bf16 v[82:97], v[2:5], v[114:117], 0
	s_nop 8
	v_exp_f32_e32 v2, v18
	v_exp_f32_e32 v3, v19
	v_exp_f32_e32 v4, v20
	v_exp_f32_e32 v5, v21
	v_exp_f32_e32 v18, v22
	v_exp_f32_e32 v19, v23
	v_exp_f32_e32 v20, v24
	v_exp_f32_e32 v21, v25
	v_mfma_f32_32x32x16_bf16 v[66:81], v[14:17], v[118:121], v[66:81]
	v_exp_f32_e32 v6, v26
	v_exp_f32_e32 v7, v27
	v_exp_f32_e32 v8, v28
	v_exp_f32_e32 v9, v29
	v_mfma_f32_32x32x16_bf16 v[82:97], v[10:13], v[118:121], v[82:97]
	v_exp_f32_e32 v10, v30
	v_exp_f32_e32 v11, v31
	v_exp_f32_e32 v12, v32
	v_exp_f32_e32 v13, v33
	v_add_f32_e32 v14, v54, v55
	v_add_f32_e32 v15, v2, v3
	v_mfma_f32_32x32x16_bf16 v[66:81], v[38:41], v[122:125], v[66:81]
	v_add_f32_e32 v14, v14, v56
	v_add_f32_e32 v15, v15, v4
	v_cvt_pk_bf16_f32 v54, v54, v55
	v_add_f32_e32 v14, v14, v57
	v_add_f32_e32 v15, v15, v5
	v_cvt_pk_bf16_f32 v55, v56, v57
	v_add_f32_e32 v14, v14, v58
	v_add_f32_e32 v15, v15, v18
	v_cvt_pk_bf16_f32 v56, v58, v59
	v_add_f32_e32 v14, v14, v59
	v_add_f32_e32 v15, v15, v19
	v_cvt_pk_bf16_f32 v57, v60, v61
	v_add_f32_e32 v14, v14, v60
	v_add_f32_e32 v15, v15, v20
	s_nop 0
	v_permlane32_swap_b32_e32 v54, v56
	v_add_f32_e32 v14, v14, v61
	v_add_f32_e32 v15, v15, v21
	v_permlane32_swap_b32_e32 v55, v57
	v_add_f32_e32 v14, v14, v62
	v_add_f32_e32 v15, v15, v6
	v_mfma_f32_32x32x16_bf16 v[82:97], v[34:37], v[122:125], v[82:97]
	v_add_f32_e32 v14, v14, v63
	v_add_f32_e32 v15, v15, v7
	s_nop 0
	v_add_f32_e32 v14, v14, v64
	v_add_f32_e32 v15, v15, v8
	s_nop 0
	v_add_f32_e32 v14, v14, v65
	v_add_f32_e32 v15, v15, v9
	s_nop 0
	v_add_f32_e32 v14, v14, v102
	v_add_f32_e32 v15, v15, v10
	s_nop 0
	v_add_f32_e32 v14, v14, v103
	v_add_f32_e32 v15, v15, v11
	s_nop 0
	v_add_f32_e32 v14, v14, v104
	v_add_f32_e32 v15, v15, v12
	s_nop 0
	v_add_f32_e32 v14, v14, v105
	v_add_f32_e32 v15, v15, v13
	s_nop 0
	v_add_f32_e32 v14, v14, v15
	v_mov_b32_e32 v15, v14
	s_nop 1
	v_permlane32_swap_b32_e32 v14, v15
	v_add_f32_e32 v14, v14, v15
	v_add_f32_e32 v135, 0, v14
	v_mfma_f32_32x32x16_bf16 v[66:81], v[50:53], v[126:129], v[66:81]
	v_cvt_pk_bf16_f32 v100, v62, v63
	v_cvt_pk_bf16_f32 v101, v64, v65
	v_cvt_pk_bf16_f32 v102, v102, v103
	v_cvt_pk_bf16_f32 v103, v104, v105
	v_cvt_pk_bf16_f32 v104, v2, v3
	v_cvt_pk_bf16_f32 v105, v4, v5
	v_cvt_pk_bf16_f32 v106, v18, v19
	v_cvt_pk_bf16_f32 v107, v20, v21
	v_cvt_pk_bf16_f32 v108, v6, v7
	v_cvt_pk_bf16_f32 v109, v8, v9
	v_cvt_pk_bf16_f32 v110, v10, v11
	v_cvt_pk_bf16_f32 v111, v12, v13
	v_mfma_f32_32x32x16_bf16 v[82:97], v[46:49], v[126:129], v[82:97]
	v_permlane32_swap_b32_e32 v100, v102
	v_permlane32_swap_b32_e32 v101, v103
	v_permlane32_swap_b32_e32 v104, v106
	v_permlane32_swap_b32_e32 v105, v107
	v_permlane32_swap_b32_e32 v108, v110
	v_permlane32_swap_b32_e32 v109, v111
	ds_read_b64_tr_b16 v[2:3], v168 offset:0
	ds_read_b64_tr_b16 v[4:5], v168 offset:0x800
	ds_read_b64_tr_b16 v[18:19], v168 offset:0x1000
	ds_read_b64_tr_b16 v[20:21], v168 offset:0x1800
	ds_read_b64_tr_b16 v[22:23], v168 offset:0x2000
	ds_read_b64_tr_b16 v[24:25], v168 offset:0x2800
	ds_read_b64_tr_b16 v[26:27], v168 offset:0x3000
	ds_read_b64_tr_b16 v[28:29], v168 offset:0x3800
	ds_read_b64_tr_b16 v[30:31], v168 offset:0x200
	ds_read_b64_tr_b16 v[32:33], v168 offset:0xa00
	ds_read_b64_tr_b16 v[34:35], v168 offset:0x1200
	ds_read_b64_tr_b16 v[36:37], v168 offset:0x1a00
	ds_read_b64_tr_b16 v[38:39], v168 offset:0x2200
	ds_read_b64_tr_b16 v[40:41], v168 offset:0x2a00
	ds_read_b64_tr_b16 v[42:43], v168 offset:0x3200
	ds_read_b64_tr_b16 v[44:45], v168 offset:0x3a00
	s_waitcnt lgkmcnt(8)
	s_nop 0
	v_mfma_f32_32x32x16_bf16 v[2:17], v[54:57], v[2:5], 0
	s_nop 3
	v_exp_f32_e32 v139, v82
	v_exp_f32_e32 v141, v83
	v_exp_f32_e32 v143, v84
	v_exp_f32_e32 v145, v85
	v_mfma_f32_32x32x16_bf16 v[2:17], v[100:103], v[18:21], v[2:17]
	v_mfma_f32_32x32x16_bf16 v[2:17], v[104:107], v[22:25], v[2:17]
	v_mfma_f32_32x32x16_bf16 v[2:17], v[108:111], v[26:29], v[2:17]
	ds_read_b64_tr_b16 v[46:47], v168 offset:0x400
	ds_read_b64_tr_b16 v[48:49], v168 offset:0xc00
	ds_read_b64_tr_b16 v[50:51], v168 offset:0x1400
	ds_read_b64_tr_b16 v[52:53], v168 offset:0x1c00
	ds_read_b64_tr_b16 v[58:59], v168 offset:0x2400
	ds_read_b64_tr_b16 v[60:61], v168 offset:0x2c00
	ds_read_b64_tr_b16 v[62:63], v168 offset:0x3400
	ds_read_b64_tr_b16 v[64:65], v168 offset:0x3c00
	s_waitcnt lgkmcnt(8)
	v_mfma_f32_32x32x16_bf16 v[18:33], v[54:57], v[30:33], 0
	v_exp_f32_e32 v147, v86
	v_exp_f32_e32 v149, v87
	v_exp_f32_e32 v196, v88
	v_exp_f32_e32 v197, v89
	v_mfma_f32_32x32x16_bf16 v[18:33], v[100:103], v[34:37], v[18:33]
	v_mfma_f32_32x32x16_bf16 v[18:33], v[104:107], v[38:41], v[18:33]
	v_mfma_f32_32x32x16_bf16 v[18:33], v[108:111], v[42:45], v[18:33]
	ds_read_b64_tr_b16 v[82:83], v168 offset:0x600
	ds_read_b64_tr_b16 v[84:85], v168 offset:0xe00
	ds_read_b64_tr_b16 v[86:87], v168 offset:0x1600
	ds_read_b64_tr_b16 v[88:89], v168 offset:0x1e00
	ds_read_b64_tr_b16 v[156:157], v168 offset:0x2600
	ds_read_b64_tr_b16 v[158:159], v168 offset:0x2e00
	ds_read_b64_tr_b16 v[176:177], v168 offset:0x3600
	ds_read_b64_tr_b16 v[178:179], v168 offset:0x3e00
	s_waitcnt lgkmcnt(8)
	v_mfma_f32_32x32x16_bf16 v[34:49], v[54:57], v[46:49], 0
	v_exp_f32_e32 v198, v90
	v_exp_f32_e32 v199, v91
	v_exp_f32_e32 v200, v92
	v_exp_f32_e32 v201, v93
	v_mfma_f32_32x32x16_bf16 v[34:49], v[100:103], v[50:53], v[34:49]
	v_mfma_f32_32x32x16_bf16 v[34:49], v[104:107], v[58:61], v[34:49]
	v_mfma_f32_32x32x16_bf16 v[34:49], v[108:111], v[62:65], v[34:49]
	s_waitcnt lgkmcnt(0)
	v_mfma_f32_32x32x16_bf16 v[50:65], v[54:57], v[82:85], 0
	v_exp_f32_e32 v202, v94
	v_exp_f32_e32 v203, v95
	v_exp_f32_e32 v204, v96
	v_exp_f32_e32 v205, v97
	v_mfma_f32_32x32x16_bf16 v[50:65], v[100:103], v[86:89], v[50:65]
	v_mfma_f32_32x32x16_bf16 v[50:65], v[104:107], v[156:159], v[50:65]
	v_mfma_f32_32x32x16_bf16 v[50:65], v[108:111], v[176:179], v[50:65]
	s_add_u32 s28, s61, 0x18182000
	s_mov_b32 m0, s55
	v_lshl_add_u64 v[82:83], v[98:99], 0, s[16:17]
	s_addc_u32 s29, s62, 0
	s_waitcnt vmcnt(0)
	s_waitcnt vmcnt(0)
	s_barrier
	global_load_lds_dwordx4 v[82:83], off
	v_lshl_add_u64 v[82:83], s[28:29], 0, v[152:153]
	s_mov_b32 m0, s34
	v_lshl_add_u64 v[90:91], s[0:1], 0, v[150:151]
	global_load_lds_dwordx4 v[82:83], off
	v_lshl_add_u64 v[82:83], s[28:29], 0, v[154:155]
	s_mov_b32 m0, s54
	v_lshl_add_u64 v[160:161], v[90:91], 0, s[14:15]
	global_load_lds_dwordx4 v[82:83], off
	ds_read_b128 v[82:85], v172 offset:32768
	ds_read_b128 v[86:89], v172 offset:36864
	ds_read_b128 v[156:159], v173 offset:32768
	ds_read_b128 v[176:179], v173 offset:36864
	ds_read_b128 v[180:183], v174 offset:32768
	ds_read_b128 v[184:187], v174 offset:36864
	ds_read_b128 v[188:191], v175 offset:32768
	ds_read_b128 v[192:195], v175 offset:36864
	s_waitcnt lgkmcnt(0)
	v_mfma_f32_32x32x16_bf16 v[98:113], v[82:85], v[114:117], 0
	v_exp_f32_e32 v206, v66
	v_exp_f32_e32 v207, v67
	v_exp_f32_e32 v208, v68
	v_exp_f32_e32 v209, v69
	v_exp_f32_e32 v210, v70
	v_exp_f32_e32 v211, v71
	v_exp_f32_e32 v212, v72
	v_exp_f32_e32 v213, v73
	v_mfma_f32_32x32x16_bf16 v[82:97], v[86:89], v[114:117], 0
	v_exp_f32_e32 v81, v81
	v_mfma_f32_32x32x16_bf16 v[98:113], v[156:159], v[118:121], v[98:113]
	v_exp_f32_e32 v157, v74
	v_exp_f32_e32 v159, v75
	v_exp_f32_e32 v214, v76
	v_exp_f32_e32 v215, v77
	v_exp_f32_e32 v216, v78
	v_exp_f32_e32 v217, v79
	v_exp_f32_e32 v218, v80
	v_mfma_f32_32x32x16_bf16 v[82:97], v[176:179], v[118:121], v[82:97]
	v_add_f32_e32 v66, v139, v141
	v_add_f32_e32 v67, v206, v207
	v_cvt_pk_bf16_f32 v68, v147, v149
	v_add_f32_e32 v66, v66, v143
	v_add_f32_e32 v67, v67, v208
	v_cvt_pk_bf16_f32 v69, v196, v197
	v_add_f32_e32 v66, v66, v145
	v_add_f32_e32 v67, v67, v209
	v_mfma_f32_32x32x16_bf16 v[98:113], v[180:183], v[122:125], v[98:113]
	v_add_f32_e32 v66, v66, v147
	v_add_f32_e32 v67, v67, v210
	s_nop 0
	v_add_f32_e32 v66, v66, v149
	v_add_f32_e32 v67, v67, v211
	s_nop 0
	v_add_f32_e32 v66, v66, v196
	v_add_f32_e32 v67, v67, v212
	v_mfma_f32_32x32x16_bf16 v[82:97], v[184:187], v[122:125], v[82:97]
	v_add_f32_e32 v66, v66, v197
	v_add_f32_e32 v67, v67, v213
	s_nop 0
	v_add_f32_e32 v66, v66, v198
	v_add_f32_e32 v67, v67, v157
	s_nop 0
	v_add_f32_e32 v66, v66, v199
	v_add_f32_e32 v67, v67, v159
	s_nop 0
	v_add_f32_e32 v66, v66, v200
	v_add_f32_e32 v67, v67, v214
	s_nop 0
	v_add_f32_e32 v66, v66, v201
	v_add_f32_e32 v67, v67, v215
	s_nop 0
	v_add_f32_e32 v66, v66, v202
	v_add_f32_e32 v67, v67, v216
	s_nop 0
	v_add_f32_e32 v66, v66, v203
	v_add_f32_e32 v67, v67, v217
	s_nop 0
	v_add_f32_e32 v66, v66, v204
	v_add_f32_e32 v67, v67, v218
	s_nop 0
	v_add_f32_e32 v66, v66, v205
	v_add_f32_e32 v67, v67, v81
	s_nop 0
	v_add_f32_e32 v156, v66, v67
	v_cvt_pk_bf16_f32 v66, v139, v141
	v_cvt_pk_bf16_f32 v67, v143, v145
	v_mov_b32_e32 v158, v156
	v_permlane32_swap_b32_e32 v66, v68
	v_permlane32_swap_b32_e32 v67, v69
	v_permlane32_swap_b32_e32 v156, v158
	v_cvt_pk_bf16_f32 v70, v198, v199
	v_cvt_pk_bf16_f32 v71, v200, v201
	v_cvt_pk_bf16_f32 v72, v202, v203
	v_cvt_pk_bf16_f32 v73, v204, v205
	v_cvt_pk_bf16_f32 v74, v206, v207
	v_cvt_pk_bf16_f32 v75, v208, v209
	v_cvt_pk_bf16_f32 v76, v210, v211
	v_cvt_pk_bf16_f32 v77, v212, v213
	v_cvt_pk_bf16_f32 v78, v157, v159
	v_cvt_pk_bf16_f32 v79, v214, v215
	v_cvt_pk_bf16_f32 v80, v216, v217
	v_cvt_pk_bf16_f32 v81, v218, v81
	v_permlane32_swap_b32_e32 v70, v72
	v_permlane32_swap_b32_e32 v71, v73
	v_permlane32_swap_b32_e32 v74, v76
	v_permlane32_swap_b32_e32 v75, v77
	v_permlane32_swap_b32_e32 v78, v80
	v_permlane32_swap_b32_e32 v79, v81
	v_mfma_f32_32x32x16_bf16 v[98:113], v[188:191], v[126:129], v[98:113]
	v_mfma_f32_32x32x16_bf16 v[82:97], v[192:195], v[126:129], v[82:97]
	ds_read_b64_tr_b16 v[176:177], v169 offset:0
	ds_read_b64_tr_b16 v[178:179], v169 offset:0x800
	ds_read_b64_tr_b16 v[180:181], v169 offset:0x1000
	ds_read_b64_tr_b16 v[182:183], v169 offset:0x1800
	ds_read_b64_tr_b16 v[184:185], v169 offset:0x2000
	ds_read_b64_tr_b16 v[186:187], v169 offset:0x2800
	ds_read_b64_tr_b16 v[188:189], v169 offset:0x3000
	ds_read_b64_tr_b16 v[190:191], v169 offset:0x3800
	ds_read_b64_tr_b16 v[192:193], v169 offset:0x200
	ds_read_b64_tr_b16 v[194:195], v169 offset:0xa00
	ds_read_b64_tr_b16 v[196:197], v169 offset:0x1200
	ds_read_b64_tr_b16 v[198:199], v169 offset:0x1a00
	ds_read_b64_tr_b16 v[200:201], v169 offset:0x2200
	ds_read_b64_tr_b16 v[202:203], v169 offset:0x2a00
	ds_read_b64_tr_b16 v[204:205], v169 offset:0x3200
	ds_read_b64_tr_b16 v[206:207], v169 offset:0x3a00
	s_waitcnt lgkmcnt(8)
	s_nop 0
	v_mfma_f32_32x32x16_bf16 v[2:17], v[66:69], v[176:179], v[2:17]
	s_nop 8
	v_exp_f32_e32 v139, v98
	v_exp_f32_e32 v141, v99
	v_exp_f32_e32 v143, v100
	v_exp_f32_e32 v145, v101
	v_mfma_f32_32x32x16_bf16 v[2:17], v[70:73], v[180:183], v[2:17]
	v_mfma_f32_32x32x16_bf16 v[2:17], v[74:77], v[184:187], v[2:17]
	v_mfma_f32_32x32x16_bf16 v[2:17], v[78:81], v[188:191], v[2:17]
	ds_read_b64_tr_b16 v[98:99], v169 offset:0x400
	ds_read_b64_tr_b16 v[100:101], v169 offset:0xc00
	ds_read_b64_tr_b16 v[176:177], v169 offset:0x1400
	ds_read_b64_tr_b16 v[178:179], v169 offset:0x1c00
	ds_read_b64_tr_b16 v[180:181], v169 offset:0x2400
	ds_read_b64_tr_b16 v[182:183], v169 offset:0x2c00
	ds_read_b64_tr_b16 v[184:185], v169 offset:0x3400
	ds_read_b64_tr_b16 v[186:187], v169 offset:0x3c00
	s_waitcnt lgkmcnt(8)
	v_mfma_f32_32x32x16_bf16 v[18:33], v[66:69], v[192:195], v[18:33]
	v_exp_f32_e32 v147, v102
	v_exp_f32_e32 v149, v103
	v_mfma_f32_32x32x16_bf16 v[18:33], v[70:73], v[196:199], v[18:33]
	v_mfma_f32_32x32x16_bf16 v[18:33], v[74:77], v[200:203], v[18:33]
	v_exp_f32_e32 v200, v104
	v_exp_f32_e32 v201, v105
	v_mfma_f32_32x32x16_bf16 v[18:33], v[78:81], v[204:207], v[18:33]
	ds_read_b64_tr_b16 v[102:103], v169 offset:0x600
	ds_read_b64_tr_b16 v[104:105], v169 offset:0xe00
	ds_read_b64_tr_b16 v[188:189], v169 offset:0x1600
	ds_read_b64_tr_b16 v[190:191], v169 offset:0x1e00
	ds_read_b64_tr_b16 v[192:193], v169 offset:0x2600
	ds_read_b64_tr_b16 v[194:195], v169 offset:0x2e00
	ds_read_b64_tr_b16 v[196:197], v169 offset:0x3600
	ds_read_b64_tr_b16 v[198:199], v169 offset:0x3e00
	s_waitcnt lgkmcnt(8)
	v_mfma_f32_32x32x16_bf16 v[34:49], v[66:69], v[98:101], v[34:49]
	v_exp_f32_e32 v202, v106
	v_exp_f32_e32 v203, v107
	v_exp_f32_e32 v204, v108
	v_exp_f32_e32 v205, v109
	v_mfma_f32_32x32x16_bf16 v[34:49], v[70:73], v[176:179], v[34:49]
	v_mfma_f32_32x32x16_bf16 v[34:49], v[74:77], v[180:183], v[34:49]
	v_mfma_f32_32x32x16_bf16 v[34:49], v[78:81], v[184:187], v[34:49]
	s_waitcnt lgkmcnt(0)
	v_mfma_f32_32x32x16_bf16 v[50:65], v[66:69], v[102:105], v[50:65]
	v_exp_f32_e32 v206, v110
	v_exp_f32_e32 v207, v111
	v_exp_f32_e32 v208, v112
	v_exp_f32_e32 v209, v113
	v_mfma_f32_32x32x16_bf16 v[50:65], v[70:73], v[188:191], v[50:65]
	v_mfma_f32_32x32x16_bf16 v[50:65], v[74:77], v[192:195], v[50:65]
	v_mfma_f32_32x32x16_bf16 v[50:65], v[78:81], v[196:199], v[50:65]
	s_add_u32 s0, s61, 0x18242000
	s_mov_b32 m0, s35
	s_addc_u32 s1, s62, 0
	s_waitcnt vmcnt(0)
	s_waitcnt vmcnt(0)
	s_barrier
	global_load_lds_dwordx4 v[160:161], off
	v_lshl_add_u64 v[66:67], s[0:1], 0, v[152:153]
	s_mov_b32 m0, s56
	s_nop 0
	global_load_lds_dwordx4 v[66:67], off
	v_lshl_add_u64 v[66:67], s[0:1], 0, v[154:155]
	s_mov_b32 m0, s57
	s_nop 0
	global_load_lds_dwordx4 v[66:67], off
	ds_read_b128 v[66:69], v172 offset:40960
	ds_read_b128 v[70:73], v172 offset:45056
	ds_read_b128 v[152:155], v173 offset:40960
	ds_read_b128 v[176:179], v173 offset:45056
	ds_read_b128 v[180:183], v174 offset:40960
	ds_read_b128 v[184:187], v174 offset:45056
	ds_read_b128 v[188:191], v175 offset:40960
	ds_read_b128 v[192:195], v175 offset:45056
	s_waitcnt lgkmcnt(0)
	v_mfma_f32_32x32x16_bf16 v[98:113], v[66:69], v[114:117], 0
	v_exp_f32_e32 v160, v82
	v_exp_f32_e32 v161, v83
	v_exp_f32_e32 v196, v84
	v_exp_f32_e32 v197, v85
	v_exp_f32_e32 v198, v86
	v_exp_f32_e32 v199, v87
	v_exp_f32_e32 v210, v88
	v_mfma_f32_32x32x16_bf16 v[66:81], v[70:73], v[114:117], 0
	v_exp_f32_e32 v211, v89
	v_mfma_f32_32x32x16_bf16 v[66:81], v[176:179], v[118:121], v[66:81]
	v_exp_f32_e32 v212, v94
	v_exp_f32_e32 v213, v95
	v_exp_f32_e32 v214, v96
	v_exp_f32_e32 v97, v97
	v_mfma_f32_32x32x16_bf16 v[98:113], v[152:155], v[118:121], v[98:113]
	v_exp_f32_e32 v152, v90
	v_exp_f32_e32 v153, v91
	v_exp_f32_e32 v154, v92
	v_exp_f32_e32 v155, v93
	v_add_f32_e32 v82, v139, v141
	v_add_f32_e32 v83, v160, v161
	v_mfma_f32_32x32x16_bf16 v[66:81], v[184:187], v[122:125], v[66:81]
	v_add_f32_e32 v82, v82, v143
	v_add_f32_e32 v83, v83, v196
	v_cvt_pk_bf16_f32 v84, v147, v149
	v_add_f32_e32 v82, v82, v145
	v_add_f32_e32 v83, v83, v197
	v_cvt_pk_bf16_f32 v85, v200, v201
	v_add_f32_e32 v82, v82, v147
	v_add_f32_e32 v83, v83, v198
	v_mfma_f32_32x32x16_bf16 v[98:113], v[180:183], v[122:125], v[98:113]
	v_add_f32_e32 v82, v82, v149
	v_add_f32_e32 v83, v83, v199
	s_nop 0
	v_add_f32_e32 v82, v82, v200
	v_add_f32_e32 v83, v83, v210
	s_nop 0
	v_add_f32_e32 v82, v82, v201
	v_add_f32_e32 v83, v83, v211
	s_nop 0
	v_add_f32_e32 v82, v82, v202
	v_add_f32_e32 v83, v83, v152
	s_nop 0
	v_add_f32_e32 v82, v82, v203
	v_add_f32_e32 v83, v83, v153
	s_nop 0
	v_add_f32_e32 v82, v82, v204
	v_add_f32_e32 v83, v83, v154
	s_nop 0
	v_add_f32_e32 v82, v82, v205
	v_add_f32_e32 v83, v83, v155
	s_nop 0
	v_add_f32_e32 v82, v82, v206
	v_add_f32_e32 v83, v83, v212
	s_nop 0
	v_add_f32_e32 v82, v82, v207
	v_add_f32_e32 v83, v83, v213
	s_nop 0
	v_add_f32_e32 v82, v82, v208
	v_add_f32_e32 v83, v83, v214
	s_nop 0
	v_add_f32_e32 v82, v82, v209
	v_add_f32_e32 v83, v83, v97
	s_nop 0
	v_add_f32_e32 v157, v82, v83
	v_mov_b32_e32 v159, v157
	s_nop 1
	v_permlane32_swap_b32_e32 v157, v159
	v_add_f32_e64 v82, v156, v158
	v_add_f32_e64 v83, v157, v159
	v_add_f32_e32 v82, v135, v82
	v_add_f32_e32 v135, v82, v83
	v_cvt_pk_bf16_f32 v82, v139, v141
	v_cvt_pk_bf16_f32 v83, v143, v145
	s_nop 0
	v_permlane32_swap_b32_e32 v82, v84
	v_permlane32_swap_b32_e32 v83, v85
	v_mfma_f32_32x32x16_bf16 v[66:81], v[192:195], v[126:129], v[66:81]
	v_cvt_pk_bf16_f32 v86, v202, v203
	v_cvt_pk_bf16_f32 v87, v204, v205
	v_cvt_pk_bf16_f32 v88, v206, v207
	v_cvt_pk_bf16_f32 v89, v208, v209
	v_cvt_pk_bf16_f32 v90, v160, v161
	v_cvt_pk_bf16_f32 v91, v196, v197
	v_cvt_pk_bf16_f32 v92, v198, v199
	v_cvt_pk_bf16_f32 v93, v210, v211
	v_cvt_pk_bf16_f32 v94, v152, v153
	v_cvt_pk_bf16_f32 v95, v154, v155
	v_cvt_pk_bf16_f32 v96, v212, v213
	v_cvt_pk_bf16_f32 v97, v214, v97
	v_mfma_f32_32x32x16_bf16 v[98:113], v[188:191], v[126:129], v[98:113]
	v_permlane32_swap_b32_e32 v86, v88
	v_permlane32_swap_b32_e32 v87, v89
	v_permlane32_swap_b32_e32 v90, v92
	v_permlane32_swap_b32_e32 v91, v93
	v_permlane32_swap_b32_e32 v94, v96
	v_permlane32_swap_b32_e32 v95, v97
	ds_read_b64_tr_b16 v[152:153], v168 offset:0
	ds_read_b64_tr_b16 v[154:155], v168 offset:0x800
	ds_read_b64_tr_b16 v[156:157], v168 offset:0x1000
	ds_read_b64_tr_b16 v[158:159], v168 offset:0x1800
	ds_read_b64_tr_b16 v[176:177], v168 offset:0x2000
	ds_read_b64_tr_b16 v[178:179], v168 offset:0x2800
	ds_read_b64_tr_b16 v[180:181], v168 offset:0x3000
	ds_read_b64_tr_b16 v[182:183], v168 offset:0x3800
	ds_read_b64_tr_b16 v[184:185], v168 offset:0x200
	ds_read_b64_tr_b16 v[186:187], v168 offset:0xa00
	ds_read_b64_tr_b16 v[188:189], v168 offset:0x1200
	ds_read_b64_tr_b16 v[190:191], v168 offset:0x1a00
	ds_read_b64_tr_b16 v[192:193], v168 offset:0x2200
	ds_read_b64_tr_b16 v[194:195], v168 offset:0x2a00
	ds_read_b64_tr_b16 v[196:197], v168 offset:0x3200
	ds_read_b64_tr_b16 v[198:199], v168 offset:0x3a00
	s_waitcnt lgkmcnt(8)
	s_nop 0
	v_mfma_f32_32x32x16_bf16 v[2:17], v[82:85], v[152:155], v[2:17]
	s_nop 3
	v_exp_f32_e32 v139, v98
	v_exp_f32_e32 v141, v99
	v_exp_f32_e32 v143, v100
	v_exp_f32_e32 v145, v101
	v_mfma_f32_32x32x16_bf16 v[2:17], v[86:89], v[156:159], v[2:17]
	v_mfma_f32_32x32x16_bf16 v[2:17], v[90:93], v[176:179], v[2:17]
	v_mfma_f32_32x32x16_bf16 v[2:17], v[94:97], v[180:183], v[2:17]
	ds_read_b64_tr_b16 v[98:99], v168 offset:0x400
	ds_read_b64_tr_b16 v[100:101], v168 offset:0xc00
	ds_read_b64_tr_b16 v[152:153], v168 offset:0x1400
	ds_read_b64_tr_b16 v[154:155], v168 offset:0x1c00
	ds_read_b64_tr_b16 v[156:157], v168 offset:0x2400
	ds_read_b64_tr_b16 v[158:159], v168 offset:0x2c00
	ds_read_b64_tr_b16 v[200:201], v168 offset:0x3400
	ds_read_b64_tr_b16 v[202:203], v168 offset:0x3c00
	s_waitcnt lgkmcnt(8)
	v_mfma_f32_32x32x16_bf16 v[18:33], v[82:85], v[184:187], v[18:33]
	v_exp_f32_e32 v147, v102
	v_exp_f32_e32 v149, v103
	v_exp_f32_e32 v176, v104
	v_exp_f32_e32 v177, v105
	v_mfma_f32_32x32x16_bf16 v[18:33], v[86:89], v[188:191], v[18:33]
	v_mfma_f32_32x32x16_bf16 v[18:33], v[90:93], v[192:195], v[18:33]
	v_mfma_f32_32x32x16_bf16 v[18:33], v[94:97], v[196:199], v[18:33]
	ds_read_b64_tr_b16 v[102:103], v168 offset:0x600
	ds_read_b64_tr_b16 v[104:105], v168 offset:0xe00
	ds_read_b64_tr_b16 v[182:183], v168 offset:0x1600
	ds_read_b64_tr_b16 v[184:185], v168 offset:0x1e00
	ds_read_b64_tr_b16 v[186:187], v168 offset:0x2600
	ds_read_b64_tr_b16 v[188:189], v168 offset:0x2e00
	ds_read_b64_tr_b16 v[190:191], v168 offset:0x3600
	ds_read_b64_tr_b16 v[192:193], v168 offset:0x3e00
	s_waitcnt lgkmcnt(8)
	v_mfma_f32_32x32x16_bf16 v[34:49], v[82:85], v[98:101], v[34:49]
	v_exp_f32_e32 v178, v106
	v_exp_f32_e32 v179, v107
	v_exp_f32_e32 v180, v108
	v_exp_f32_e32 v181, v109
	v_mfma_f32_32x32x16_bf16 v[34:49], v[86:89], v[152:155], v[34:49]
	v_mfma_f32_32x32x16_bf16 v[34:49], v[90:93], v[156:159], v[34:49]
	v_mfma_f32_32x32x16_bf16 v[34:49], v[94:97], v[200:203], v[34:49]
	s_waitcnt lgkmcnt(0)
	v_mfma_f32_32x32x16_bf16 v[50:65], v[82:85], v[102:105], v[50:65]
	v_mfma_f32_32x32x16_bf16 v[50:65], v[86:89], v[182:185], v[50:65]
	v_exp_f32_e32 v182, v110
	v_exp_f32_e32 v183, v111
	v_exp_f32_e32 v184, v112
	v_exp_f32_e32 v185, v113
	v_mfma_f32_32x32x16_bf16 v[50:65], v[90:93], v[186:189], v[50:65]
	v_mfma_f32_32x32x16_bf16 v[50:65], v[94:97], v[190:193], v[50:65]
	v_add_u32_e32 v82, s60, v163
	v_mul_lo_u32 v82, v82, s22
	v_or3_b32 v82, v162, v82, v137
	v_ashrrev_i32_e32 v83, 31, v82
	v_lshlrev_b64 v[152:153], 1, v[82:83]
	v_add_u32_e32 v82, s59, v163
	v_mul_lo_u32 v82, v82, s22
	v_or3_b32 v82, v162, v82, v137
	s_waitcnt vmcnt(0)
	v_ashrrev_i32_e32 v83, 31, v82
	s_add_u32 s0, s90, s58
	v_lshlrev_b64 v[154:155], 1, v[82:83]
	v_lshl_add_u64 v[150:151], s[52:53], 0, v[150:151]
	s_addc_u32 s1, s91, s25
	v_or_b32_e32 v152, s24, v152
	v_or_b32_e32 v154, s24, v154
	s_mov_b32 s52, 4
	s_waitcnt vmcnt(0)
	s_barrier
	v_exp_f32_e32 v220, v66
	v_exp_f32_e32 v221, v67
	v_exp_f32_e32 v222, v68
	v_exp_f32_e32 v223, v69
	v_exp_f32_e32 v224, v70
	v_exp_f32_e32 v225, v71
	v_exp_f32_e32 v226, v72
	v_exp_f32_e32 v227, v73
	v_exp_f32_e32 v228, v74
	v_exp_f32_e32 v229, v75
	v_exp_f32_e32 v230, v76
	v_exp_f32_e32 v231, v77
	v_exp_f32_e32 v232, v78
	v_exp_f32_e32 v233, v79
	v_exp_f32_e32 v234, v80
	v_exp_f32_e32 v235, v81
	s_branch .LBB0_2320
	.p2alignl 6, 3212836864

.LBB0_2397:
	s_ashr_i32 s15, s14, 31
	s_lshl_b64 s[16:17], s[14:15], 20
	v_readlane_b32 s18, v242, 15
	v_readlane_b32 s19, v242, 16
	s_add_u32 s16, s18, s16
	s_addc_u32 s17, s19, s17
	s_and_b64 s[18:19], s[2:3], exec
	s_cselect_b32 s15, s17, s23
	s_cselect_b32 s46, s16, s22
	s_ashr_i32 s13, s12, 31
	s_lshl_b64 s[18:19], s[12:13], 20
	s_add_u32 s18, s20, s18
	s_addc_u32 s19, s24, s19
	s_and_b64 s[28:29], s[2:3], exec
	s_cselect_b32 s13, s19, s1
	s_cselect_b32 s47, s18, s0
	s_add_u32 s38, s22, 0x80080
	s_addc_u32 s39, s23, 0
	s_add_u32 s52, s0, 0x100
	v_mov_b32_e32 v2, 0
	s_addc_u32 s53, s1, 0
	s_mov_b32 s54, -2
	v_mov_b32_e32 v3, v2
	v_mov_b32_e32 v4, v2
	v_mov_b32_e32 v5, v2
	v_mov_b32_e32 v6, v2
	v_mov_b32_e32 v7, v2
	v_mov_b32_e32 v8, v2
	v_mov_b32_e32 v9, v2
	v_mov_b32_e32 v18, v2
	v_mov_b32_e32 v19, v2
	v_mov_b32_e32 v20, v2
	v_mov_b32_e32 v21, v2
	v_mov_b32_e32 v22, v2
	v_mov_b32_e32 v23, v2
	v_mov_b32_e32 v24, v2
	v_mov_b32_e32 v25, v2
	v_mov_b32_e32 v34, v2
	v_mov_b32_e32 v35, v2
	v_mov_b32_e32 v36, v2
	v_mov_b32_e32 v37, v2
	s_waitcnt lgkmcnt(0)
	v_mov_b32_e32 v38, v2
	v_mov_b32_e32 v39, v2
	v_mov_b32_e32 v40, v2
	v_mov_b32_e32 v41, v2
	v_mov_b32_e32 v50, v2
	v_mov_b32_e32 v51, v2
	v_mov_b32_e32 v52, v2
	v_mov_b32_e32 v53, v2
	v_mov_b32_e32 v54, v2
	v_mov_b32_e32 v55, v2
	v_mov_b32_e32 v56, v2
	v_mov_b32_e32 v57, v2
	v_mov_b32_e32 v10, v2
	v_mov_b32_e32 v11, v2
	v_mov_b32_e32 v12, v2
	v_mov_b32_e32 v13, v2
	v_mov_b32_e32 v14, v2
	v_mov_b32_e32 v15, v2
	v_mov_b32_e32 v16, v2
	v_mov_b32_e32 v17, v2
	v_mov_b32_e32 v26, v2
	v_mov_b32_e32 v27, v2
	v_mov_b32_e32 v28, v2
	v_mov_b32_e32 v29, v2
	v_mov_b32_e32 v30, v2
	v_mov_b32_e32 v31, v2
	v_mov_b32_e32 v32, v2
	v_mov_b32_e32 v33, v2
	v_mov_b32_e32 v42, v2
	v_mov_b32_e32 v43, v2
	v_mov_b32_e32 v44, v2
	v_mov_b32_e32 v45, v2
	v_mov_b32_e32 v46, v2
	v_mov_b32_e32 v47, v2
	v_mov_b32_e32 v48, v2
	v_mov_b32_e32 v49, v2
	v_mov_b32_e32 v58, v2
	v_mov_b32_e32 v59, v2
	v_mov_b32_e32 v60, v2
	v_mov_b32_e32 v61, v2
	v_mov_b32_e32 v62, v2
	v_mov_b32_e32 v63, v2
	v_mov_b32_e32 v64, v2
	v_mov_b32_e32 v65, v2
	v_mov_b32_e32 v66, v2
	v_mov_b32_e32 v67, v2
	v_mov_b32_e32 v68, v2
	v_mov_b32_e32 v69, v2
	v_mov_b32_e32 v70, v2
	v_mov_b32_e32 v71, v2
	v_mov_b32_e32 v72, v2
	v_mov_b32_e32 v73, v2
	v_mov_b32_e32 v82, v2
	v_mov_b32_e32 v83, v2
	v_mov_b32_e32 v84, v2
	v_mov_b32_e32 v85, v2
	v_mov_b32_e32 v86, v2
	v_mov_b32_e32 v87, v2
	v_mov_b32_e32 v88, v2
	v_mov_b32_e32 v89, v2
	v_mov_b32_e32 v98, v2
	v_mov_b32_e32 v99, v2
	v_mov_b32_e32 v100, v2
	v_mov_b32_e32 v101, v2
	v_mov_b32_e32 v102, v2
	v_mov_b32_e32 v103, v2
	v_mov_b32_e32 v104, v2
	v_mov_b32_e32 v105, v2
	v_mov_b32_e32 v114, v2
	v_mov_b32_e32 v115, v2
	v_mov_b32_e32 v116, v2
	v_mov_b32_e32 v117, v2
	v_mov_b32_e32 v118, v2
	v_mov_b32_e32 v119, v2
	v_mov_b32_e32 v120, v2
	v_mov_b32_e32 v121, v2
	v_mov_b32_e32 v74, v2
	v_mov_b32_e32 v75, v2
	v_mov_b32_e32 v76, v2
	v_mov_b32_e32 v77, v2
	v_mov_b32_e32 v78, v2
	v_mov_b32_e32 v79, v2
	v_mov_b32_e32 v80, v2
	v_mov_b32_e32 v81, v2
	v_mov_b32_e32 v90, v2
	v_mov_b32_e32 v91, v2
	v_mov_b32_e32 v92, v2
	v_mov_b32_e32 v93, v2
	v_mov_b32_e32 v94, v2
	v_mov_b32_e32 v95, v2
	v_mov_b32_e32 v96, v2
	v_mov_b32_e32 v97, v2
	v_mov_b32_e32 v106, v2
	v_mov_b32_e32 v107, v2
	v_mov_b32_e32 v108, v2
	v_mov_b32_e32 v109, v2
	v_mov_b32_e32 v110, v2
	v_mov_b32_e32 v111, v2
	v_mov_b32_e32 v112, v2
	v_mov_b32_e32 v113, v2
	v_mov_b32_e32 v122, v2
	v_mov_b32_e32 v123, v2
	v_mov_b32_e32 v124, v2
	v_mov_b32_e32 v125, v2
	v_mov_b32_e32 v126, v2
	v_mov_b32_e32 v127, v2
	v_mov_b32_e32 v128, v2
	v_mov_b32_e32 v129, v2
	.p2alignl 6, 3212836864

.LBB0_2480:
	s_ashr_i32 s15, s14, 31
	s_lshl_b64 s[28:29], s[14:15], 19
	s_add_u32 s15, s20, s28
	s_addc_u32 s21, s24, s29
	s_ashr_i32 s17, s16, 31
	s_lshl_b64 s[28:29], s[16:17], 22
	s_add_u32 s36, s15, s28
	s_addc_u32 s37, s21, s29
	s_and_b64 s[4:5], s[4:5], exec
	s_cselect_b32 s15, s37, s1
	s_cselect_b32 s17, s36, s0
	s_add_u32 s4, s22, 0x180080
	s_addc_u32 s5, s23, 0
	s_add_u32 s46, s0, 0x100
	v_mov_b32_e32 v2, 0
	s_addc_u32 s47, s1, 0
	s_mov_b32 s52, -2
	v_mov_b32_e32 v3, v2
	v_mov_b32_e32 v4, v2
	v_mov_b32_e32 v5, v2
	v_mov_b32_e32 v6, v2
	v_mov_b32_e32 v7, v2
	v_mov_b32_e32 v8, v2
	v_mov_b32_e32 v9, v2
	v_mov_b32_e32 v14, v2
	v_mov_b32_e32 v15, v2
	v_mov_b32_e32 v16, v2
	v_mov_b32_e32 v17, v2
	s_waitcnt vmcnt(0)
	v_mov_b32_e32 v22, v2
	v_mov_b32_e32 v23, v2
	v_mov_b32_e32 v24, v2
	v_mov_b32_e32 v25, v2
	v_mov_b32_e32 v34, v2
	v_mov_b32_e32 v35, v2
	v_mov_b32_e32 v36, v2
	v_mov_b32_e32 v37, v2
	s_waitcnt lgkmcnt(0)
	v_mov_b32_e32 v38, v2
	v_mov_b32_e32 v39, v2
	v_mov_b32_e32 v40, v2
	v_mov_b32_e32 v41, v2
	v_mov_b32_e32 v42, v2
	v_mov_b32_e32 v43, v2
	v_mov_b32_e32 v44, v2
	v_mov_b32_e32 v45, v2
	v_mov_b32_e32 v46, v2
	v_mov_b32_e32 v47, v2
	v_mov_b32_e32 v48, v2
	v_mov_b32_e32 v49, v2
	v_mov_b32_e32 v10, v2
	v_mov_b32_e32 v11, v2
	v_mov_b32_e32 v12, v2
	v_mov_b32_e32 v13, v2
	v_mov_b32_e32 v18, v2
	v_mov_b32_e32 v19, v2
	v_mov_b32_e32 v20, v2
	v_mov_b32_e32 v21, v2
	v_mov_b32_e32 v26, v2
	v_mov_b32_e32 v27, v2
	v_mov_b32_e32 v28, v2
	v_mov_b32_e32 v29, v2
	v_mov_b32_e32 v30, v2
	v_mov_b32_e32 v31, v2
	v_mov_b32_e32 v32, v2
	v_mov_b32_e32 v33, v2
	v_mov_b32_e32 v50, v2
	v_mov_b32_e32 v51, v2
	v_mov_b32_e32 v52, v2
	v_mov_b32_e32 v53, v2
	v_mov_b32_e32 v54, v2
	v_mov_b32_e32 v55, v2
	v_mov_b32_e32 v56, v2
	v_mov_b32_e32 v57, v2
	v_mov_b32_e32 v58, v2
	v_mov_b32_e32 v59, v2
	v_mov_b32_e32 v60, v2
	v_mov_b32_e32 v61, v2
	v_mov_b32_e32 v62, v2
	v_mov_b32_e32 v63, v2
	v_mov_b32_e32 v64, v2
	v_mov_b32_e32 v65, v2
	v_mov_b32_e32 v66, v2
	v_mov_b32_e32 v67, v2
	v_mov_b32_e32 v68, v2
	v_mov_b32_e32 v69, v2
	v_mov_b32_e32 v70, v2
	v_mov_b32_e32 v71, v2
	v_mov_b32_e32 v72, v2
	v_mov_b32_e32 v73, v2
	v_mov_b32_e32 v74, v2
	v_mov_b32_e32 v75, v2
	v_mov_b32_e32 v76, v2
	v_mov_b32_e32 v77, v2
	v_mov_b32_e32 v78, v2
	v_mov_b32_e32 v79, v2
	v_mov_b32_e32 v80, v2
	v_mov_b32_e32 v81, v2
	v_mov_b32_e32 v98, v2
	v_mov_b32_e32 v99, v2
	v_mov_b32_e32 v100, v2
	v_mov_b32_e32 v101, v2
	v_mov_b32_e32 v102, v2
	v_mov_b32_e32 v103, v2
	v_mov_b32_e32 v104, v2
	v_mov_b32_e32 v105, v2
	v_mov_b32_e32 v106, v2
	v_mov_b32_e32 v107, v2
	v_mov_b32_e32 v108, v2
	v_mov_b32_e32 v109, v2
	v_mov_b32_e32 v110, v2
	v_mov_b32_e32 v111, v2
	v_mov_b32_e32 v112, v2
	v_mov_b32_e32 v113, v2
	v_mov_b32_e32 v82, v2
	v_mov_b32_e32 v83, v2
	v_mov_b32_e32 v84, v2
	v_mov_b32_e32 v85, v2
	v_mov_b32_e32 v86, v2
	v_mov_b32_e32 v87, v2
	v_mov_b32_e32 v88, v2
	v_mov_b32_e32 v89, v2
	v_mov_b32_e32 v90, v2
	v_mov_b32_e32 v91, v2
	v_mov_b32_e32 v92, v2
	v_mov_b32_e32 v93, v2
	v_mov_b32_e32 v94, v2
	v_mov_b32_e32 v95, v2
	v_mov_b32_e32 v96, v2
	v_mov_b32_e32 v97, v2
	v_mov_b32_e32 v114, v2
	v_mov_b32_e32 v115, v2
	v_mov_b32_e32 v116, v2
	v_mov_b32_e32 v117, v2
	v_mov_b32_e32 v118, v2
	v_mov_b32_e32 v119, v2
	v_mov_b32_e32 v120, v2
	v_mov_b32_e32 v121, v2
	v_mov_b32_e32 v122, v2
	v_mov_b32_e32 v123, v2
	v_mov_b32_e32 v124, v2
	v_mov_b32_e32 v125, v2
	v_mov_b32_e32 v126, v2
	v_mov_b32_e32 v127, v2
	v_mov_b32_e32 v128, v2
	v_mov_b32_e32 v129, v2
	.p2alignl 6, 3212836864

.LBB0_2593:
	s_ashr_i32 s15, s14, 31
	s_lshl_b64 s[16:17], s[14:15], 20
	v_readlane_b32 s18, v242, 15
	v_readlane_b32 s19, v242, 16
	s_add_u32 s16, s18, s16
	s_addc_u32 s17, s19, s17
	s_and_b64 s[18:19], s[2:3], exec
	s_cselect_b32 s15, s17, s23
	s_cselect_b32 s47, s16, s22
	s_ashr_i32 s13, s12, 31
	s_lshl_b64 s[18:19], s[12:13], 20
	s_add_u32 s18, s24, s18
	s_addc_u32 s19, s25, s19
	s_and_b64 s[28:29], s[2:3], exec
	s_cselect_b32 s13, s19, s1
	s_cselect_b32 s52, s18, s0
	s_add_u32 s38, s22, 0x80080
	s_addc_u32 s39, s23, 0
	s_add_u32 s53, s0, 0x100
	v_mov_b32_e32 v2, 0
	s_addc_u32 s54, s1, 0
	s_mov_b32 s55, -2
	v_mov_b32_e32 v3, v2
	v_mov_b32_e32 v4, v2
	v_mov_b32_e32 v5, v2
	v_mov_b32_e32 v34, v2
	v_mov_b32_e32 v35, v2
	v_mov_b32_e32 v36, v2
	v_mov_b32_e32 v37, v2
	v_mov_b32_e32 v6, v2
	v_mov_b32_e32 v7, v2
	v_mov_b32_e32 v8, v2
	v_mov_b32_e32 v9, v2
	s_waitcnt lgkmcnt(0)
	v_mov_b32_e32 v38, v2
	v_mov_b32_e32 v39, v2
	v_mov_b32_e32 v40, v2
	v_mov_b32_e32 v41, v2
	v_mov_b32_e32 v10, v2
	v_mov_b32_e32 v11, v2
	v_mov_b32_e32 v12, v2
	v_mov_b32_e32 v13, v2
	v_mov_b32_e32 v42, v2
	v_mov_b32_e32 v43, v2
	v_mov_b32_e32 v44, v2
	v_mov_b32_e32 v45, v2
	v_mov_b32_e32 v14, v2
	v_mov_b32_e32 v15, v2
	v_mov_b32_e32 v16, v2
	v_mov_b32_e32 v17, v2
	v_mov_b32_e32 v46, v2
	v_mov_b32_e32 v47, v2
	v_mov_b32_e32 v48, v2
	v_mov_b32_e32 v49, v2
	v_mov_b32_e32 v66, v2
	v_mov_b32_e32 v67, v2
	v_mov_b32_e32 v68, v2
	v_mov_b32_e32 v69, v2
	v_mov_b32_e32 v98, v2
	v_mov_b32_e32 v99, v2
	v_mov_b32_e32 v100, v2
	v_mov_b32_e32 v101, v2
	v_mov_b32_e32 v70, v2
	v_mov_b32_e32 v71, v2
	v_mov_b32_e32 v72, v2
	v_mov_b32_e32 v73, v2
	v_mov_b32_e32 v102, v2
	v_mov_b32_e32 v103, v2
	v_mov_b32_e32 v104, v2
	v_mov_b32_e32 v105, v2
	v_mov_b32_e32 v74, v2
	v_mov_b32_e32 v75, v2
	v_mov_b32_e32 v76, v2
	v_mov_b32_e32 v77, v2
	v_mov_b32_e32 v110, v2
	v_mov_b32_e32 v111, v2
	v_mov_b32_e32 v112, v2
	v_mov_b32_e32 v113, v2
	v_mov_b32_e32 v78, v2
	v_mov_b32_e32 v79, v2
	v_mov_b32_e32 v80, v2
	v_mov_b32_e32 v81, v2
	v_mov_b32_e32 v114, v2
	v_mov_b32_e32 v115, v2
	v_mov_b32_e32 v116, v2
	v_mov_b32_e32 v117, v2
	s_waitcnt vmcnt(0)
	v_mov_b32_e32 v18, v2
	v_mov_b32_e32 v19, v2
	v_mov_b32_e32 v20, v2
	v_mov_b32_e32 v21, v2
	v_mov_b32_e32 v50, v2
	v_mov_b32_e32 v51, v2
	v_mov_b32_e32 v52, v2
	v_mov_b32_e32 v53, v2
	v_mov_b32_e32 v22, v2
	v_mov_b32_e32 v23, v2
	v_mov_b32_e32 v24, v2
	v_mov_b32_e32 v25, v2
	v_mov_b32_e32 v54, v2
	v_mov_b32_e32 v55, v2
	v_mov_b32_e32 v56, v2
	v_mov_b32_e32 v57, v2
	v_mov_b32_e32 v26, v2
	v_mov_b32_e32 v27, v2
	v_mov_b32_e32 v28, v2
	v_mov_b32_e32 v29, v2
	v_mov_b32_e32 v58, v2
	v_mov_b32_e32 v59, v2
	v_mov_b32_e32 v60, v2
	v_mov_b32_e32 v61, v2
	v_mov_b32_e32 v30, v2
	v_mov_b32_e32 v31, v2
	v_mov_b32_e32 v32, v2
	v_mov_b32_e32 v33, v2
	v_mov_b32_e32 v62, v2
	v_mov_b32_e32 v63, v2
	v_mov_b32_e32 v64, v2
	v_mov_b32_e32 v65, v2
	v_mov_b32_e32 v82, v2
	v_mov_b32_e32 v83, v2
	v_mov_b32_e32 v84, v2
	v_mov_b32_e32 v85, v2
	v_mov_b32_e32 v118, v2
	v_mov_b32_e32 v119, v2
	v_mov_b32_e32 v120, v2
	v_mov_b32_e32 v121, v2
	v_mov_b32_e32 v86, v2
	v_mov_b32_e32 v87, v2
	v_mov_b32_e32 v88, v2
	v_mov_b32_e32 v89, v2
	v_mov_b32_e32 v122, v2
	v_mov_b32_e32 v123, v2
	v_mov_b32_e32 v124, v2
	v_mov_b32_e32 v125, v2
	v_mov_b32_e32 v90, v2
	v_mov_b32_e32 v91, v2
	v_mov_b32_e32 v92, v2
	v_mov_b32_e32 v93, v2
	v_mov_b32_e32 v126, v2
	v_mov_b32_e32 v127, v2
	v_mov_b32_e32 v128, v2
	v_mov_b32_e32 v129, v2
	v_mov_b32_e32 v94, v2
	v_mov_b32_e32 v95, v2
	v_mov_b32_e32 v96, v2
	v_mov_b32_e32 v97, v2
	v_mov_b32_e32 v130, v2
	v_mov_b32_e32 v131, v2
	v_mov_b32_e32 v132, v2
	v_mov_b32_e32 v133, v2
	.p2alignl 6, 3212836864

.LBB0_2722:
	s_ashr_i32 s15, s14, 31
	s_lshl_b64 s[16:17], s[14:15], 20
	v_readlane_b32 s18, v242, 15
	v_readlane_b32 s19, v242, 16
	s_add_u32 s16, s18, s16
	s_addc_u32 s17, s19, s17
	s_and_b64 s[18:19], s[2:3], exec
	s_cselect_b32 s15, s17, s23
	s_cselect_b32 s46, s16, s22
	s_ashr_i32 s13, s12, 31
	s_lshl_b64 s[18:19], s[12:13], 20
	s_add_u32 s18, s20, s18
	s_addc_u32 s19, s24, s19
	s_and_b64 s[28:29], s[2:3], exec
	s_cselect_b32 s13, s19, s1
	s_cselect_b32 s47, s18, s0
	s_add_u32 s38, s22, 0x80080
	s_addc_u32 s39, s23, 0
	s_add_u32 s52, s0, 0x100
	v_mov_b32_e32 v2, 0
	s_addc_u32 s53, s1, 0
	s_mov_b32 s54, -2
	v_mov_b32_e32 v3, v2
	v_mov_b32_e32 v4, v2
	v_mov_b32_e32 v5, v2
	v_mov_b32_e32 v10, v2
	v_mov_b32_e32 v11, v2
	v_mov_b32_e32 v12, v2
	v_mov_b32_e32 v13, v2
	v_mov_b32_e32 v18, v2
	v_mov_b32_e32 v19, v2
	v_mov_b32_e32 v20, v2
	v_mov_b32_e32 v21, v2
	v_mov_b32_e32 v26, v2
	v_mov_b32_e32 v27, v2
	v_mov_b32_e32 v28, v2
	v_mov_b32_e32 v29, v2
	v_mov_b32_e32 v34, v2
	v_mov_b32_e32 v35, v2
	v_mov_b32_e32 v36, v2
	v_mov_b32_e32 v37, v2
	v_mov_b32_e32 v42, v2
	v_mov_b32_e32 v43, v2
	v_mov_b32_e32 v44, v2
	v_mov_b32_e32 v45, v2
	v_mov_b32_e32 v50, v2
	v_mov_b32_e32 v51, v2
	v_mov_b32_e32 v52, v2
	v_mov_b32_e32 v53, v2
	v_mov_b32_e32 v58, v2
	v_mov_b32_e32 v59, v2
	v_mov_b32_e32 v60, v2
	v_mov_b32_e32 v61, v2
	v_mov_b32_e32 v6, v2
	v_mov_b32_e32 v7, v2
	v_mov_b32_e32 v8, v2
	v_mov_b32_e32 v9, v2
	v_mov_b32_e32 v14, v2
	v_mov_b32_e32 v15, v2
	v_mov_b32_e32 v16, v2
	v_mov_b32_e32 v17, v2
	v_mov_b32_e32 v22, v2
	v_mov_b32_e32 v23, v2
	v_mov_b32_e32 v24, v2
	v_mov_b32_e32 v25, v2
	v_mov_b32_e32 v30, v2
	v_mov_b32_e32 v31, v2
	v_mov_b32_e32 v32, v2
	v_mov_b32_e32 v33, v2
	s_waitcnt lgkmcnt(0)
	v_mov_b32_e32 v38, v2
	v_mov_b32_e32 v39, v2
	v_mov_b32_e32 v40, v2
	v_mov_b32_e32 v41, v2
	v_mov_b32_e32 v46, v2
	v_mov_b32_e32 v47, v2
	v_mov_b32_e32 v48, v2
	v_mov_b32_e32 v49, v2
	v_mov_b32_e32 v54, v2
	v_mov_b32_e32 v55, v2
	v_mov_b32_e32 v56, v2
	v_mov_b32_e32 v57, v2
	v_mov_b32_e32 v62, v2
	v_mov_b32_e32 v63, v2
	v_mov_b32_e32 v64, v2
	v_mov_b32_e32 v65, v2
	v_mov_b32_e32 v66, v2
	v_mov_b32_e32 v67, v2
	v_mov_b32_e32 v68, v2
	v_mov_b32_e32 v69, v2
	v_mov_b32_e32 v74, v2
	v_mov_b32_e32 v75, v2
	v_mov_b32_e32 v76, v2
	v_mov_b32_e32 v77, v2
	v_mov_b32_e32 v82, v2
	v_mov_b32_e32 v83, v2
	v_mov_b32_e32 v84, v2
	v_mov_b32_e32 v85, v2
	v_mov_b32_e32 v90, v2
	v_mov_b32_e32 v91, v2
	v_mov_b32_e32 v92, v2
	v_mov_b32_e32 v93, v2
	v_mov_b32_e32 v98, v2
	v_mov_b32_e32 v99, v2
	v_mov_b32_e32 v100, v2
	v_mov_b32_e32 v101, v2
	v_mov_b32_e32 v106, v2
	v_mov_b32_e32 v107, v2
	v_mov_b32_e32 v108, v2
	v_mov_b32_e32 v109, v2
	v_mov_b32_e32 v114, v2
	v_mov_b32_e32 v115, v2
	v_mov_b32_e32 v116, v2
	v_mov_b32_e32 v117, v2
	v_mov_b32_e32 v122, v2
	v_mov_b32_e32 v123, v2
	v_mov_b32_e32 v124, v2
	v_mov_b32_e32 v125, v2
	v_mov_b32_e32 v70, v2
	v_mov_b32_e32 v71, v2
	v_mov_b32_e32 v72, v2
	v_mov_b32_e32 v73, v2
	v_mov_b32_e32 v78, v2
	v_mov_b32_e32 v79, v2
	v_mov_b32_e32 v80, v2
	v_mov_b32_e32 v81, v2
	v_mov_b32_e32 v86, v2
	v_mov_b32_e32 v87, v2
	v_mov_b32_e32 v88, v2
	v_mov_b32_e32 v89, v2
	v_mov_b32_e32 v94, v2
	v_mov_b32_e32 v95, v2
	v_mov_b32_e32 v96, v2
	v_mov_b32_e32 v97, v2
	v_mov_b32_e32 v102, v2
	v_mov_b32_e32 v103, v2
	v_mov_b32_e32 v104, v2
	v_mov_b32_e32 v105, v2
	v_mov_b32_e32 v110, v2
	v_mov_b32_e32 v111, v2
	v_mov_b32_e32 v112, v2
	v_mov_b32_e32 v113, v2
	v_mov_b32_e32 v118, v2
	v_mov_b32_e32 v119, v2
	v_mov_b32_e32 v120, v2
	v_mov_b32_e32 v121, v2
	v_mov_b32_e32 v126, v2
	v_mov_b32_e32 v127, v2
	v_mov_b32_e32 v128, v2
	v_mov_b32_e32 v129, v2
	.p2alignl 6, 3212836864

.LBB0_2817:
	s_cmp_lg_u32 s18, 0
	s_cselect_b64 s[38:39], -1, 0
	s_cmp_eq_u32 s18, 0
	s_cselect_b32 s19, 0x58, 8
	s_add_i32 s58, s19, -2
	s_add_u32 s36, s24, 0x160080
	s_addc_u32 s37, s25, 0
	s_add_u32 s24, s0, 0x100
	v_mov_b32_e32 v0, 0
	s_mov_b32 s22, 0
	s_addc_u32 s25, s1, 0
	v_mov_b32_e32 v1, v0
	v_mov_b32_e32 v2, v0
	v_mov_b32_e32 v3, v0
	s_waitcnt vmcnt(0)
	v_mov_b32_e32 v32, v0
	v_mov_b32_e32 v33, v0
	v_mov_b32_e32 v34, v0
	v_mov_b32_e32 v35, v0
	v_mov_b32_e32 v4, v0
	v_mov_b32_e32 v5, v0
	v_mov_b32_e32 v6, v0
	v_mov_b32_e32 v7, v0
	v_mov_b32_e32 v36, v0
	v_mov_b32_e32 v37, v0
	s_waitcnt lgkmcnt(0)
	v_mov_b32_e32 v38, v0
	v_mov_b32_e32 v39, v0
	v_mov_b32_e32 v8, v0
	v_mov_b32_e32 v9, v0
	v_mov_b32_e32 v10, v0
	v_mov_b32_e32 v11, v0
	v_mov_b32_e32 v40, v0
	v_mov_b32_e32 v41, v0
	v_mov_b32_e32 v42, v0
	v_mov_b32_e32 v43, v0
	v_mov_b32_e32 v12, v0
	v_mov_b32_e32 v13, v0
	v_mov_b32_e32 v14, v0
	v_mov_b32_e32 v15, v0
	v_mov_b32_e32 v44, v0
	v_mov_b32_e32 v45, v0
	v_mov_b32_e32 v46, v0
	v_mov_b32_e32 v47, v0
	v_mov_b32_e32 v64, v0
	v_mov_b32_e32 v65, v0
	v_mov_b32_e32 v66, v0
	v_mov_b32_e32 v67, v0
	v_mov_b32_e32 v96, v0
	v_mov_b32_e32 v97, v0
	v_mov_b32_e32 v98, v0
	v_mov_b32_e32 v99, v0
	v_mov_b32_e32 v68, v0
	v_mov_b32_e32 v69, v0
	v_mov_b32_e32 v70, v0
	v_mov_b32_e32 v71, v0
	v_mov_b32_e32 v100, v0
	v_mov_b32_e32 v101, v0
	v_mov_b32_e32 v102, v0
	v_mov_b32_e32 v103, v0
	v_mov_b32_e32 v72, v0
	v_mov_b32_e32 v73, v0
	v_mov_b32_e32 v74, v0
	v_mov_b32_e32 v75, v0
	v_mov_b32_e32 v104, v0
	v_mov_b32_e32 v105, v0
	v_mov_b32_e32 v106, v0
	v_mov_b32_e32 v107, v0
	v_mov_b32_e32 v76, v0
	v_mov_b32_e32 v77, v0
	v_mov_b32_e32 v78, v0
	v_mov_b32_e32 v79, v0
	v_mov_b32_e32 v108, v0
	v_mov_b32_e32 v109, v0
	v_mov_b32_e32 v110, v0
	v_mov_b32_e32 v111, v0
	v_mov_b32_e32 v16, v0
	v_mov_b32_e32 v17, v0
	v_mov_b32_e32 v18, v0
	v_mov_b32_e32 v19, v0
	v_mov_b32_e32 v48, v0
	v_mov_b32_e32 v49, v0
	v_mov_b32_e32 v50, v0
	v_mov_b32_e32 v51, v0
	v_mov_b32_e32 v20, v0
	v_mov_b32_e32 v21, v0
	v_mov_b32_e32 v22, v0
	v_mov_b32_e32 v23, v0
	v_mov_b32_e32 v52, v0
	v_mov_b32_e32 v53, v0
	v_mov_b32_e32 v54, v0
	v_mov_b32_e32 v55, v0
	v_mov_b32_e32 v24, v0
	v_mov_b32_e32 v25, v0
	v_mov_b32_e32 v26, v0
	v_mov_b32_e32 v27, v0
	v_mov_b32_e32 v56, v0
	v_mov_b32_e32 v57, v0
	v_mov_b32_e32 v58, v0
	v_mov_b32_e32 v59, v0
	v_mov_b32_e32 v28, v0
	v_mov_b32_e32 v29, v0
	v_mov_b32_e32 v30, v0
	v_mov_b32_e32 v31, v0
	v_mov_b32_e32 v60, v0
	v_mov_b32_e32 v61, v0
	v_mov_b32_e32 v62, v0
	v_mov_b32_e32 v63, v0
	v_mov_b32_e32 v80, v0
	v_mov_b32_e32 v81, v0
	v_mov_b32_e32 v82, v0
	v_mov_b32_e32 v83, v0
	v_mov_b32_e32 v112, v0
	v_mov_b32_e32 v113, v0
	v_mov_b32_e32 v114, v0
	v_mov_b32_e32 v115, v0
	v_mov_b32_e32 v84, v0
	v_mov_b32_e32 v85, v0
	v_mov_b32_e32 v86, v0
	v_mov_b32_e32 v87, v0
	v_mov_b32_e32 v116, v0
	v_mov_b32_e32 v117, v0
	v_mov_b32_e32 v118, v0
	v_mov_b32_e32 v119, v0
	v_mov_b32_e32 v88, v0
	v_mov_b32_e32 v89, v0
	v_mov_b32_e32 v90, v0
	v_mov_b32_e32 v91, v0
	v_mov_b32_e32 v120, v0
	v_mov_b32_e32 v121, v0
	v_mov_b32_e32 v122, v0
	v_mov_b32_e32 v123, v0
	v_mov_b32_e32 v92, v0
	v_mov_b32_e32 v93, v0
	v_mov_b32_e32 v94, v0
	v_mov_b32_e32 v95, v0
	v_mov_b32_e32 v124, v0
	v_mov_b32_e32 v125, v0
	v_mov_b32_e32 v126, v0
	v_mov_b32_e32 v127, v0
	.p2alignl 6, 3212836864
